# v12: v11 with the 128 per-segment s_setprio flips of the 8 GEMM K-loops deleted (A/B per guide 6.3)
# baseline (speedup 1.0000x reference)
.LBB0_237:
	ds_read_b128 v[128:131], v169
	ds_read_b128 v[152:155], v169 offset:1024
	ds_read_b128 v[156:159], v169 offset:2048
	ds_read_b128 v[160:163], v169 offset:3072
	s_add_u32 s20, s8, 0xfff80080
	s_addc_u32 s21, s9, -1
	s_cmp_eq_u32 s35, 28
	s_cselect_b32 s21, s1, s21
	s_cselect_b32 s20, s7, s20
	s_cselect_b32 s79, s22, s34
	s_cselect_b32 s78, s23, s33
	v_lshl_add_u64 v[164:165], s[8:9], 0, v[142:143]
	s_add_i32 m0, s12, 0xc000
	ds_read_b128 v[172:175], v170
	ds_read_b128 v[176:179], v170 offset:1024
	ds_read_b128 v[180:183], v170 offset:2048
	ds_read_b128 v[184:187], v170 offset:3072
	ds_read_b128 v[188:191], v170 offset:4096
	ds_read_b128 v[194:197], v170 offset:5120
	ds_read_b128 v[198:201], v170 offset:6144
	ds_read_b128 v[202:205], v170 offset:7168
	global_load_lds_dwordx4 v[164:165], off
	s_add_i32 m0, s12, 0xe000
	v_lshl_add_u64 v[164:165], s[8:9], 0, v[146:147]
	global_load_lds_dwordx4 v[164:165], off
	s_waitcnt lgkmcnt(8)
	s_barrier
	s_waitcnt lgkmcnt(0)
	v_mfma_f32_16x16x32_bf16 v[124:127], v[128:131], v[172:175], v[124:127]
	v_mfma_f32_16x16x32_bf16 v[120:123], v[156:159], v[172:175], v[120:123]
	v_mfma_f32_16x16x32_bf16 v[108:111], v[128:131], v[180:183], v[108:111]
	v_mfma_f32_16x16x32_bf16 v[104:107], v[156:159], v[180:183], v[104:107]
	v_mfma_f32_16x16x32_bf16 v[92:95], v[128:131], v[188:191], v[92:95]
	v_mfma_f32_16x16x32_bf16 v[88:91], v[156:159], v[188:191], v[88:91]
	v_mfma_f32_16x16x32_bf16 v[76:79], v[128:131], v[198:201], v[76:79]
	v_mfma_f32_16x16x32_bf16 v[72:75], v[156:159], v[198:201], v[72:75]
	v_mfma_f32_16x16x32_bf16 v[124:127], v[152:155], v[176:179], v[124:127]
	v_mfma_f32_16x16x32_bf16 v[120:123], v[160:163], v[176:179], v[120:123]
	v_mfma_f32_16x16x32_bf16 v[108:111], v[152:155], v[184:187], v[108:111]
	v_mfma_f32_16x16x32_bf16 v[104:107], v[160:163], v[184:187], v[104:107]
	v_mfma_f32_16x16x32_bf16 v[92:95], v[152:155], v[194:197], v[92:95]
	v_mfma_f32_16x16x32_bf16 v[88:91], v[160:163], v[194:197], v[88:91]
	v_mfma_f32_16x16x32_bf16 v[76:79], v[152:155], v[202:205], v[76:79]
	v_mfma_f32_16x16x32_bf16 v[72:75], v[160:163], v[202:205], v[72:75]
	s_barrier
	s_add_i32 s50, s82, s11
	v_lshl_add_u64 v[164:165], s[78:79], 0, v[134:135]
	s_mov_b32 m0, s50
	ds_read_b128 v[206:209], v171
	ds_read_b128 v[210:213], v171 offset:1024
	ds_read_b128 v[214:217], v171 offset:2048
	ds_read_b128 v[218:221], v171 offset:3072
	global_load_lds_dwordx4 v[164:165], off
	s_add_i32 m0, s50, 0x2000
	v_lshl_add_u64 v[222:223], s[78:79], 0, v[138:139]
	global_load_lds_dwordx4 v[222:223], off
	s_barrier
	s_waitcnt lgkmcnt(0)
	v_mfma_f32_16x16x32_bf16 v[116:119], v[206:209], v[172:175], v[116:119]
	v_mfma_f32_16x16x32_bf16 v[112:115], v[214:217], v[172:175], v[112:115]
	v_mfma_f32_16x16x32_bf16 v[100:103], v[206:209], v[180:183], v[100:103]
	v_mfma_f32_16x16x32_bf16 v[96:99], v[214:217], v[180:183], v[96:99]
	v_mfma_f32_16x16x32_bf16 v[84:87], v[206:209], v[188:191], v[84:87]
	v_mfma_f32_16x16x32_bf16 v[80:83], v[214:217], v[188:191], v[80:83]
	v_mfma_f32_16x16x32_bf16 v[68:71], v[206:209], v[198:201], v[68:71]
	v_mfma_f32_16x16x32_bf16 v[64:67], v[214:217], v[198:201], v[64:67]
	v_mfma_f32_16x16x32_bf16 v[116:119], v[210:213], v[176:179], v[116:119]
	v_mfma_f32_16x16x32_bf16 v[112:115], v[218:221], v[176:179], v[112:115]
	v_mfma_f32_16x16x32_bf16 v[100:103], v[210:213], v[184:187], v[100:103]
	v_mfma_f32_16x16x32_bf16 v[96:99], v[218:221], v[184:187], v[96:99]
	v_mfma_f32_16x16x32_bf16 v[84:87], v[210:213], v[194:197], v[84:87]
	v_mfma_f32_16x16x32_bf16 v[80:83], v[218:221], v[194:197], v[80:83]
	v_mfma_f32_16x16x32_bf16 v[68:71], v[210:213], v[202:205], v[68:71]
	v_mfma_f32_16x16x32_bf16 v[64:67], v[218:221], v[202:205], v[64:67]
	s_mov_b32 m0, s12
	v_lshl_add_u64 v[224:225], s[20:21], 0, v[132:133]
	s_barrier
	ds_read_b128 v[172:175], v170 offset:16384
	ds_read_b128 v[176:179], v170 offset:17408
	ds_read_b128 v[180:183], v170 offset:18432
	ds_read_b128 v[184:187], v170 offset:19456
	ds_read_b128 v[188:191], v170 offset:20480
	ds_read_b128 v[194:197], v170 offset:21504
	ds_read_b128 v[198:201], v170 offset:22528
	ds_read_b128 v[202:205], v170 offset:23552
	global_load_lds_dwordx4 v[224:225], off
	s_mov_b32 m0, s36
	v_lshl_add_u64 v[226:227], s[20:21], 0, v[136:137]
	global_load_lds_dwordx4 v[226:227], off
	s_barrier
	s_waitcnt lgkmcnt(0)
	v_mfma_f32_16x16x32_bf16 v[60:63], v[128:131], v[172:175], v[60:63]
	v_mfma_f32_16x16x32_bf16 v[56:59], v[156:159], v[172:175], v[56:59]
	v_mfma_f32_16x16x32_bf16 v[44:47], v[128:131], v[180:183], v[44:47]
	v_mfma_f32_16x16x32_bf16 v[40:43], v[156:159], v[180:183], v[40:43]
	v_mfma_f32_16x16x32_bf16 v[28:31], v[128:131], v[188:191], v[28:31]
	v_mfma_f32_16x16x32_bf16 v[24:27], v[156:159], v[188:191], v[24:27]
	v_mfma_f32_16x16x32_bf16 v[12:15], v[128:131], v[198:201], v[12:15]
	v_mfma_f32_16x16x32_bf16 v[8:11], v[156:159], v[198:201], v[8:11]
	v_mfma_f32_16x16x32_bf16 v[60:63], v[152:155], v[176:179], v[60:63]
	v_mfma_f32_16x16x32_bf16 v[56:59], v[160:163], v[176:179], v[56:59]
	v_mfma_f32_16x16x32_bf16 v[44:47], v[152:155], v[184:187], v[44:47]
	v_mfma_f32_16x16x32_bf16 v[40:43], v[160:163], v[184:187], v[40:43]
	v_mfma_f32_16x16x32_bf16 v[28:31], v[152:155], v[194:197], v[28:31]
	v_mfma_f32_16x16x32_bf16 v[24:27], v[160:163], v[194:197], v[24:27]
	v_mfma_f32_16x16x32_bf16 v[12:15], v[152:155], v[202:205], v[12:15]
	v_mfma_f32_16x16x32_bf16 v[8:11], v[160:163], v[202:205], v[8:11]
	s_barrier
	s_add_u32 s50, s78, 0x80000
	s_addc_u32 s51, s79, 0
	s_add_i32 s58, s84, s11
	s_mov_b32 m0, s58
	v_lshl_add_u64 v[128:129], s[50:51], 0, v[134:135]
	global_load_lds_dwordx4 v[128:129], off
	s_add_i32 m0, s58, 0x2000
	v_lshl_add_u64 v[128:129], s[50:51], 0, v[138:139]
	global_load_lds_dwordx4 v[128:129], off
	s_waitcnt vmcnt(6)
	s_barrier
	v_mfma_f32_16x16x32_bf16 v[52:55], v[206:209], v[172:175], v[52:55]
	v_mfma_f32_16x16x32_bf16 v[48:51], v[214:217], v[172:175], v[48:51]
	v_mfma_f32_16x16x32_bf16 v[36:39], v[206:209], v[180:183], v[36:39]
	v_mfma_f32_16x16x32_bf16 v[32:35], v[214:217], v[180:183], v[32:35]
	v_mfma_f32_16x16x32_bf16 v[20:23], v[206:209], v[188:191], v[20:23]
	v_mfma_f32_16x16x32_bf16 v[16:19], v[214:217], v[188:191], v[16:19]
	v_mfma_f32_16x16x32_bf16 v[4:7], v[206:209], v[198:201], v[4:7]
	v_mfma_f32_16x16x32_bf16 v[0:3], v[214:217], v[198:201], v[0:3]
	v_mfma_f32_16x16x32_bf16 v[52:55], v[210:213], v[176:179], v[52:55]
	v_mfma_f32_16x16x32_bf16 v[48:51], v[218:221], v[176:179], v[48:51]
	v_mfma_f32_16x16x32_bf16 v[36:39], v[210:213], v[184:187], v[36:39]
	v_mfma_f32_16x16x32_bf16 v[32:35], v[218:221], v[184:187], v[32:35]
	v_mfma_f32_16x16x32_bf16 v[20:23], v[210:213], v[194:197], v[20:23]
	v_mfma_f32_16x16x32_bf16 v[16:19], v[218:221], v[194:197], v[16:19]
	v_mfma_f32_16x16x32_bf16 v[4:7], v[210:213], v[202:205], v[4:7]
	v_mfma_f32_16x16x32_bf16 v[0:3], v[218:221], v[202:205], v[0:3]
	s_add_i32 s50, 0, 0x18000
	v_add_u32_e32 v140, s50, v167
	s_barrier
	ds_read_b128 v[128:131], v140
	ds_read_b128 v[152:155], v140 offset:1024
	ds_read_b128 v[156:159], v140 offset:2048
	ds_read_b128 v[160:163], v140 offset:3072
	s_add_u32 s20, s20, 0x80000
	s_addc_u32 s21, s21, 0
	s_mov_b32 m0, s37
	v_lshl_add_u64 v[206:207], s[20:21], 0, v[132:133]
	ds_read_b128 v[172:175], v170 offset:32768
	ds_read_b128 v[176:179], v170 offset:33792
	ds_read_b128 v[180:183], v170 offset:34816
	ds_read_b128 v[184:187], v170 offset:35840
	ds_read_b128 v[188:191], v170 offset:36864
	ds_read_b128 v[194:197], v170 offset:37888
	ds_read_b128 v[198:201], v170 offset:38912
	ds_read_b128 v[202:205], v170 offset:39936
	global_load_lds_dwordx4 v[206:207], off
	s_mov_b32 m0, s38
	v_lshl_add_u64 v[206:207], s[20:21], 0, v[136:137]
	global_load_lds_dwordx4 v[206:207], off
	s_waitcnt lgkmcnt(8)
	s_barrier
	s_waitcnt lgkmcnt(0)
	v_mfma_f32_16x16x32_bf16 v[124:127], v[128:131], v[172:175], v[124:127]
	v_mfma_f32_16x16x32_bf16 v[120:123], v[156:159], v[172:175], v[120:123]
	v_mfma_f32_16x16x32_bf16 v[108:111], v[128:131], v[180:183], v[108:111]
	v_mfma_f32_16x16x32_bf16 v[104:107], v[156:159], v[180:183], v[104:107]
	v_mfma_f32_16x16x32_bf16 v[92:95], v[128:131], v[188:191], v[92:95]
	v_mfma_f32_16x16x32_bf16 v[88:91], v[156:159], v[188:191], v[88:91]
	v_mfma_f32_16x16x32_bf16 v[76:79], v[128:131], v[198:201], v[76:79]
	v_mfma_f32_16x16x32_bf16 v[72:75], v[156:159], v[198:201], v[72:75]
	v_mfma_f32_16x16x32_bf16 v[124:127], v[152:155], v[176:179], v[124:127]
	v_mfma_f32_16x16x32_bf16 v[120:123], v[160:163], v[176:179], v[120:123]
	v_mfma_f32_16x16x32_bf16 v[108:111], v[152:155], v[184:187], v[108:111]
	v_mfma_f32_16x16x32_bf16 v[104:107], v[160:163], v[184:187], v[104:107]
	v_mfma_f32_16x16x32_bf16 v[92:95], v[152:155], v[194:197], v[92:95]
	v_mfma_f32_16x16x32_bf16 v[88:91], v[160:163], v[194:197], v[88:91]
	v_mfma_f32_16x16x32_bf16 v[76:79], v[152:155], v[202:205], v[76:79]
	v_mfma_f32_16x16x32_bf16 v[72:75], v[160:163], v[202:205], v[72:75]
	s_barrier
	s_add_i32 s51, 0, 0x1c000
	s_add_i32 s20, s50, s11
	v_add_u32_e32 v140, s51, v167
	v_lshl_add_u64 v[164:165], v[164:165], 0, s[18:19]
	s_mov_b32 m0, s20
	ds_read_b128 v[206:209], v140
	ds_read_b128 v[210:213], v140 offset:1024
	ds_read_b128 v[214:217], v140 offset:2048
	ds_read_b128 v[218:221], v140 offset:3072
	global_load_lds_dwordx4 v[164:165], off
	s_add_i32 m0, s20, 0x2000
	v_lshl_add_u64 v[164:165], v[222:223], 0, s[18:19]
	global_load_lds_dwordx4 v[164:165], off
	s_barrier
	s_waitcnt lgkmcnt(0)
	v_mfma_f32_16x16x32_bf16 v[116:119], v[206:209], v[172:175], v[116:119]
	v_mfma_f32_16x16x32_bf16 v[112:115], v[214:217], v[172:175], v[112:115]
	v_mfma_f32_16x16x32_bf16 v[100:103], v[206:209], v[180:183], v[100:103]
	v_mfma_f32_16x16x32_bf16 v[96:99], v[214:217], v[180:183], v[96:99]
	v_mfma_f32_16x16x32_bf16 v[84:87], v[206:209], v[188:191], v[84:87]
	v_mfma_f32_16x16x32_bf16 v[80:83], v[214:217], v[188:191], v[80:83]
	v_mfma_f32_16x16x32_bf16 v[68:71], v[206:209], v[198:201], v[68:71]
	v_mfma_f32_16x16x32_bf16 v[64:67], v[214:217], v[198:201], v[64:67]
	v_mfma_f32_16x16x32_bf16 v[116:119], v[210:213], v[176:179], v[116:119]
	v_mfma_f32_16x16x32_bf16 v[112:115], v[218:221], v[176:179], v[112:115]
	v_mfma_f32_16x16x32_bf16 v[100:103], v[210:213], v[184:187], v[100:103]
	v_mfma_f32_16x16x32_bf16 v[96:99], v[218:221], v[184:187], v[96:99]
	v_mfma_f32_16x16x32_bf16 v[84:87], v[210:213], v[194:197], v[84:87]
	v_mfma_f32_16x16x32_bf16 v[80:83], v[218:221], v[194:197], v[80:83]
	v_mfma_f32_16x16x32_bf16 v[68:71], v[210:213], v[202:205], v[68:71]
	v_mfma_f32_16x16x32_bf16 v[64:67], v[218:221], v[202:205], v[64:67]
	s_mov_b32 m0, s57
	v_lshl_add_u64 v[164:165], v[224:225], 0, s[18:19]
	s_barrier
	ds_read_b128 v[172:175], v170 offset:49152
	ds_read_b128 v[176:179], v170 offset:50176
	ds_read_b128 v[180:183], v170 offset:51200
	ds_read_b128 v[184:187], v170 offset:52224
	ds_read_b128 v[188:191], v170 offset:53248
	ds_read_b128 v[194:197], v170 offset:54272
	ds_read_b128 v[198:201], v170 offset:55296
	ds_read_b128 v[202:205], v170 offset:56320
	global_load_lds_dwordx4 v[164:165], off
	s_mov_b32 m0, s80
	v_lshl_add_u64 v[164:165], v[226:227], 0, s[18:19]
	global_load_lds_dwordx4 v[164:165], off
	s_barrier
	s_waitcnt lgkmcnt(0)
	v_mfma_f32_16x16x32_bf16 v[60:63], v[128:131], v[172:175], v[60:63]
	v_mfma_f32_16x16x32_bf16 v[56:59], v[156:159], v[172:175], v[56:59]
	v_mfma_f32_16x16x32_bf16 v[44:47], v[128:131], v[180:183], v[44:47]
	v_mfma_f32_16x16x32_bf16 v[40:43], v[156:159], v[180:183], v[40:43]
	v_mfma_f32_16x16x32_bf16 v[28:31], v[128:131], v[188:191], v[28:31]
	v_mfma_f32_16x16x32_bf16 v[24:27], v[156:159], v[188:191], v[24:27]
	v_mfma_f32_16x16x32_bf16 v[12:15], v[128:131], v[198:201], v[12:15]
	v_mfma_f32_16x16x32_bf16 v[8:11], v[156:159], v[198:201], v[8:11]
	v_mfma_f32_16x16x32_bf16 v[60:63], v[152:155], v[176:179], v[60:63]
	v_mfma_f32_16x16x32_bf16 v[56:59], v[160:163], v[176:179], v[56:59]
	v_mfma_f32_16x16x32_bf16 v[44:47], v[152:155], v[184:187], v[44:47]
	v_mfma_f32_16x16x32_bf16 v[40:43], v[160:163], v[184:187], v[40:43]
	v_mfma_f32_16x16x32_bf16 v[28:31], v[152:155], v[194:197], v[28:31]
	v_mfma_f32_16x16x32_bf16 v[24:27], v[160:163], v[194:197], v[24:27]
	v_mfma_f32_16x16x32_bf16 v[12:15], v[152:155], v[202:205], v[12:15]
	v_mfma_f32_16x16x32_bf16 v[8:11], v[160:163], v[202:205], v[8:11]
	s_barrier
	s_add_u32 s20, s78, 0x80080
	s_addc_u32 s21, s79, 0
	s_add_i32 s50, s51, s11
	s_mov_b32 m0, s50
	v_lshl_add_u64 v[128:129], s[20:21], 0, v[134:135]
	global_load_lds_dwordx4 v[128:129], off
	s_add_i32 m0, s50, 0x2000
	v_lshl_add_u64 v[128:129], s[20:21], 0, v[138:139]
	global_load_lds_dwordx4 v[128:129], off
	s_waitcnt vmcnt(6)
	s_barrier
	v_mfma_f32_16x16x32_bf16 v[52:55], v[206:209], v[172:175], v[52:55]
	v_mfma_f32_16x16x32_bf16 v[48:51], v[214:217], v[172:175], v[48:51]
	v_mfma_f32_16x16x32_bf16 v[36:39], v[206:209], v[180:183], v[36:39]
	v_mfma_f32_16x16x32_bf16 v[32:35], v[214:217], v[180:183], v[32:35]
	v_mfma_f32_16x16x32_bf16 v[20:23], v[206:209], v[188:191], v[20:23]
	v_mfma_f32_16x16x32_bf16 v[16:19], v[214:217], v[188:191], v[16:19]
	v_mfma_f32_16x16x32_bf16 v[4:7], v[206:209], v[198:201], v[4:7]
	v_mfma_f32_16x16x32_bf16 v[0:3], v[214:217], v[198:201], v[0:3]
	v_mfma_f32_16x16x32_bf16 v[52:55], v[210:213], v[176:179], v[52:55]
	v_mfma_f32_16x16x32_bf16 v[48:51], v[218:221], v[176:179], v[48:51]
	v_mfma_f32_16x16x32_bf16 v[36:39], v[210:213], v[184:187], v[36:39]
	v_mfma_f32_16x16x32_bf16 v[32:35], v[218:221], v[184:187], v[32:35]
	v_mfma_f32_16x16x32_bf16 v[20:23], v[210:213], v[194:197], v[20:23]
	v_mfma_f32_16x16x32_bf16 v[16:19], v[218:221], v[194:197], v[16:19]
	v_mfma_f32_16x16x32_bf16 v[4:7], v[210:213], v[202:205], v[4:7]
	v_mfma_f32_16x16x32_bf16 v[0:3], v[218:221], v[202:205], v[0:3]
	s_add_i32 s35, s35, 2
	s_add_u32 s8, s8, 0x100
	s_addc_u32 s9, s9, 0
	s_add_u32 s33, s33, 0x100
	s_addc_u32 s34, s34, 0
	s_cmp_gt_u32 s35, 29
	s_barrier
	s_cbranch_scc0 .LBB0_237
	s_lshl_b32 s65, s6, 8
	v_lshl_add_u32 v154, s0, 8, v166
	v_or_b32_e32 v152, s65, v168
	v_ashrrev_i32_e32 v155, 31, v154
	v_lshlrev_b64 v[162:163], 7, v[154:155]
	v_lshlrev_b64 v[160:161], 11, v[154:155]
	v_mad_i64_i32 v[158:159], s[0:1], v154, s85, 0
	v_cmp_gt_i32_e64 s[8:9], s39, v154
	v_lshlrev_b64 v[156:157], 12, v[154:155]
	v_cvt_pk_bf16_f32 v128, v124, v125
	v_cvt_pk_bf16_f32 v129, v126, v127
	v_cvt_pk_bf16_f32 v130, v120, v121
	v_cvt_pk_bf16_f32 v131, v122, v123
	v_cmp_lt_i32_e64 s[6:7], s86, v152
	s_and_saveexec_b64 s[0:1], s[6:7]
	s_xor_b64 s[0:1], exec, s[0:1]
	s_cbranch_execz .LBB0_255
	s_cmpk_gt_u32 s65, 0xbff
	s_mov_b64 s[20:21], -1
	s_cbranch_scc0 .LBB0_251
	s_cmpk_gt_u32 s65, 0x17ff
	s_cbranch_scc0 .LBB0_248
	s_cmpk_gt_u32 s65, 0x1bff
	s_cbranch_scc0 .LBB0_245
	v_cmp_gt_u32_e32 vcc, s87, v152
	s_and_saveexec_b64 s[20:21], vcc
	s_cbranch_execz .LBB0_244
	v_readlane_b32 s22, v254, 24
	v_readlane_b32 s23, v254, 25
	v_mov_b32_e32 v153, v141
	s_nop 0
	v_lshl_add_u64 v[164:165], s[22:23], 0, v[162:163]
	v_lshl_add_u64 v[164:165], v[152:153], 2, v[164:165]
	v_add_co_u32_e32 v172, vcc, 0xffff9000, v164
	s_nop 1
	v_addc_co_u32_e32 v173, vcc, -1, v165, vcc
	v_add_co_u32_e32 v164, vcc, 0xffffa000, v164
	global_store_dwordx4 v[172:173], v[124:127], off
	s_nop 0
	v_addc_co_u32_e32 v165, vcc, -1, v165, vcc
	global_store_dwordx4 v[164:165], v[120:123], off offset:-4080

.LBB0_912:
	ds_read_b128 v[150:153], v161
	ds_read_b128 v[154:157], v161 offset:1024
	ds_read_b128 v[164:167], v161 offset:2048
	ds_read_b128 v[168:171], v161 offset:3072
	s_add_u32 s20, s48, 0xfff80080
	s_addc_u32 s21, s49, -1
	s_cmp_eq_u32 s47, 28
	s_cselect_b32 s21, s17, s21
	s_cselect_b32 s20, s33, s20
	s_cselect_b32 s51, s15, s45
	s_cselect_b32 s50, s34, s35
	v_lshl_add_u64 v[208:209], s[48:49], 0, v[138:139]
	s_add_i32 m0, s36, 0xc000
	ds_read_b128 v[172:175], v162
	ds_read_b128 v[176:179], v162 offset:1024
	ds_read_b128 v[180:183], v162 offset:2048
	ds_read_b128 v[184:187], v162 offset:3072
	ds_read_b128 v[188:191], v162 offset:4096
	ds_read_b128 v[196:199], v162 offset:5120
	ds_read_b128 v[200:203], v162 offset:6144
	ds_read_b128 v[204:207], v162 offset:7168
	global_load_lds_dwordx4 v[208:209], off
	s_add_i32 m0, s36, 0xe000
	v_lshl_add_u64 v[208:209], s[48:49], 0, v[140:141]
	global_load_lds_dwordx4 v[208:209], off
	s_waitcnt lgkmcnt(8)
	s_barrier
	s_waitcnt lgkmcnt(0)
	v_mfma_f32_16x16x32_bf16 v[124:127], v[150:153], v[172:175], v[124:127]
	v_mfma_f32_16x16x32_bf16 v[120:123], v[164:167], v[172:175], v[120:123]
	v_mfma_f32_16x16x32_bf16 v[108:111], v[150:153], v[180:183], v[108:111]
	v_mfma_f32_16x16x32_bf16 v[104:107], v[164:167], v[180:183], v[104:107]
	v_mfma_f32_16x16x32_bf16 v[92:95], v[150:153], v[188:191], v[92:95]
	v_mfma_f32_16x16x32_bf16 v[88:91], v[164:167], v[188:191], v[88:91]
	v_mfma_f32_16x16x32_bf16 v[76:79], v[150:153], v[200:203], v[76:79]
	v_mfma_f32_16x16x32_bf16 v[72:75], v[164:167], v[200:203], v[72:75]
	v_mfma_f32_16x16x32_bf16 v[124:127], v[154:157], v[176:179], v[124:127]
	v_mfma_f32_16x16x32_bf16 v[120:123], v[168:171], v[176:179], v[120:123]
	v_mfma_f32_16x16x32_bf16 v[108:111], v[154:157], v[184:187], v[108:111]
	v_mfma_f32_16x16x32_bf16 v[104:107], v[168:171], v[184:187], v[104:107]
	v_mfma_f32_16x16x32_bf16 v[92:95], v[154:157], v[196:199], v[92:95]
	v_mfma_f32_16x16x32_bf16 v[88:91], v[168:171], v[196:199], v[88:91]
	v_mfma_f32_16x16x32_bf16 v[76:79], v[154:157], v[204:207], v[76:79]
	v_mfma_f32_16x16x32_bf16 v[72:75], v[168:171], v[204:207], v[72:75]
	s_barrier
	s_add_i32 s65, s62, s23
	v_lshl_add_u64 v[224:225], s[50:51], 0, v[130:131]
	s_mov_b32 m0, s65
	ds_read_b128 v[208:211], v163
	ds_read_b128 v[212:215], v163 offset:1024
	ds_read_b128 v[216:219], v163 offset:2048
	ds_read_b128 v[220:223], v163 offset:3072
	global_load_lds_dwordx4 v[224:225], off
	s_add_i32 m0, s65, 0x2000
	v_lshl_add_u64 v[226:227], s[50:51], 0, v[134:135]
	global_load_lds_dwordx4 v[226:227], off
	s_barrier
	s_waitcnt lgkmcnt(0)
	v_mfma_f32_16x16x32_bf16 v[116:119], v[208:211], v[172:175], v[116:119]
	v_mfma_f32_16x16x32_bf16 v[112:115], v[216:219], v[172:175], v[112:115]
	v_mfma_f32_16x16x32_bf16 v[100:103], v[208:211], v[180:183], v[100:103]
	v_mfma_f32_16x16x32_bf16 v[96:99], v[216:219], v[180:183], v[96:99]
	v_mfma_f32_16x16x32_bf16 v[84:87], v[208:211], v[188:191], v[84:87]
	v_mfma_f32_16x16x32_bf16 v[80:83], v[216:219], v[188:191], v[80:83]
	v_mfma_f32_16x16x32_bf16 v[68:71], v[208:211], v[200:203], v[68:71]
	v_mfma_f32_16x16x32_bf16 v[64:67], v[216:219], v[200:203], v[64:67]
	v_mfma_f32_16x16x32_bf16 v[116:119], v[212:215], v[176:179], v[116:119]
	v_mfma_f32_16x16x32_bf16 v[112:115], v[220:223], v[176:179], v[112:115]
	v_mfma_f32_16x16x32_bf16 v[100:103], v[212:215], v[184:187], v[100:103]
	v_mfma_f32_16x16x32_bf16 v[96:99], v[220:223], v[184:187], v[96:99]
	v_mfma_f32_16x16x32_bf16 v[84:87], v[212:215], v[196:199], v[84:87]
	v_mfma_f32_16x16x32_bf16 v[80:83], v[220:223], v[196:199], v[80:83]
	v_mfma_f32_16x16x32_bf16 v[68:71], v[212:215], v[204:207], v[68:71]
	v_mfma_f32_16x16x32_bf16 v[64:67], v[220:223], v[204:207], v[64:67]
	s_mov_b32 m0, s36
	v_lshl_add_u64 v[228:229], s[20:21], 0, v[128:129]
	s_barrier
	ds_read_b128 v[172:175], v162 offset:16384
	ds_read_b128 v[176:179], v162 offset:17408
	ds_read_b128 v[180:183], v162 offset:18432
	ds_read_b128 v[184:187], v162 offset:19456
	ds_read_b128 v[188:191], v162 offset:20480
	ds_read_b128 v[196:199], v162 offset:21504
	ds_read_b128 v[200:203], v162 offset:22528
	ds_read_b128 v[204:207], v162 offset:23552
	global_load_lds_dwordx4 v[228:229], off
	s_mov_b32 m0, s37
	v_lshl_add_u64 v[230:231], s[20:21], 0, v[132:133]
	global_load_lds_dwordx4 v[230:231], off
	s_barrier
	s_waitcnt lgkmcnt(0)
	v_mfma_f32_16x16x32_bf16 v[60:63], v[150:153], v[172:175], v[60:63]
	v_mfma_f32_16x16x32_bf16 v[56:59], v[164:167], v[172:175], v[56:59]
	v_mfma_f32_16x16x32_bf16 v[44:47], v[150:153], v[180:183], v[44:47]
	v_mfma_f32_16x16x32_bf16 v[40:43], v[164:167], v[180:183], v[40:43]
	v_mfma_f32_16x16x32_bf16 v[28:31], v[150:153], v[188:191], v[28:31]
	v_mfma_f32_16x16x32_bf16 v[24:27], v[164:167], v[188:191], v[24:27]
	v_mfma_f32_16x16x32_bf16 v[12:15], v[150:153], v[200:203], v[12:15]
	v_mfma_f32_16x16x32_bf16 v[8:11], v[164:167], v[200:203], v[8:11]
	v_mfma_f32_16x16x32_bf16 v[60:63], v[154:157], v[176:179], v[60:63]
	v_mfma_f32_16x16x32_bf16 v[56:59], v[168:171], v[176:179], v[56:59]
	v_mfma_f32_16x16x32_bf16 v[44:47], v[154:157], v[184:187], v[44:47]
	v_mfma_f32_16x16x32_bf16 v[40:43], v[168:171], v[184:187], v[40:43]
	v_mfma_f32_16x16x32_bf16 v[28:31], v[154:157], v[196:199], v[28:31]
	v_mfma_f32_16x16x32_bf16 v[24:27], v[168:171], v[196:199], v[24:27]
	v_mfma_f32_16x16x32_bf16 v[12:15], v[154:157], v[204:207], v[12:15]
	v_mfma_f32_16x16x32_bf16 v[8:11], v[168:171], v[204:207], v[8:11]
	s_barrier
	s_add_u32 s66, s50, 0x80000
	s_addc_u32 s67, s51, 0
	s_add_i32 s65, s63, s23
	s_mov_b32 m0, s65
	v_lshl_add_u64 v[150:151], s[66:67], 0, v[130:131]
	global_load_lds_dwordx4 v[150:151], off
	s_add_i32 m0, s65, 0x2000
	v_lshl_add_u64 v[150:151], s[66:67], 0, v[134:135]
	global_load_lds_dwordx4 v[150:151], off
	s_waitcnt vmcnt(6)
	s_barrier
	v_mfma_f32_16x16x32_bf16 v[52:55], v[208:211], v[172:175], v[52:55]
	v_mfma_f32_16x16x32_bf16 v[48:51], v[216:219], v[172:175], v[48:51]
	v_mfma_f32_16x16x32_bf16 v[36:39], v[208:211], v[180:183], v[36:39]
	v_mfma_f32_16x16x32_bf16 v[32:35], v[216:219], v[180:183], v[32:35]
	v_mfma_f32_16x16x32_bf16 v[20:23], v[208:211], v[188:191], v[20:23]
	v_mfma_f32_16x16x32_bf16 v[16:19], v[216:219], v[188:191], v[16:19]
	v_mfma_f32_16x16x32_bf16 v[4:7], v[208:211], v[200:203], v[4:7]
	v_mfma_f32_16x16x32_bf16 v[0:3], v[216:219], v[200:203], v[0:3]
	v_mfma_f32_16x16x32_bf16 v[52:55], v[212:215], v[176:179], v[52:55]
	v_mfma_f32_16x16x32_bf16 v[48:51], v[220:223], v[176:179], v[48:51]
	v_mfma_f32_16x16x32_bf16 v[36:39], v[212:215], v[184:187], v[36:39]
	v_mfma_f32_16x16x32_bf16 v[32:35], v[220:223], v[184:187], v[32:35]
	v_mfma_f32_16x16x32_bf16 v[20:23], v[212:215], v[196:199], v[20:23]
	v_mfma_f32_16x16x32_bf16 v[16:19], v[220:223], v[196:199], v[16:19]
	v_mfma_f32_16x16x32_bf16 v[4:7], v[212:215], v[204:207], v[4:7]
	v_mfma_f32_16x16x32_bf16 v[0:3], v[220:223], v[204:207], v[0:3]
	s_add_i32 s65, 0, 0x18000
	v_add_u32_e32 v136, s65, v158
	s_barrier
	ds_read_b128 v[150:153], v136
	ds_read_b128 v[154:157], v136 offset:1024
	ds_read_b128 v[164:167], v136 offset:2048
	ds_read_b128 v[168:171], v136 offset:3072
	s_add_u32 s20, s20, 0x80000
	s_addc_u32 s21, s21, 0
	s_mov_b32 m0, s38
	v_lshl_add_u64 v[208:209], s[20:21], 0, v[128:129]
	ds_read_b128 v[172:175], v162 offset:32768
	ds_read_b128 v[176:179], v162 offset:33792
	ds_read_b128 v[180:183], v162 offset:34816
	ds_read_b128 v[184:187], v162 offset:35840
	ds_read_b128 v[188:191], v162 offset:36864
	ds_read_b128 v[196:199], v162 offset:37888
	ds_read_b128 v[200:203], v162 offset:38912
	ds_read_b128 v[204:207], v162 offset:39936
	global_load_lds_dwordx4 v[208:209], off
	s_mov_b32 m0, s39
	v_lshl_add_u64 v[208:209], s[20:21], 0, v[132:133]
	global_load_lds_dwordx4 v[208:209], off
	s_waitcnt lgkmcnt(8)
	s_barrier
	s_waitcnt lgkmcnt(0)
	v_mfma_f32_16x16x32_bf16 v[124:127], v[150:153], v[172:175], v[124:127]
	v_mfma_f32_16x16x32_bf16 v[120:123], v[164:167], v[172:175], v[120:123]
	v_mfma_f32_16x16x32_bf16 v[108:111], v[150:153], v[180:183], v[108:111]
	v_mfma_f32_16x16x32_bf16 v[104:107], v[164:167], v[180:183], v[104:107]
	v_mfma_f32_16x16x32_bf16 v[92:95], v[150:153], v[188:191], v[92:95]
	v_mfma_f32_16x16x32_bf16 v[88:91], v[164:167], v[188:191], v[88:91]
	v_mfma_f32_16x16x32_bf16 v[76:79], v[150:153], v[200:203], v[76:79]
	v_mfma_f32_16x16x32_bf16 v[72:75], v[164:167], v[200:203], v[72:75]
	v_mfma_f32_16x16x32_bf16 v[124:127], v[154:157], v[176:179], v[124:127]
	v_mfma_f32_16x16x32_bf16 v[120:123], v[168:171], v[176:179], v[120:123]
	v_mfma_f32_16x16x32_bf16 v[108:111], v[154:157], v[184:187], v[108:111]
	v_mfma_f32_16x16x32_bf16 v[104:107], v[168:171], v[184:187], v[104:107]
	v_mfma_f32_16x16x32_bf16 v[92:95], v[154:157], v[196:199], v[92:95]
	v_mfma_f32_16x16x32_bf16 v[88:91], v[168:171], v[196:199], v[88:91]
	v_mfma_f32_16x16x32_bf16 v[76:79], v[154:157], v[204:207], v[76:79]
	v_mfma_f32_16x16x32_bf16 v[72:75], v[168:171], v[204:207], v[72:75]
	s_barrier
	s_add_i32 s66, 0, 0x1c000
	s_add_i32 s20, s65, s23
	v_add_u32_e32 v136, s66, v158
	v_lshl_add_u64 v[224:225], v[224:225], 0, s[10:11]
	s_mov_b32 m0, s20
	ds_read_b128 v[208:211], v136
	ds_read_b128 v[212:215], v136 offset:1024
	ds_read_b128 v[216:219], v136 offset:2048
	ds_read_b128 v[220:223], v136 offset:3072
	global_load_lds_dwordx4 v[224:225], off
	s_add_i32 m0, s20, 0x2000
	v_lshl_add_u64 v[224:225], v[226:227], 0, s[10:11]
	global_load_lds_dwordx4 v[224:225], off
	s_barrier
	s_waitcnt lgkmcnt(0)
	v_mfma_f32_16x16x32_bf16 v[116:119], v[208:211], v[172:175], v[116:119]
	v_mfma_f32_16x16x32_bf16 v[112:115], v[216:219], v[172:175], v[112:115]
	v_mfma_f32_16x16x32_bf16 v[100:103], v[208:211], v[180:183], v[100:103]
	v_mfma_f32_16x16x32_bf16 v[96:99], v[216:219], v[180:183], v[96:99]
	v_mfma_f32_16x16x32_bf16 v[84:87], v[208:211], v[188:191], v[84:87]
	v_mfma_f32_16x16x32_bf16 v[80:83], v[216:219], v[188:191], v[80:83]
	v_mfma_f32_16x16x32_bf16 v[68:71], v[208:211], v[200:203], v[68:71]
	v_mfma_f32_16x16x32_bf16 v[64:67], v[216:219], v[200:203], v[64:67]
	v_mfma_f32_16x16x32_bf16 v[116:119], v[212:215], v[176:179], v[116:119]
	v_mfma_f32_16x16x32_bf16 v[112:115], v[220:223], v[176:179], v[112:115]
	v_mfma_f32_16x16x32_bf16 v[100:103], v[212:215], v[184:187], v[100:103]
	v_mfma_f32_16x16x32_bf16 v[96:99], v[220:223], v[184:187], v[96:99]
	v_mfma_f32_16x16x32_bf16 v[84:87], v[212:215], v[196:199], v[84:87]
	v_mfma_f32_16x16x32_bf16 v[80:83], v[220:223], v[196:199], v[80:83]
	v_mfma_f32_16x16x32_bf16 v[68:71], v[212:215], v[204:207], v[68:71]
	v_mfma_f32_16x16x32_bf16 v[64:67], v[220:223], v[204:207], v[64:67]
	s_mov_b32 m0, s58
	v_lshl_add_u64 v[224:225], v[228:229], 0, s[10:11]
	s_barrier
	ds_read_b128 v[172:175], v162 offset:49152
	ds_read_b128 v[176:179], v162 offset:50176
	ds_read_b128 v[180:183], v162 offset:51200
	ds_read_b128 v[184:187], v162 offset:52224
	ds_read_b128 v[188:191], v162 offset:53248
	ds_read_b128 v[196:199], v162 offset:54272
	ds_read_b128 v[200:203], v162 offset:55296
	ds_read_b128 v[204:207], v162 offset:56320
	global_load_lds_dwordx4 v[224:225], off
	s_mov_b32 m0, s59
	v_lshl_add_u64 v[224:225], v[230:231], 0, s[10:11]
	global_load_lds_dwordx4 v[224:225], off
	s_barrier
	s_waitcnt lgkmcnt(0)
	v_mfma_f32_16x16x32_bf16 v[60:63], v[150:153], v[172:175], v[60:63]
	v_mfma_f32_16x16x32_bf16 v[56:59], v[164:167], v[172:175], v[56:59]
	v_mfma_f32_16x16x32_bf16 v[44:47], v[150:153], v[180:183], v[44:47]
	v_mfma_f32_16x16x32_bf16 v[40:43], v[164:167], v[180:183], v[40:43]
	v_mfma_f32_16x16x32_bf16 v[28:31], v[150:153], v[188:191], v[28:31]
	v_mfma_f32_16x16x32_bf16 v[24:27], v[164:167], v[188:191], v[24:27]
	v_mfma_f32_16x16x32_bf16 v[12:15], v[150:153], v[200:203], v[12:15]
	v_mfma_f32_16x16x32_bf16 v[8:11], v[164:167], v[200:203], v[8:11]
	v_mfma_f32_16x16x32_bf16 v[60:63], v[154:157], v[176:179], v[60:63]
	v_mfma_f32_16x16x32_bf16 v[56:59], v[168:171], v[176:179], v[56:59]
	v_mfma_f32_16x16x32_bf16 v[44:47], v[154:157], v[184:187], v[44:47]
	v_mfma_f32_16x16x32_bf16 v[40:43], v[168:171], v[184:187], v[40:43]
	v_mfma_f32_16x16x32_bf16 v[28:31], v[154:157], v[196:199], v[28:31]
	v_mfma_f32_16x16x32_bf16 v[24:27], v[168:171], v[196:199], v[24:27]
	v_mfma_f32_16x16x32_bf16 v[12:15], v[154:157], v[204:207], v[12:15]
	v_mfma_f32_16x16x32_bf16 v[8:11], v[168:171], v[204:207], v[8:11]
	s_barrier
	s_add_u32 s20, s50, 0x80080
	s_addc_u32 s21, s51, 0
	s_add_i32 s50, s66, s23
	s_mov_b32 m0, s50
	v_lshl_add_u64 v[150:151], s[20:21], 0, v[130:131]
	global_load_lds_dwordx4 v[150:151], off
	s_add_i32 m0, s50, 0x2000
	v_lshl_add_u64 v[150:151], s[20:21], 0, v[134:135]
	global_load_lds_dwordx4 v[150:151], off
	s_waitcnt vmcnt(6)
	s_barrier
	v_mfma_f32_16x16x32_bf16 v[52:55], v[208:211], v[172:175], v[52:55]
	v_mfma_f32_16x16x32_bf16 v[48:51], v[216:219], v[172:175], v[48:51]
	v_mfma_f32_16x16x32_bf16 v[36:39], v[208:211], v[180:183], v[36:39]
	v_mfma_f32_16x16x32_bf16 v[32:35], v[216:219], v[180:183], v[32:35]
	v_mfma_f32_16x16x32_bf16 v[20:23], v[208:211], v[188:191], v[20:23]
	v_mfma_f32_16x16x32_bf16 v[16:19], v[216:219], v[188:191], v[16:19]
	v_mfma_f32_16x16x32_bf16 v[4:7], v[208:211], v[200:203], v[4:7]
	v_mfma_f32_16x16x32_bf16 v[0:3], v[216:219], v[200:203], v[0:3]
	v_mfma_f32_16x16x32_bf16 v[52:55], v[212:215], v[176:179], v[52:55]
	v_mfma_f32_16x16x32_bf16 v[48:51], v[220:223], v[176:179], v[48:51]
	v_mfma_f32_16x16x32_bf16 v[36:39], v[212:215], v[184:187], v[36:39]
	v_mfma_f32_16x16x32_bf16 v[32:35], v[220:223], v[184:187], v[32:35]
	v_mfma_f32_16x16x32_bf16 v[20:23], v[212:215], v[196:199], v[20:23]
	v_mfma_f32_16x16x32_bf16 v[16:19], v[220:223], v[196:199], v[16:19]
	v_mfma_f32_16x16x32_bf16 v[4:7], v[212:215], v[204:207], v[4:7]
	v_mfma_f32_16x16x32_bf16 v[0:3], v[220:223], v[204:207], v[0:3]
	s_add_i32 s47, s47, 2
	s_add_u32 s48, s48, 0x100
	s_addc_u32 s49, s49, 0
	s_add_u32 s35, s35, 0x100
	s_addc_u32 s45, s45, 0
	s_cmp_gt_u32 s47, 29
	s_cbranch_scc0 .Lepi_nl_about
	s_cmp_lg_u32 s57, 64
	s_cbranch_scc1 .Lepi_nl_about
	s_lshl_b32 s15, s46, 8
	s_add_i32 s15, s15, s57
	v_or_b32_e32 v154, s15, v147
	s_add_i32 s17, s15, 0xffffe000
	v_lshl_or_b32 v150, s44, 8, v160
	s_lshr_b32 s17, s17, 12
	v_lshlrev_b32_e32 v151, 13, v154
	s_add_i32 s17, s17, 1
	s_sub_u32 s34, s54, 0x4000000
	s_subb_u32 s35, s55, 0
	v_lshlrev_b32_e32 v152, 12, v154
	s_cmp_gt_i32 s15, s64
	s_cselect_b32 s34, s34, s52
	s_cselect_b32 s35, s35, s53
	s_cselect_b32 s17, s17, 0
	s_mul_i32 s17, s17, 0xc000
	v_lshl_add_u32 v151, v150, 2, v151
	s_add_u32 s20, s8, s17
	s_addc_u32 s21, s9, 0
	v_lshl_add_u32 v152, v150, 1, v152
	v_lshlrev_b32_e32 v153, 2, v150
	s_nop 0
	global_load_dwordx4 v[196:199], v153, s[20:21]
	global_load_dwordx4 v[200:203], v153, s[20:21] offset:16
	global_load_dwordx4 v[204:207], v153, s[20:21] offset:512
	global_load_dwordx4 v[208:211], v153, s[20:21] offset:528
	global_load_dwordx4 v[164:167], v151, s[34:35]
	global_load_dwordx4 v[168:171], v151, s[34:35] offset:16
	global_load_dwordx4 v[172:175], v151, s[34:35] offset:512
	global_load_dwordx4 v[176:179], v151, s[34:35] offset:528
	v_add_u32_e32 v155, 0x20000, v151
	global_load_dwordx4 v[180:183], v155, s[34:35]
	global_load_dwordx4 v[184:187], v155, s[34:35] offset:16
	global_load_dwordx4 v[188:191], v155, s[34:35] offset:512
	global_load_dwordx4 v[212:215], v155, s[34:35] offset:528
	v_add_u32_e32 v155, 0x40000, v151
	global_load_dwordx4 v[216:219], v155, s[34:35]
	global_load_dwordx4 v[220:223], v155, s[34:35] offset:16
	global_load_dwordx4 v[224:227], v155, s[34:35] offset:512
	global_load_dwordx4 v[228:231], v155, s[34:35] offset:528
	v_add_u32_e32 v155, 0x60000, v151
	global_load_dwordx4 v[236:239], v155, s[34:35]
	global_load_dwordx4 v[240:243], v155, s[34:35] offset:16
	global_load_dwordx4 v[244:247], v155, s[34:35] offset:512
	global_load_dwordx4 v[248:251], v155, s[34:35] offset:528
	s_waitcnt vmcnt(0)
	v_pk_fma_f32 v[124:125], v[124:125], v[196:197], v[164:165]
	v_pk_fma_f32 v[126:127], v[126:127], v[198:199], v[166:167]
	v_pk_fma_f32 v[120:121], v[120:121], v[200:201], v[168:169]
	v_pk_fma_f32 v[122:123], v[122:123], v[202:203], v[170:171]
	v_cvt_pk_bf16_f32 v123, v122, v123
	v_cvt_pk_bf16_f32 v122, v120, v121
	v_cvt_pk_bf16_f32 v121, v126, v127
	v_cvt_pk_bf16_f32 v120, v124, v125
	global_store_dwordx4 v152, v[120:123], s[74:75]
	v_pk_fma_f32 v[116:117], v[116:117], v[204:205], v[172:173]
	v_pk_fma_f32 v[118:119], v[118:119], v[206:207], v[174:175]
	v_pk_fma_f32 v[112:113], v[112:113], v[208:209], v[176:177]
	v_pk_fma_f32 v[114:115], v[114:115], v[210:211], v[178:179]
	v_cvt_pk_bf16_f32 v115, v114, v115
	v_cvt_pk_bf16_f32 v114, v112, v113
	v_cvt_pk_bf16_f32 v113, v118, v119
	v_cvt_pk_bf16_f32 v112, v116, v117
	global_store_dwordx4 v152, v[112:115], s[74:75] offset:256
	v_pk_fma_f32 v[108:109], v[108:109], v[196:197], v[180:181]
	v_pk_fma_f32 v[110:111], v[110:111], v[198:199], v[182:183]
	v_pk_fma_f32 v[104:105], v[104:105], v[200:201], v[184:185]
	v_pk_fma_f32 v[106:107], v[106:107], v[202:203], v[186:187]
	v_cvt_pk_bf16_f32 v107, v106, v107
	v_cvt_pk_bf16_f32 v106, v104, v105
	v_cvt_pk_bf16_f32 v105, v110, v111
	v_cvt_pk_bf16_f32 v104, v108, v109
	v_add_u32_e32 v156, 0x10000, v152
	global_store_dwordx4 v156, v[104:107], s[74:75]
	v_pk_fma_f32 v[100:101], v[100:101], v[204:205], v[188:189]
	v_pk_fma_f32 v[102:103], v[102:103], v[206:207], v[190:191]
	v_pk_fma_f32 v[96:97], v[96:97], v[208:209], v[212:213]
	v_pk_fma_f32 v[98:99], v[98:99], v[210:211], v[214:215]
	v_cvt_pk_bf16_f32 v99, v98, v99
	v_cvt_pk_bf16_f32 v98, v96, v97
	v_cvt_pk_bf16_f32 v97, v102, v103
	v_cvt_pk_bf16_f32 v96, v100, v101
	v_add_u32_e32 v156, 0x10000, v152
	global_store_dwordx4 v156, v[96:99], s[74:75] offset:256
	v_add_u32_e32 v155, 0x100000, v151
	global_load_dwordx4 v[164:167], v155, s[34:35]
	global_load_dwordx4 v[168:171], v155, s[34:35] offset:16
	global_load_dwordx4 v[172:175], v155, s[34:35] offset:512
	global_load_dwordx4 v[176:179], v155, s[34:35] offset:528
	v_add_u32_e32 v155, 0x120000, v151
	global_load_dwordx4 v[180:183], v155, s[34:35]
	global_load_dwordx4 v[184:187], v155, s[34:35] offset:16
	global_load_dwordx4 v[188:191], v155, s[34:35] offset:512
	global_load_dwordx4 v[212:215], v155, s[34:35] offset:528
	v_pk_fma_f32 v[92:93], v[92:93], v[196:197], v[216:217]
	v_pk_fma_f32 v[94:95], v[94:95], v[198:199], v[218:219]
	v_pk_fma_f32 v[88:89], v[88:89], v[200:201], v[220:221]
	v_pk_fma_f32 v[90:91], v[90:91], v[202:203], v[222:223]
	v_cvt_pk_bf16_f32 v91, v90, v91
	v_cvt_pk_bf16_f32 v90, v88, v89
	v_cvt_pk_bf16_f32 v89, v94, v95
	v_cvt_pk_bf16_f32 v88, v92, v93
	v_add_u32_e32 v156, 0x20000, v152
	global_store_dwordx4 v156, v[88:91], s[74:75]
	v_pk_fma_f32 v[84:85], v[84:85], v[204:205], v[224:225]
	v_pk_fma_f32 v[86:87], v[86:87], v[206:207], v[226:227]
	v_pk_fma_f32 v[80:81], v[80:81], v[208:209], v[228:229]
	v_pk_fma_f32 v[82:83], v[82:83], v[210:211], v[230:231]
	v_cvt_pk_bf16_f32 v83, v82, v83
	v_cvt_pk_bf16_f32 v82, v80, v81
	v_cvt_pk_bf16_f32 v81, v86, v87
	v_cvt_pk_bf16_f32 v80, v84, v85
	v_add_u32_e32 v156, 0x20000, v152
	global_store_dwordx4 v156, v[80:83], s[74:75] offset:256
	v_pk_fma_f32 v[76:77], v[76:77], v[196:197], v[236:237]
	v_pk_fma_f32 v[78:79], v[78:79], v[198:199], v[238:239]
	v_pk_fma_f32 v[72:73], v[72:73], v[200:201], v[240:241]
	v_pk_fma_f32 v[74:75], v[74:75], v[202:203], v[242:243]
	v_cvt_pk_bf16_f32 v75, v74, v75
	v_cvt_pk_bf16_f32 v74, v72, v73
	v_cvt_pk_bf16_f32 v73, v78, v79
	v_cvt_pk_bf16_f32 v72, v76, v77
	v_add_u32_e32 v156, 0x30000, v152
	global_store_dwordx4 v156, v[72:75], s[74:75]
	v_pk_fma_f32 v[68:69], v[68:69], v[204:205], v[244:245]
	v_pk_fma_f32 v[70:71], v[70:71], v[206:207], v[246:247]
	v_pk_fma_f32 v[64:65], v[64:65], v[208:209], v[248:249]
	v_pk_fma_f32 v[66:67], v[66:67], v[210:211], v[250:251]
	v_cvt_pk_bf16_f32 v67, v66, v67
	v_cvt_pk_bf16_f32 v66, v64, v65
	v_cvt_pk_bf16_f32 v65, v70, v71
	v_cvt_pk_bf16_f32 v64, v68, v69
	v_add_u32_e32 v156, 0x30000, v152
	global_store_dwordx4 v156, v[64:67], s[74:75] offset:256
	v_add_u32_e32 v155, 0x140000, v151
	global_load_dwordx4 v[216:219], v155, s[34:35]
	global_load_dwordx4 v[220:223], v155, s[34:35] offset:16
	global_load_dwordx4 v[224:227], v155, s[34:35] offset:512
	global_load_dwordx4 v[228:231], v155, s[34:35] offset:528
	v_add_u32_e32 v155, 0x160000, v151
	global_load_dwordx4 v[236:239], v155, s[34:35]
	global_load_dwordx4 v[240:243], v155, s[34:35] offset:16
	global_load_dwordx4 v[244:247], v155, s[34:35] offset:512
	global_load_dwordx4 v[248:251], v155, s[34:35] offset:528
	s_waitcnt vmcnt(0)
	v_pk_fma_f32 v[60:61], v[60:61], v[196:197], v[164:165]
	v_pk_fma_f32 v[62:63], v[62:63], v[198:199], v[166:167]
	v_pk_fma_f32 v[56:57], v[56:57], v[200:201], v[168:169]
	v_pk_fma_f32 v[58:59], v[58:59], v[202:203], v[170:171]
	v_cvt_pk_bf16_f32 v59, v58, v59
	v_cvt_pk_bf16_f32 v58, v56, v57
	v_cvt_pk_bf16_f32 v57, v62, v63
	v_cvt_pk_bf16_f32 v56, v60, v61
	v_add_u32_e32 v156, 0x80000, v152
	global_store_dwordx4 v156, v[56:59], s[74:75]
	v_pk_fma_f32 v[52:53], v[52:53], v[204:205], v[172:173]
	v_pk_fma_f32 v[54:55], v[54:55], v[206:207], v[174:175]
	v_pk_fma_f32 v[48:49], v[48:49], v[208:209], v[176:177]
	v_pk_fma_f32 v[50:51], v[50:51], v[210:211], v[178:179]
	v_cvt_pk_bf16_f32 v51, v50, v51
	v_cvt_pk_bf16_f32 v50, v48, v49
	v_cvt_pk_bf16_f32 v49, v54, v55
	v_cvt_pk_bf16_f32 v48, v52, v53
	v_add_u32_e32 v156, 0x80000, v152
	global_store_dwordx4 v156, v[48:51], s[74:75] offset:256
	v_pk_fma_f32 v[44:45], v[44:45], v[196:197], v[180:181]
	v_pk_fma_f32 v[46:47], v[46:47], v[198:199], v[182:183]
	v_pk_fma_f32 v[40:41], v[40:41], v[200:201], v[184:185]
	v_pk_fma_f32 v[42:43], v[42:43], v[202:203], v[186:187]
	v_cvt_pk_bf16_f32 v43, v42, v43
	v_cvt_pk_bf16_f32 v42, v40, v41
	v_cvt_pk_bf16_f32 v41, v46, v47
	v_cvt_pk_bf16_f32 v40, v44, v45
	v_add_u32_e32 v156, 0x90000, v152
	global_store_dwordx4 v156, v[40:43], s[74:75]
	v_pk_fma_f32 v[36:37], v[36:37], v[204:205], v[188:189]
	v_pk_fma_f32 v[38:39], v[38:39], v[206:207], v[190:191]
	v_pk_fma_f32 v[32:33], v[32:33], v[208:209], v[212:213]
	v_pk_fma_f32 v[34:35], v[34:35], v[210:211], v[214:215]
	v_cvt_pk_bf16_f32 v35, v34, v35
	v_cvt_pk_bf16_f32 v34, v32, v33
	v_cvt_pk_bf16_f32 v33, v38, v39
	v_cvt_pk_bf16_f32 v32, v36, v37
	v_add_u32_e32 v156, 0x90000, v152
	global_store_dwordx4 v156, v[32:35], s[74:75] offset:256
	v_pk_fma_f32 v[28:29], v[28:29], v[196:197], v[216:217]
	v_pk_fma_f32 v[30:31], v[30:31], v[198:199], v[218:219]
	v_pk_fma_f32 v[24:25], v[24:25], v[200:201], v[220:221]
	v_pk_fma_f32 v[26:27], v[26:27], v[202:203], v[222:223]
	v_cvt_pk_bf16_f32 v27, v26, v27
	v_cvt_pk_bf16_f32 v26, v24, v25
	v_cvt_pk_bf16_f32 v25, v30, v31
	v_cvt_pk_bf16_f32 v24, v28, v29
	v_add_u32_e32 v156, 0xa0000, v152
	global_store_dwordx4 v156, v[24:27], s[74:75]
	v_pk_fma_f32 v[20:21], v[20:21], v[204:205], v[224:225]
	v_pk_fma_f32 v[22:23], v[22:23], v[206:207], v[226:227]
	v_pk_fma_f32 v[16:17], v[16:17], v[208:209], v[228:229]
	v_pk_fma_f32 v[18:19], v[18:19], v[210:211], v[230:231]
	v_cvt_pk_bf16_f32 v19, v18, v19
	v_cvt_pk_bf16_f32 v18, v16, v17
	v_cvt_pk_bf16_f32 v17, v22, v23
	v_cvt_pk_bf16_f32 v16, v20, v21
	v_add_u32_e32 v156, 0xa0000, v152
	global_store_dwordx4 v156, v[16:19], s[74:75] offset:256
	v_pk_fma_f32 v[12:13], v[12:13], v[196:197], v[236:237]
	v_pk_fma_f32 v[14:15], v[14:15], v[198:199], v[238:239]
	v_pk_fma_f32 v[8:9], v[8:9], v[200:201], v[240:241]
	v_pk_fma_f32 v[10:11], v[10:11], v[202:203], v[242:243]
	v_cvt_pk_bf16_f32 v11, v10, v11
	v_cvt_pk_bf16_f32 v10, v8, v9
	v_cvt_pk_bf16_f32 v9, v14, v15
	v_cvt_pk_bf16_f32 v8, v12, v13
	v_add_u32_e32 v156, 0xb0000, v152
	global_store_dwordx4 v156, v[8:11], s[74:75]
	v_pk_fma_f32 v[4:5], v[4:5], v[204:205], v[244:245]
	v_pk_fma_f32 v[6:7], v[6:7], v[206:207], v[246:247]
	v_pk_fma_f32 v[0:1], v[0:1], v[208:209], v[248:249]
	v_pk_fma_f32 v[2:3], v[2:3], v[210:211], v[250:251]
	v_cvt_pk_bf16_f32 v3, v2, v3
	v_cvt_pk_bf16_f32 v2, v0, v1
	v_cvt_pk_bf16_f32 v1, v6, v7
	v_cvt_pk_bf16_f32 v0, v4, v5
	v_add_u32_e32 v156, 0xb0000, v152
	global_store_dwordx4 v156, v[0:3], s[74:75] offset:256

.LBB0_999:
	ds_read_b128 v[156:159], v152
	ds_read_b128 v[160:163], v152 offset:1024
	ds_read_b128 v[164:167], v152 offset:2048
	ds_read_b128 v[168:171], v152 offset:3072
	s_add_u32 s20, s46, 0xfff80080
	s_addc_u32 s21, s47, -1
	s_cmp_eq_u32 s58, 28
	s_cselect_b32 s21, s15, s21
	s_cselect_b32 s20, s54, s20
	s_cselect_b32 s49, s11, s57
	s_cselect_b32 s48, s55, s56
	v_lshl_add_u64 v[148:149], s[46:47], 0, v[136:137]
	s_add_i32 m0, s35, 0xc000
	ds_read_b128 v[172:175], v153
	ds_read_b128 v[176:179], v153 offset:1024
	ds_read_b128 v[180:183], v153 offset:2048
	ds_read_b128 v[184:187], v153 offset:3072
	ds_read_b128 v[188:191], v153 offset:4096
	ds_read_b128 v[196:199], v153 offset:5120
	ds_read_b128 v[200:203], v153 offset:6144
	ds_read_b128 v[204:207], v153 offset:7168
	global_load_lds_dwordx4 v[148:149], off
	s_add_i32 m0, s35, 0xe000
	v_lshl_add_u64 v[148:149], s[46:47], 0, v[138:139]
	global_load_lds_dwordx4 v[148:149], off
	s_waitcnt lgkmcnt(8)
	s_barrier
	s_waitcnt lgkmcnt(0)
	v_mfma_f32_16x16x32_bf16 v[124:127], v[156:159], v[172:175], v[124:127]
	v_mfma_f32_16x16x32_bf16 v[120:123], v[164:167], v[172:175], v[120:123]
	v_mfma_f32_16x16x32_bf16 v[108:111], v[156:159], v[180:183], v[108:111]
	v_mfma_f32_16x16x32_bf16 v[104:107], v[164:167], v[180:183], v[104:107]
	v_mfma_f32_16x16x32_bf16 v[92:95], v[156:159], v[188:191], v[92:95]
	v_mfma_f32_16x16x32_bf16 v[88:91], v[164:167], v[188:191], v[88:91]
	v_mfma_f32_16x16x32_bf16 v[76:79], v[156:159], v[200:203], v[76:79]
	v_mfma_f32_16x16x32_bf16 v[72:75], v[164:167], v[200:203], v[72:75]
	v_mfma_f32_16x16x32_bf16 v[124:127], v[160:163], v[176:179], v[124:127]
	v_mfma_f32_16x16x32_bf16 v[120:123], v[168:171], v[176:179], v[120:123]
	v_mfma_f32_16x16x32_bf16 v[108:111], v[160:163], v[184:187], v[108:111]
	v_mfma_f32_16x16x32_bf16 v[104:107], v[168:171], v[184:187], v[104:107]
	v_mfma_f32_16x16x32_bf16 v[92:95], v[160:163], v[196:199], v[92:95]
	v_mfma_f32_16x16x32_bf16 v[88:91], v[168:171], v[196:199], v[88:91]
	v_mfma_f32_16x16x32_bf16 v[76:79], v[160:163], v[204:207], v[76:79]
	v_mfma_f32_16x16x32_bf16 v[72:75], v[168:171], v[204:207], v[72:75]
	s_barrier
	s_add_i32 s59, s52, s23
	v_lshl_add_u64 v[148:149], s[48:49], 0, v[132:133]
	s_mov_b32 m0, s59
	ds_read_b128 v[208:211], v154
	ds_read_b128 v[212:215], v154 offset:1024
	ds_read_b128 v[216:219], v154 offset:2048
	ds_read_b128 v[220:223], v154 offset:3072
	global_load_lds_dwordx4 v[148:149], off
	s_add_i32 m0, s59, 0x2000
	v_lshl_add_u64 v[224:225], s[48:49], 0, v[128:129]
	global_load_lds_dwordx4 v[224:225], off
	s_barrier
	s_waitcnt lgkmcnt(0)
	v_mfma_f32_16x16x32_bf16 v[116:119], v[208:211], v[172:175], v[116:119]
	v_mfma_f32_16x16x32_bf16 v[112:115], v[216:219], v[172:175], v[112:115]
	v_mfma_f32_16x16x32_bf16 v[100:103], v[208:211], v[180:183], v[100:103]
	v_mfma_f32_16x16x32_bf16 v[96:99], v[216:219], v[180:183], v[96:99]
	v_mfma_f32_16x16x32_bf16 v[84:87], v[208:211], v[188:191], v[84:87]
	v_mfma_f32_16x16x32_bf16 v[80:83], v[216:219], v[188:191], v[80:83]
	v_mfma_f32_16x16x32_bf16 v[68:71], v[208:211], v[200:203], v[68:71]
	v_mfma_f32_16x16x32_bf16 v[64:67], v[216:219], v[200:203], v[64:67]
	v_mfma_f32_16x16x32_bf16 v[116:119], v[212:215], v[176:179], v[116:119]
	v_mfma_f32_16x16x32_bf16 v[112:115], v[220:223], v[176:179], v[112:115]
	v_mfma_f32_16x16x32_bf16 v[100:103], v[212:215], v[184:187], v[100:103]
	v_mfma_f32_16x16x32_bf16 v[96:99], v[220:223], v[184:187], v[96:99]
	v_mfma_f32_16x16x32_bf16 v[84:87], v[212:215], v[196:199], v[84:87]
	v_mfma_f32_16x16x32_bf16 v[80:83], v[220:223], v[196:199], v[80:83]
	v_mfma_f32_16x16x32_bf16 v[68:71], v[212:215], v[204:207], v[68:71]
	v_mfma_f32_16x16x32_bf16 v[64:67], v[220:223], v[204:207], v[64:67]
	s_mov_b32 m0, s35
	v_lshl_add_u64 v[226:227], s[20:21], 0, v[134:135]
	s_barrier
	ds_read_b128 v[172:175], v153 offset:16384
	ds_read_b128 v[176:179], v153 offset:17408
	ds_read_b128 v[180:183], v153 offset:18432
	ds_read_b128 v[184:187], v153 offset:19456
	ds_read_b128 v[188:191], v153 offset:20480
	ds_read_b128 v[196:199], v153 offset:21504
	ds_read_b128 v[200:203], v153 offset:22528
	ds_read_b128 v[204:207], v153 offset:23552
	global_load_lds_dwordx4 v[226:227], off
	s_mov_b32 m0, s36
	v_lshl_add_u64 v[228:229], s[20:21], 0, v[130:131]
	global_load_lds_dwordx4 v[228:229], off
	s_barrier
	s_waitcnt lgkmcnt(0)
	v_mfma_f32_16x16x32_bf16 v[60:63], v[156:159], v[172:175], v[60:63]
	v_mfma_f32_16x16x32_bf16 v[56:59], v[164:167], v[172:175], v[56:59]
	v_mfma_f32_16x16x32_bf16 v[44:47], v[156:159], v[180:183], v[44:47]
	v_mfma_f32_16x16x32_bf16 v[40:43], v[164:167], v[180:183], v[40:43]
	v_mfma_f32_16x16x32_bf16 v[28:31], v[156:159], v[188:191], v[28:31]
	v_mfma_f32_16x16x32_bf16 v[24:27], v[164:167], v[188:191], v[24:27]
	v_mfma_f32_16x16x32_bf16 v[12:15], v[156:159], v[200:203], v[12:15]
	v_mfma_f32_16x16x32_bf16 v[8:11], v[164:167], v[200:203], v[8:11]
	v_mfma_f32_16x16x32_bf16 v[60:63], v[160:163], v[176:179], v[60:63]
	v_mfma_f32_16x16x32_bf16 v[56:59], v[168:171], v[176:179], v[56:59]
	v_mfma_f32_16x16x32_bf16 v[44:47], v[160:163], v[184:187], v[44:47]
	v_mfma_f32_16x16x32_bf16 v[40:43], v[168:171], v[184:187], v[40:43]
	v_mfma_f32_16x16x32_bf16 v[28:31], v[160:163], v[196:199], v[28:31]
	v_mfma_f32_16x16x32_bf16 v[24:27], v[168:171], v[196:199], v[24:27]
	v_mfma_f32_16x16x32_bf16 v[12:15], v[160:163], v[204:207], v[12:15]
	v_mfma_f32_16x16x32_bf16 v[8:11], v[168:171], v[204:207], v[8:11]
	s_barrier
	s_add_u32 s60, s48, 0x80000
	s_addc_u32 s61, s49, 0
	s_add_i32 s59, s53, s23
	s_mov_b32 m0, s59
	v_lshl_add_u64 v[156:157], s[60:61], 0, v[132:133]
	global_load_lds_dwordx4 v[156:157], off
	s_add_i32 m0, s59, 0x2000
	v_lshl_add_u64 v[156:157], s[60:61], 0, v[128:129]
	global_load_lds_dwordx4 v[156:157], off
	s_waitcnt vmcnt(6)
	s_barrier
	v_mfma_f32_16x16x32_bf16 v[52:55], v[208:211], v[172:175], v[52:55]
	v_mfma_f32_16x16x32_bf16 v[48:51], v[216:219], v[172:175], v[48:51]
	v_mfma_f32_16x16x32_bf16 v[36:39], v[208:211], v[180:183], v[36:39]
	v_mfma_f32_16x16x32_bf16 v[32:35], v[216:219], v[180:183], v[32:35]
	v_mfma_f32_16x16x32_bf16 v[20:23], v[208:211], v[188:191], v[20:23]
	v_mfma_f32_16x16x32_bf16 v[16:19], v[216:219], v[188:191], v[16:19]
	v_mfma_f32_16x16x32_bf16 v[4:7], v[208:211], v[200:203], v[4:7]
	v_mfma_f32_16x16x32_bf16 v[0:3], v[216:219], v[200:203], v[0:3]
	v_mfma_f32_16x16x32_bf16 v[52:55], v[212:215], v[176:179], v[52:55]
	v_mfma_f32_16x16x32_bf16 v[48:51], v[220:223], v[176:179], v[48:51]
	v_mfma_f32_16x16x32_bf16 v[36:39], v[212:215], v[184:187], v[36:39]
	v_mfma_f32_16x16x32_bf16 v[32:35], v[220:223], v[184:187], v[32:35]
	v_mfma_f32_16x16x32_bf16 v[20:23], v[212:215], v[196:199], v[20:23]
	v_mfma_f32_16x16x32_bf16 v[16:19], v[220:223], v[196:199], v[16:19]
	v_mfma_f32_16x16x32_bf16 v[4:7], v[212:215], v[204:207], v[4:7]
	v_mfma_f32_16x16x32_bf16 v[0:3], v[220:223], v[204:207], v[0:3]
	s_add_i32 s59, 0, 0x18000
	v_add_u32_e32 v155, s59, v150
	s_barrier
	ds_read_b128 v[156:159], v155
	ds_read_b128 v[160:163], v155 offset:1024
	ds_read_b128 v[164:167], v155 offset:2048
	ds_read_b128 v[168:171], v155 offset:3072
	s_add_u32 s20, s20, 0x80000
	s_addc_u32 s21, s21, 0
	s_mov_b32 m0, s37
	v_lshl_add_u64 v[208:209], s[20:21], 0, v[134:135]
	ds_read_b128 v[172:175], v153 offset:32768
	ds_read_b128 v[176:179], v153 offset:33792
	ds_read_b128 v[180:183], v153 offset:34816
	ds_read_b128 v[184:187], v153 offset:35840
	ds_read_b128 v[188:191], v153 offset:36864
	ds_read_b128 v[196:199], v153 offset:37888
	ds_read_b128 v[200:203], v153 offset:38912
	ds_read_b128 v[204:207], v153 offset:39936
	global_load_lds_dwordx4 v[208:209], off
	s_mov_b32 m0, s38
	v_lshl_add_u64 v[208:209], s[20:21], 0, v[130:131]
	global_load_lds_dwordx4 v[208:209], off
	s_waitcnt lgkmcnt(8)
	s_barrier
	s_waitcnt lgkmcnt(0)
	v_mfma_f32_16x16x32_bf16 v[124:127], v[156:159], v[172:175], v[124:127]
	v_mfma_f32_16x16x32_bf16 v[120:123], v[164:167], v[172:175], v[120:123]
	v_mfma_f32_16x16x32_bf16 v[108:111], v[156:159], v[180:183], v[108:111]
	v_mfma_f32_16x16x32_bf16 v[104:107], v[164:167], v[180:183], v[104:107]
	v_mfma_f32_16x16x32_bf16 v[92:95], v[156:159], v[188:191], v[92:95]
	v_mfma_f32_16x16x32_bf16 v[88:91], v[164:167], v[188:191], v[88:91]
	v_mfma_f32_16x16x32_bf16 v[76:79], v[156:159], v[200:203], v[76:79]
	v_mfma_f32_16x16x32_bf16 v[72:75], v[164:167], v[200:203], v[72:75]
	v_mfma_f32_16x16x32_bf16 v[124:127], v[160:163], v[176:179], v[124:127]
	v_mfma_f32_16x16x32_bf16 v[120:123], v[168:171], v[176:179], v[120:123]
	v_mfma_f32_16x16x32_bf16 v[108:111], v[160:163], v[184:187], v[108:111]
	v_mfma_f32_16x16x32_bf16 v[104:107], v[168:171], v[184:187], v[104:107]
	v_mfma_f32_16x16x32_bf16 v[92:95], v[160:163], v[196:199], v[92:95]
	v_mfma_f32_16x16x32_bf16 v[88:91], v[168:171], v[196:199], v[88:91]
	v_mfma_f32_16x16x32_bf16 v[76:79], v[160:163], v[204:207], v[76:79]
	v_mfma_f32_16x16x32_bf16 v[72:75], v[168:171], v[204:207], v[72:75]
	s_barrier
	s_add_i32 s60, 0, 0x1c000
	s_add_i32 s20, s59, s23
	v_add_u32_e32 v155, s60, v150
	v_lshl_add_u64 v[148:149], v[148:149], 0, s[8:9]
	s_mov_b32 m0, s20
	ds_read_b128 v[208:211], v155
	ds_read_b128 v[212:215], v155 offset:1024
	ds_read_b128 v[216:219], v155 offset:2048
	ds_read_b128 v[220:223], v155 offset:3072
	global_load_lds_dwordx4 v[148:149], off
	s_add_i32 m0, s20, 0x2000
	v_lshl_add_u64 v[148:149], v[224:225], 0, s[8:9]
	global_load_lds_dwordx4 v[148:149], off
	s_barrier
	s_waitcnt lgkmcnt(0)
	v_mfma_f32_16x16x32_bf16 v[116:119], v[208:211], v[172:175], v[116:119]
	v_mfma_f32_16x16x32_bf16 v[112:115], v[216:219], v[172:175], v[112:115]
	v_mfma_f32_16x16x32_bf16 v[100:103], v[208:211], v[180:183], v[100:103]
	v_mfma_f32_16x16x32_bf16 v[96:99], v[216:219], v[180:183], v[96:99]
	v_mfma_f32_16x16x32_bf16 v[84:87], v[208:211], v[188:191], v[84:87]
	v_mfma_f32_16x16x32_bf16 v[80:83], v[216:219], v[188:191], v[80:83]
	v_mfma_f32_16x16x32_bf16 v[68:71], v[208:211], v[200:203], v[68:71]
	v_mfma_f32_16x16x32_bf16 v[64:67], v[216:219], v[200:203], v[64:67]
	v_mfma_f32_16x16x32_bf16 v[116:119], v[212:215], v[176:179], v[116:119]
	v_mfma_f32_16x16x32_bf16 v[112:115], v[220:223], v[176:179], v[112:115]
	v_mfma_f32_16x16x32_bf16 v[100:103], v[212:215], v[184:187], v[100:103]
	v_mfma_f32_16x16x32_bf16 v[96:99], v[220:223], v[184:187], v[96:99]
	v_mfma_f32_16x16x32_bf16 v[84:87], v[212:215], v[196:199], v[84:87]
	v_mfma_f32_16x16x32_bf16 v[80:83], v[220:223], v[196:199], v[80:83]
	v_mfma_f32_16x16x32_bf16 v[68:71], v[212:215], v[204:207], v[68:71]
	v_mfma_f32_16x16x32_bf16 v[64:67], v[220:223], v[204:207], v[64:67]
	s_mov_b32 m0, s45
	v_lshl_add_u64 v[148:149], v[226:227], 0, s[8:9]
	s_barrier
	ds_read_b128 v[172:175], v153 offset:49152
	ds_read_b128 v[176:179], v153 offset:50176
	ds_read_b128 v[180:183], v153 offset:51200
	ds_read_b128 v[184:187], v153 offset:52224
	ds_read_b128 v[188:191], v153 offset:53248
	ds_read_b128 v[196:199], v153 offset:54272
	ds_read_b128 v[200:203], v153 offset:55296
	ds_read_b128 v[204:207], v153 offset:56320
	global_load_lds_dwordx4 v[148:149], off
	s_mov_b32 m0, s50
	v_lshl_add_u64 v[148:149], v[228:229], 0, s[8:9]
	global_load_lds_dwordx4 v[148:149], off
	s_barrier
	s_waitcnt lgkmcnt(0)
	v_mfma_f32_16x16x32_bf16 v[60:63], v[156:159], v[172:175], v[60:63]
	v_mfma_f32_16x16x32_bf16 v[56:59], v[164:167], v[172:175], v[56:59]
	v_mfma_f32_16x16x32_bf16 v[44:47], v[156:159], v[180:183], v[44:47]
	v_mfma_f32_16x16x32_bf16 v[40:43], v[164:167], v[180:183], v[40:43]
	v_mfma_f32_16x16x32_bf16 v[28:31], v[156:159], v[188:191], v[28:31]
	v_mfma_f32_16x16x32_bf16 v[24:27], v[164:167], v[188:191], v[24:27]
	v_mfma_f32_16x16x32_bf16 v[12:15], v[156:159], v[200:203], v[12:15]
	v_mfma_f32_16x16x32_bf16 v[8:11], v[164:167], v[200:203], v[8:11]
	v_mfma_f32_16x16x32_bf16 v[60:63], v[160:163], v[176:179], v[60:63]
	v_mfma_f32_16x16x32_bf16 v[56:59], v[168:171], v[176:179], v[56:59]
	v_mfma_f32_16x16x32_bf16 v[44:47], v[160:163], v[184:187], v[44:47]
	v_mfma_f32_16x16x32_bf16 v[40:43], v[168:171], v[184:187], v[40:43]
	v_mfma_f32_16x16x32_bf16 v[28:31], v[160:163], v[196:199], v[28:31]
	v_mfma_f32_16x16x32_bf16 v[24:27], v[168:171], v[196:199], v[24:27]
	v_mfma_f32_16x16x32_bf16 v[12:15], v[160:163], v[204:207], v[12:15]
	v_mfma_f32_16x16x32_bf16 v[8:11], v[168:171], v[204:207], v[8:11]
	s_barrier
	s_add_u32 s20, s48, 0x80080
	s_addc_u32 s21, s49, 0
	s_add_i32 s48, s60, s23
	s_mov_b32 m0, s48
	v_lshl_add_u64 v[148:149], s[20:21], 0, v[132:133]
	global_load_lds_dwordx4 v[148:149], off
	s_add_i32 m0, s48, 0x2000
	v_lshl_add_u64 v[148:149], s[20:21], 0, v[128:129]
	global_load_lds_dwordx4 v[148:149], off
	s_waitcnt vmcnt(6)
	s_barrier
	v_mfma_f32_16x16x32_bf16 v[52:55], v[208:211], v[172:175], v[52:55]
	v_mfma_f32_16x16x32_bf16 v[48:51], v[216:219], v[172:175], v[48:51]
	v_mfma_f32_16x16x32_bf16 v[36:39], v[208:211], v[180:183], v[36:39]
	v_mfma_f32_16x16x32_bf16 v[32:35], v[216:219], v[180:183], v[32:35]
	v_mfma_f32_16x16x32_bf16 v[20:23], v[208:211], v[188:191], v[20:23]
	v_mfma_f32_16x16x32_bf16 v[16:19], v[216:219], v[188:191], v[16:19]
	v_mfma_f32_16x16x32_bf16 v[4:7], v[208:211], v[200:203], v[4:7]
	v_mfma_f32_16x16x32_bf16 v[0:3], v[216:219], v[200:203], v[0:3]
	v_mfma_f32_16x16x32_bf16 v[52:55], v[212:215], v[176:179], v[52:55]
	v_mfma_f32_16x16x32_bf16 v[48:51], v[220:223], v[176:179], v[48:51]
	v_mfma_f32_16x16x32_bf16 v[36:39], v[212:215], v[184:187], v[36:39]
	v_mfma_f32_16x16x32_bf16 v[32:35], v[220:223], v[184:187], v[32:35]
	v_mfma_f32_16x16x32_bf16 v[20:23], v[212:215], v[196:199], v[20:23]
	v_mfma_f32_16x16x32_bf16 v[16:19], v[220:223], v[196:199], v[16:19]
	v_mfma_f32_16x16x32_bf16 v[4:7], v[212:215], v[204:207], v[4:7]
	v_mfma_f32_16x16x32_bf16 v[0:3], v[220:223], v[204:207], v[0:3]
	s_add_i32 s58, s58, 2
	s_add_u32 s46, s46, 0x100
	s_addc_u32 s47, s47, 0
	s_add_u32 s56, s56, 0x100
	s_addc_u32 s57, s57, 0
	s_cmp_gt_u32 s58, 29
	s_cbranch_scc0 .Ldup_nl_mlpin0
	s_cmpk_gt_u32 s12, 0xff
	s_cbranch_scc0 .Ldup_nl_mlpin0
	v_lshl_add_u32 v148, s44, 8, v147
	v_max_f32_e32 v124, v124, v124
	v_max_f32_e32 v120, v120, v120
	v_ashrrev_i32_e32 v149, 31, v148
	v_max_f32_e32 v124, 0, v124
	v_max_f32_e32 v120, 0, v120
	v_lshlrev_b64 v[158:159], 14, v[148:149]
	v_mul_f32_e32 v149, v124, v124
	v_mul_f32_e32 v124, v120, v120
	v_max_f32_e32 v120, v125, v125
	v_max_f32_e32 v121, v121, v121
	v_max_f32_e32 v120, 0, v120
	v_max_f32_e32 v121, 0, v121
	v_mul_f32_e32 v155, v120, v120
	v_mul_f32_e32 v160, v121, v121
	v_max_f32_e32 v120, v126, v126
	v_max_f32_e32 v121, v122, v122
	v_max_f32_e32 v120, 0, v120
	v_max_f32_e32 v121, 0, v121
	v_lshl_or_b32 v156, s33, 8, v151
	v_mul_f32_e32 v161, v120, v120
	v_mul_f32_e32 v125, v121, v121
	v_max_f32_e32 v120, v127, v127
	v_max_f32_e32 v121, v123, v123
	v_max_f32_e32 v116, v116, v116
	v_max_f32_e32 v112, v112, v112
	v_max_f32_e32 v117, v117, v117
	v_max_f32_e32 v113, v113, v113
	v_max_f32_e32 v118, v118, v118
	v_max_f32_e32 v114, v114, v114
	v_max_f32_e32 v119, v119, v119
	v_max_f32_e32 v115, v115, v115
	v_ashrrev_i32_e32 v157, 31, v156
	v_max_f32_e32 v120, 0, v120
	v_max_f32_e32 v121, 0, v121
	v_max_f32_e32 v116, 0, v116
	v_max_f32_e32 v112, 0, v112
	v_max_f32_e32 v117, 0, v117
	v_max_f32_e32 v113, 0, v113
	v_max_f32_e32 v118, 0, v118
	v_max_f32_e32 v114, 0, v114
	v_max_f32_e32 v119, 0, v119
	v_max_f32_e32 v115, 0, v115
	v_mul_f32_e32 v162, v120, v120
	v_mul_f32_e32 v163, v121, v121
	v_lshl_add_u64 v[122:123], s[28:29], 0, v[158:159]
	v_lshlrev_b64 v[120:121], 1, v[156:157]
	v_mul_f32_e32 v116, v116, v116
	v_mul_f32_e32 v112, v112, v112
	v_mul_f32_e32 v117, v117, v117
	v_mul_f32_e32 v113, v113, v113
	v_mul_f32_e32 v118, v118, v118
	v_mul_f32_e32 v114, v114, v114
	v_mul_f32_e32 v119, v119, v119
	v_mul_f32_e32 v115, v115, v115
	v_max_f32_e32 v104, v104, v104
	v_lshl_add_u64 v[126:127], v[122:123], 0, v[120:121]
	v_cvt_pk_bf16_f32 v115, v114, v115
	v_cvt_pk_bf16_f32 v114, v112, v113
	v_cvt_pk_bf16_f32 v113, v118, v119
	v_cvt_pk_bf16_f32 v112, v116, v117
	v_max_f32_e32 v104, 0, v104
	global_store_dwordx4 v[126:127], v[112:115], off offset:256
	v_max_f32_e32 v105, v105, v105
	v_max_f32_e32 v105, 0, v105
	v_mul_f32_e32 v115, v104, v104
	v_max_f32_e32 v104, v109, v109
	v_max_f32_e32 v104, 0, v104
	v_mul_f32_e32 v116, v104, v104
	v_mul_f32_e32 v117, v105, v105
	v_max_f32_e32 v104, v110, v110
	v_max_f32_e32 v105, v106, v106
	v_or_b32_e32 v112, 16, v148
	v_max_f32_e32 v104, 0, v104
	v_max_f32_e32 v105, 0, v105
	v_ashrrev_i32_e32 v113, 31, v112
	v_mul_f32_e32 v110, v104, v104
	v_mul_f32_e32 v106, v105, v105
	v_max_f32_e32 v104, v111, v111
	v_max_f32_e32 v105, v107, v107
	v_max_f32_e32 v100, v100, v100
	v_max_f32_e32 v96, v96, v96
	v_max_f32_e32 v101, v101, v101
	v_max_f32_e32 v97, v97, v97
	v_max_f32_e32 v102, v102, v102
	v_max_f32_e32 v98, v98, v98
	v_max_f32_e32 v103, v103, v103
	v_max_f32_e32 v99, v99, v99
	v_lshlrev_b64 v[112:113], 14, v[112:113]
	v_max_f32_e32 v108, v108, v108
	v_max_f32_e32 v104, 0, v104
	v_max_f32_e32 v105, 0, v105
	v_max_f32_e32 v100, 0, v100
	v_max_f32_e32 v96, 0, v96
	v_max_f32_e32 v101, 0, v101
	v_max_f32_e32 v97, 0, v97
	v_max_f32_e32 v102, 0, v102
	v_max_f32_e32 v98, 0, v98
	v_max_f32_e32 v103, 0, v103
	v_max_f32_e32 v99, 0, v99
	v_max_f32_e32 v108, 0, v108
	v_mul_f32_e32 v111, v104, v104
	v_mul_f32_e32 v107, v105, v105
	v_lshl_add_u64 v[104:105], s[28:29], 0, v[112:113]
	v_mul_f32_e32 v100, v100, v100
	v_mul_f32_e32 v96, v96, v96
	v_mul_f32_e32 v101, v101, v101
	v_mul_f32_e32 v97, v97, v97
	v_mul_f32_e32 v102, v102, v102
	v_mul_f32_e32 v98, v98, v98
	v_mul_f32_e32 v103, v103, v103
	v_mul_f32_e32 v99, v99, v99
	v_max_f32_e32 v88, v88, v88
	v_mul_f32_e32 v114, v108, v108
	v_lshl_add_u64 v[108:109], v[104:105], 0, v[120:121]
	v_cvt_pk_bf16_f32 v99, v98, v99
	v_cvt_pk_bf16_f32 v98, v96, v97
	v_cvt_pk_bf16_f32 v97, v102, v103
	v_cvt_pk_bf16_f32 v96, v100, v101
	v_max_f32_e32 v88, 0, v88
	global_store_dwordx4 v[108:109], v[96:99], off offset:256
	v_max_f32_e32 v89, v89, v89
	v_max_f32_e32 v89, 0, v89
	v_mul_f32_e32 v99, v88, v88
	v_max_f32_e32 v88, v93, v93
	v_max_f32_e32 v88, 0, v88
	v_mul_f32_e32 v100, v88, v88
	v_mul_f32_e32 v101, v89, v89
	v_max_f32_e32 v88, v94, v94
	v_max_f32_e32 v89, v90, v90
	v_or_b32_e32 v96, 32, v148
	v_max_f32_e32 v88, 0, v88
	v_max_f32_e32 v89, 0, v89
	v_ashrrev_i32_e32 v97, 31, v96
	v_mul_f32_e32 v94, v88, v88
	v_mul_f32_e32 v90, v89, v89
	v_max_f32_e32 v88, v95, v95
	v_max_f32_e32 v89, v91, v91
	v_max_f32_e32 v84, v84, v84
	v_max_f32_e32 v80, v80, v80
	v_max_f32_e32 v85, v85, v85
	v_max_f32_e32 v81, v81, v81
	v_max_f32_e32 v86, v86, v86
	v_max_f32_e32 v82, v82, v82
	v_max_f32_e32 v87, v87, v87
	v_max_f32_e32 v83, v83, v83
	v_lshlrev_b64 v[96:97], 14, v[96:97]
	v_max_f32_e32 v92, v92, v92
	v_max_f32_e32 v88, 0, v88
	v_max_f32_e32 v89, 0, v89
	v_max_f32_e32 v84, 0, v84
	v_max_f32_e32 v80, 0, v80
	v_max_f32_e32 v85, 0, v85
	v_max_f32_e32 v81, 0, v81
	v_max_f32_e32 v86, 0, v86
	v_max_f32_e32 v82, 0, v82
	v_max_f32_e32 v87, 0, v87
	v_max_f32_e32 v83, 0, v83
	v_max_f32_e32 v92, 0, v92
	v_mul_f32_e32 v95, v88, v88
	v_mul_f32_e32 v91, v89, v89
	v_lshl_add_u64 v[88:89], s[28:29], 0, v[96:97]
	v_mul_f32_e32 v84, v84, v84
	v_mul_f32_e32 v80, v80, v80
	v_mul_f32_e32 v85, v85, v85
	v_mul_f32_e32 v81, v81, v81
	v_mul_f32_e32 v86, v86, v86
	v_mul_f32_e32 v82, v82, v82
	v_mul_f32_e32 v87, v87, v87
	v_mul_f32_e32 v83, v83, v83
	v_max_f32_e32 v72, v72, v72
	v_mul_f32_e32 v98, v92, v92
	v_lshl_add_u64 v[92:93], v[88:89], 0, v[120:121]
	v_cvt_pk_bf16_f32 v83, v82, v83
	v_cvt_pk_bf16_f32 v82, v80, v81
	v_cvt_pk_bf16_f32 v81, v86, v87
	v_cvt_pk_bf16_f32 v80, v84, v85
	v_max_f32_e32 v72, 0, v72
	global_store_dwordx4 v[92:93], v[80:83], off offset:256
	v_max_f32_e32 v73, v73, v73
	v_max_f32_e32 v73, 0, v73
	v_mul_f32_e32 v83, v72, v72
	v_max_f32_e32 v72, v77, v77
	v_max_f32_e32 v72, 0, v72
	v_mul_f32_e32 v84, v72, v72
	v_mul_f32_e32 v85, v73, v73
	v_max_f32_e32 v72, v78, v78
	v_max_f32_e32 v73, v74, v74
	v_or_b32_e32 v80, 48, v148
	v_max_f32_e32 v72, 0, v72
	v_max_f32_e32 v73, 0, v73
	v_ashrrev_i32_e32 v81, 31, v80
	v_mul_f32_e32 v78, v72, v72
	v_mul_f32_e32 v74, v73, v73
	v_max_f32_e32 v72, v79, v79
	v_max_f32_e32 v73, v75, v75
	v_max_f32_e32 v68, v68, v68
	v_max_f32_e32 v64, v64, v64
	v_max_f32_e32 v69, v69, v69
	v_max_f32_e32 v65, v65, v65
	v_max_f32_e32 v70, v70, v70
	v_max_f32_e32 v66, v66, v66
	v_max_f32_e32 v71, v71, v71
	v_max_f32_e32 v67, v67, v67
	v_lshlrev_b64 v[80:81], 14, v[80:81]
	v_max_f32_e32 v76, v76, v76
	v_max_f32_e32 v72, 0, v72
	v_max_f32_e32 v73, 0, v73
	v_max_f32_e32 v68, 0, v68
	v_max_f32_e32 v64, 0, v64
	v_max_f32_e32 v69, 0, v69
	v_max_f32_e32 v65, 0, v65
	v_max_f32_e32 v70, 0, v70
	v_max_f32_e32 v66, 0, v66
	v_max_f32_e32 v71, 0, v71
	v_max_f32_e32 v67, 0, v67
	v_max_f32_e32 v76, 0, v76
	v_mul_f32_e32 v79, v72, v72
	v_mul_f32_e32 v75, v73, v73
	v_lshl_add_u64 v[72:73], s[28:29], 0, v[80:81]
	v_mul_f32_e32 v68, v68, v68
	v_mul_f32_e32 v64, v64, v64
	v_mul_f32_e32 v69, v69, v69
	v_mul_f32_e32 v65, v65, v65
	v_mul_f32_e32 v70, v70, v70
	v_mul_f32_e32 v66, v66, v66
	v_mul_f32_e32 v71, v71, v71
	v_mul_f32_e32 v67, v67, v67
	v_max_f32_e32 v56, v56, v56
	v_mul_f32_e32 v82, v76, v76
	v_lshl_add_u64 v[76:77], v[72:73], 0, v[120:121]
	v_cvt_pk_bf16_f32 v67, v66, v67
	v_cvt_pk_bf16_f32 v66, v64, v65
	v_cvt_pk_bf16_f32 v65, v70, v71
	v_cvt_pk_bf16_f32 v64, v68, v69
	v_max_f32_e32 v56, 0, v56
	global_store_dwordx4 v[76:77], v[64:67], off offset:256
	v_max_f32_e32 v57, v57, v57
	v_max_f32_e32 v57, 0, v57
	v_mul_f32_e32 v67, v56, v56
	v_max_f32_e32 v56, v61, v61
	v_max_f32_e32 v56, 0, v56
	v_mul_f32_e32 v68, v56, v56
	v_mul_f32_e32 v69, v57, v57
	v_max_f32_e32 v56, v62, v62
	v_max_f32_e32 v57, v58, v58
	v_add_u32_e32 v64, 0x80, v148
	v_max_f32_e32 v56, 0, v56
	v_max_f32_e32 v57, 0, v57
	v_ashrrev_i32_e32 v65, 31, v64
	v_mul_f32_e32 v62, v56, v56
	v_mul_f32_e32 v58, v57, v57
	v_max_f32_e32 v56, v63, v63
	v_max_f32_e32 v57, v59, v59
	v_max_f32_e32 v52, v52, v52
	v_max_f32_e32 v48, v48, v48
	v_max_f32_e32 v53, v53, v53
	v_max_f32_e32 v49, v49, v49
	v_max_f32_e32 v54, v54, v54
	v_max_f32_e32 v50, v50, v50
	v_max_f32_e32 v55, v55, v55
	v_max_f32_e32 v51, v51, v51
	v_lshlrev_b64 v[64:65], 14, v[64:65]
	v_max_f32_e32 v60, v60, v60
	v_max_f32_e32 v56, 0, v56
	v_max_f32_e32 v57, 0, v57
	v_max_f32_e32 v52, 0, v52
	v_max_f32_e32 v48, 0, v48
	v_max_f32_e32 v53, 0, v53
	v_max_f32_e32 v49, 0, v49
	v_max_f32_e32 v54, 0, v54
	v_max_f32_e32 v50, 0, v50
	v_max_f32_e32 v55, 0, v55
	v_max_f32_e32 v51, 0, v51
	v_max_f32_e32 v60, 0, v60
	v_mul_f32_e32 v63, v56, v56
	v_mul_f32_e32 v59, v57, v57
	v_lshl_add_u64 v[56:57], s[28:29], 0, v[64:65]
	v_mul_f32_e32 v52, v52, v52
	v_mul_f32_e32 v48, v48, v48
	v_mul_f32_e32 v53, v53, v53
	v_mul_f32_e32 v49, v49, v49
	v_mul_f32_e32 v54, v54, v54
	v_mul_f32_e32 v50, v50, v50
	v_mul_f32_e32 v55, v55, v55
	v_mul_f32_e32 v51, v51, v51
	v_max_f32_e32 v40, v40, v40
	v_mul_f32_e32 v66, v60, v60
	v_lshl_add_u64 v[60:61], v[56:57], 0, v[120:121]
	v_cvt_pk_bf16_f32 v51, v50, v51
	v_cvt_pk_bf16_f32 v50, v48, v49
	v_cvt_pk_bf16_f32 v49, v54, v55
	v_cvt_pk_bf16_f32 v48, v52, v53
	v_max_f32_e32 v40, 0, v40
	global_store_dwordx4 v[60:61], v[48:51], off offset:256
	v_max_f32_e32 v41, v41, v41
	v_max_f32_e32 v41, 0, v41
	v_mul_f32_e32 v51, v40, v40
	v_max_f32_e32 v40, v45, v45
	v_max_f32_e32 v40, 0, v40
	v_mul_f32_e32 v52, v40, v40
	v_mul_f32_e32 v53, v41, v41
	v_max_f32_e32 v40, v46, v46
	v_max_f32_e32 v41, v42, v42
	v_add_u32_e32 v48, 0x90, v148
	v_max_f32_e32 v40, 0, v40
	v_max_f32_e32 v41, 0, v41
	v_ashrrev_i32_e32 v49, 31, v48
	v_mul_f32_e32 v46, v40, v40
	v_mul_f32_e32 v42, v41, v41
	v_max_f32_e32 v40, v47, v47
	v_max_f32_e32 v41, v43, v43
	v_max_f32_e32 v36, v36, v36
	v_max_f32_e32 v32, v32, v32
	v_max_f32_e32 v37, v37, v37
	v_max_f32_e32 v33, v33, v33
	v_max_f32_e32 v38, v38, v38
	v_max_f32_e32 v34, v34, v34
	v_max_f32_e32 v39, v39, v39
	v_max_f32_e32 v35, v35, v35
	v_lshlrev_b64 v[48:49], 14, v[48:49]
	v_max_f32_e32 v44, v44, v44
	v_max_f32_e32 v40, 0, v40
	v_max_f32_e32 v41, 0, v41
	v_max_f32_e32 v36, 0, v36
	v_max_f32_e32 v32, 0, v32
	v_max_f32_e32 v37, 0, v37
	v_max_f32_e32 v33, 0, v33
	v_max_f32_e32 v38, 0, v38
	v_max_f32_e32 v34, 0, v34
	v_max_f32_e32 v39, 0, v39
	v_max_f32_e32 v35, 0, v35
	v_max_f32_e32 v44, 0, v44
	v_mul_f32_e32 v47, v40, v40
	v_mul_f32_e32 v43, v41, v41
	v_lshl_add_u64 v[40:41], s[28:29], 0, v[48:49]
	v_mul_f32_e32 v36, v36, v36
	v_mul_f32_e32 v32, v32, v32
	v_mul_f32_e32 v37, v37, v37
	v_mul_f32_e32 v33, v33, v33
	v_mul_f32_e32 v38, v38, v38
	v_mul_f32_e32 v34, v34, v34
	v_mul_f32_e32 v39, v39, v39
	v_mul_f32_e32 v35, v35, v35
	v_max_f32_e32 v24, v24, v24
	v_mul_f32_e32 v50, v44, v44
	v_lshl_add_u64 v[44:45], v[40:41], 0, v[120:121]
	v_cvt_pk_bf16_f32 v35, v34, v35
	v_cvt_pk_bf16_f32 v34, v32, v33
	v_cvt_pk_bf16_f32 v33, v38, v39
	v_cvt_pk_bf16_f32 v32, v36, v37
	v_max_f32_e32 v24, 0, v24
	global_store_dwordx4 v[44:45], v[32:35], off offset:256
	v_max_f32_e32 v25, v25, v25
	v_max_f32_e32 v25, 0, v25
	v_mul_f32_e32 v35, v24, v24
	v_max_f32_e32 v24, v29, v29
	v_max_f32_e32 v24, 0, v24
	v_mul_f32_e32 v36, v24, v24
	v_mul_f32_e32 v37, v25, v25
	v_max_f32_e32 v24, v30, v30
	v_max_f32_e32 v25, v26, v26
	v_add_u32_e32 v32, 0xa0, v148
	v_max_f32_e32 v24, 0, v24
	v_max_f32_e32 v25, 0, v25
	v_ashrrev_i32_e32 v33, 31, v32
	v_mul_f32_e32 v30, v24, v24
	v_mul_f32_e32 v26, v25, v25
	v_max_f32_e32 v24, v31, v31
	v_max_f32_e32 v25, v27, v27
	v_max_f32_e32 v20, v20, v20
	v_max_f32_e32 v16, v16, v16
	v_max_f32_e32 v21, v21, v21
	v_max_f32_e32 v17, v17, v17
	v_max_f32_e32 v22, v22, v22
	v_max_f32_e32 v18, v18, v18
	v_max_f32_e32 v23, v23, v23
	v_max_f32_e32 v19, v19, v19
	v_lshlrev_b64 v[32:33], 14, v[32:33]
	v_max_f32_e32 v28, v28, v28
	v_max_f32_e32 v24, 0, v24
	v_max_f32_e32 v25, 0, v25
	v_max_f32_e32 v20, 0, v20
	v_max_f32_e32 v16, 0, v16
	v_max_f32_e32 v21, 0, v21
	v_max_f32_e32 v17, 0, v17
	v_max_f32_e32 v22, 0, v22
	v_max_f32_e32 v18, 0, v18
	v_max_f32_e32 v23, 0, v23
	v_max_f32_e32 v19, 0, v19
	v_max_f32_e32 v28, 0, v28
	v_mul_f32_e32 v31, v24, v24
	v_mul_f32_e32 v27, v25, v25
	v_lshl_add_u64 v[24:25], s[28:29], 0, v[32:33]
	v_mul_f32_e32 v20, v20, v20
	v_mul_f32_e32 v16, v16, v16
	v_mul_f32_e32 v21, v21, v21
	v_mul_f32_e32 v17, v17, v17
	v_mul_f32_e32 v22, v22, v22
	v_mul_f32_e32 v18, v18, v18
	v_mul_f32_e32 v23, v23, v23
	v_mul_f32_e32 v19, v19, v19
	v_max_f32_e32 v8, v8, v8
	v_mul_f32_e32 v34, v28, v28
	v_lshl_add_u64 v[28:29], v[24:25], 0, v[120:121]
	v_cvt_pk_bf16_f32 v19, v18, v19
	v_cvt_pk_bf16_f32 v18, v16, v17
	v_cvt_pk_bf16_f32 v17, v22, v23
	v_cvt_pk_bf16_f32 v16, v20, v21
	v_max_f32_e32 v8, 0, v8
	global_store_dwordx4 v[28:29], v[16:19], off offset:256
	v_max_f32_e32 v9, v9, v9
	v_max_f32_e32 v9, 0, v9
	v_mul_f32_e32 v19, v8, v8
	v_max_f32_e32 v8, v13, v13
	v_max_f32_e32 v8, 0, v8
	v_mul_f32_e32 v20, v8, v8
	v_mul_f32_e32 v21, v9, v9
	v_max_f32_e32 v8, v14, v14
	v_max_f32_e32 v9, v10, v10
	v_add_u32_e32 v16, 0xb0, v148
	v_max_f32_e32 v8, 0, v8
	v_max_f32_e32 v9, 0, v9
	v_ashrrev_i32_e32 v17, 31, v16
	v_max_f32_e32 v12, v12, v12
	v_mul_f32_e32 v14, v8, v8
	v_mul_f32_e32 v10, v9, v9
	v_max_f32_e32 v8, v15, v15
	v_max_f32_e32 v9, v11, v11
	v_max_f32_e32 v4, v4, v4
	v_max_f32_e32 v0, v0, v0
	v_max_f32_e32 v5, v5, v5
	v_max_f32_e32 v1, v1, v1
	v_max_f32_e32 v6, v6, v6
	v_max_f32_e32 v2, v2, v2
	v_max_f32_e32 v7, v7, v7
	v_max_f32_e32 v3, v3, v3
	v_lshlrev_b64 v[16:17], 14, v[16:17]
	v_max_f32_e32 v12, 0, v12
	v_max_f32_e32 v8, 0, v8
	v_max_f32_e32 v9, 0, v9
	v_max_f32_e32 v4, 0, v4
	v_max_f32_e32 v0, 0, v0
	v_max_f32_e32 v5, 0, v5
	v_max_f32_e32 v1, 0, v1
	v_max_f32_e32 v6, 0, v6
	v_max_f32_e32 v2, 0, v2
	v_max_f32_e32 v7, 0, v7
	v_max_f32_e32 v3, 0, v3
	v_mul_f32_e32 v18, v12, v12
	v_mul_f32_e32 v15, v8, v8
	v_mul_f32_e32 v11, v9, v9
	v_lshl_add_u64 v[8:9], s[28:29], 0, v[16:17]
	v_mul_f32_e32 v4, v4, v4
	v_mul_f32_e32 v0, v0, v0
	v_mul_f32_e32 v5, v5, v5
	v_mul_f32_e32 v1, v1, v1
	v_mul_f32_e32 v6, v6, v6
	v_mul_f32_e32 v2, v2, v2
	v_mul_f32_e32 v7, v7, v7
	v_mul_f32_e32 v3, v3, v3
	v_cvt_pk_bf16_f32 v125, v125, v163
	v_cvt_pk_bf16_f32 v124, v124, v160
	v_cvt_pk_bf16_f32 v123, v161, v162
	v_cvt_pk_bf16_f32 v122, v149, v155
	v_cvt_pk_bf16_f32 v107, v106, v107
	v_cvt_pk_bf16_f32 v106, v115, v117
	v_cvt_pk_bf16_f32 v105, v110, v111
	v_cvt_pk_bf16_f32 v104, v114, v116
	v_cvt_pk_bf16_f32 v91, v90, v91
	v_cvt_pk_bf16_f32 v90, v99, v101
	v_cvt_pk_bf16_f32 v89, v94, v95
	v_cvt_pk_bf16_f32 v88, v98, v100
	v_cvt_pk_bf16_f32 v75, v74, v75
	v_cvt_pk_bf16_f32 v74, v83, v85
	v_cvt_pk_bf16_f32 v73, v78, v79
	v_cvt_pk_bf16_f32 v72, v82, v84
	v_cvt_pk_bf16_f32 v59, v58, v59
	v_cvt_pk_bf16_f32 v58, v67, v69
	v_cvt_pk_bf16_f32 v57, v62, v63
	v_cvt_pk_bf16_f32 v56, v66, v68
	v_cvt_pk_bf16_f32 v43, v42, v43
	v_cvt_pk_bf16_f32 v42, v51, v53
	v_cvt_pk_bf16_f32 v41, v46, v47
	v_cvt_pk_bf16_f32 v40, v50, v52
	v_cvt_pk_bf16_f32 v27, v26, v27
	v_cvt_pk_bf16_f32 v26, v35, v37
	v_cvt_pk_bf16_f32 v25, v30, v31
	v_cvt_pk_bf16_f32 v24, v34, v36
	v_lshl_add_u64 v[12:13], v[8:9], 0, v[120:121]
	v_cvt_pk_bf16_f32 v11, v10, v11
	v_cvt_pk_bf16_f32 v10, v19, v21
	v_cvt_pk_bf16_f32 v9, v14, v15
	v_cvt_pk_bf16_f32 v8, v18, v20
	v_cvt_pk_bf16_f32 v3, v2, v3
	v_cvt_pk_bf16_f32 v2, v0, v1
	v_cvt_pk_bf16_f32 v1, v6, v7
	v_cvt_pk_bf16_f32 v0, v4, v5
	global_store_dwordx4 v[126:127], v[122:125], off
	global_store_dwordx4 v[108:109], v[104:107], off
	global_store_dwordx4 v[92:93], v[88:91], off
	global_store_dwordx4 v[76:77], v[72:75], off
	global_store_dwordx4 v[60:61], v[56:59], off
	global_store_dwordx4 v[44:45], v[40:43], off
	global_store_dwordx4 v[28:29], v[24:27], off
	global_store_dwordx4 v[12:13], v[8:11], off
	global_store_dwordx4 v[12:13], v[0:3], off offset:256

.LBB0_1030:
	ds_read_b128 v[148:151], v159
	ds_read_b128 v[152:155], v159 offset:1024
	ds_read_b128 v[162:165], v159 offset:2048
	ds_read_b128 v[166:169], v159 offset:3072
	s_add_u32 s20, s48, 0xffe00080
	s_addc_u32 s21, s49, -1
	s_cmpk_eq_i32 s63, 0x7c
	s_cselect_b32 s21, s17, s21
	s_cselect_b32 s20, s59, s20
	s_cselect_b32 s51, s15, s62
	s_cselect_b32 s50, s60, s61
	v_lshl_add_u64 v[190:191], s[48:49], 0, v[136:137]
	s_add_i32 m0, s37, 0xc000
	ds_read_b128 v[170:173], v160
	ds_read_b128 v[174:177], v160 offset:1024
	ds_read_b128 v[178:181], v160 offset:2048
	ds_read_b128 v[182:185], v160 offset:3072
	ds_read_b128 v[186:189], v160 offset:4096
	ds_read_b128 v[196:199], v160 offset:5120
	ds_read_b128 v[200:203], v160 offset:6144
	ds_read_b128 v[204:207], v160 offset:7168
	global_load_lds_dwordx4 v[190:191], off
	s_add_i32 m0, s37, 0xe000
	v_lshl_add_u64 v[190:191], s[48:49], 0, v[138:139]
	global_load_lds_dwordx4 v[190:191], off
	s_waitcnt lgkmcnt(8)
	s_barrier
	s_waitcnt lgkmcnt(0)
	v_mfma_f32_16x16x32_bf16 v[124:127], v[148:151], v[170:173], v[124:127]
	v_mfma_f32_16x16x32_bf16 v[120:123], v[162:165], v[170:173], v[120:123]
	v_mfma_f32_16x16x32_bf16 v[108:111], v[148:151], v[178:181], v[108:111]
	v_mfma_f32_16x16x32_bf16 v[104:107], v[162:165], v[178:181], v[104:107]
	v_mfma_f32_16x16x32_bf16 v[92:95], v[148:151], v[186:189], v[92:95]
	v_mfma_f32_16x16x32_bf16 v[88:91], v[162:165], v[186:189], v[88:91]
	v_mfma_f32_16x16x32_bf16 v[76:79], v[148:151], v[200:203], v[76:79]
	v_mfma_f32_16x16x32_bf16 v[72:75], v[162:165], v[200:203], v[72:75]
	v_mfma_f32_16x16x32_bf16 v[124:127], v[152:155], v[174:177], v[124:127]
	v_mfma_f32_16x16x32_bf16 v[120:123], v[166:169], v[174:177], v[120:123]
	v_mfma_f32_16x16x32_bf16 v[108:111], v[152:155], v[182:185], v[108:111]
	v_mfma_f32_16x16x32_bf16 v[104:107], v[166:169], v[182:185], v[104:107]
	v_mfma_f32_16x16x32_bf16 v[92:95], v[152:155], v[196:199], v[92:95]
	v_mfma_f32_16x16x32_bf16 v[88:91], v[166:169], v[196:199], v[88:91]
	v_mfma_f32_16x16x32_bf16 v[76:79], v[152:155], v[204:207], v[76:79]
	v_mfma_f32_16x16x32_bf16 v[72:75], v[166:169], v[204:207], v[72:75]
	s_barrier
	s_add_i32 s64, s55, s23
	v_lshl_add_u64 v[190:191], s[50:51], 0, v[132:133]
	s_mov_b32 m0, s64
	ds_read_b128 v[208:211], v161
	ds_read_b128 v[212:215], v161 offset:1024
	ds_read_b128 v[216:219], v161 offset:2048
	ds_read_b128 v[220:223], v161 offset:3072
	global_load_lds_dwordx4 v[190:191], off
	s_add_i32 m0, s64, 0x2000
	v_lshl_add_u64 v[224:225], s[50:51], 0, v[128:129]
	global_load_lds_dwordx4 v[224:225], off
	s_barrier
	s_waitcnt lgkmcnt(0)
	v_mfma_f32_16x16x32_bf16 v[116:119], v[208:211], v[170:173], v[116:119]
	v_mfma_f32_16x16x32_bf16 v[112:115], v[216:219], v[170:173], v[112:115]
	v_mfma_f32_16x16x32_bf16 v[100:103], v[208:211], v[178:181], v[100:103]
	v_mfma_f32_16x16x32_bf16 v[96:99], v[216:219], v[178:181], v[96:99]
	v_mfma_f32_16x16x32_bf16 v[84:87], v[208:211], v[186:189], v[84:87]
	v_mfma_f32_16x16x32_bf16 v[80:83], v[216:219], v[186:189], v[80:83]
	v_mfma_f32_16x16x32_bf16 v[68:71], v[208:211], v[200:203], v[68:71]
	v_mfma_f32_16x16x32_bf16 v[64:67], v[216:219], v[200:203], v[64:67]
	v_mfma_f32_16x16x32_bf16 v[116:119], v[212:215], v[174:177], v[116:119]
	v_mfma_f32_16x16x32_bf16 v[112:115], v[220:223], v[174:177], v[112:115]
	v_mfma_f32_16x16x32_bf16 v[100:103], v[212:215], v[182:185], v[100:103]
	v_mfma_f32_16x16x32_bf16 v[96:99], v[220:223], v[182:185], v[96:99]
	v_mfma_f32_16x16x32_bf16 v[84:87], v[212:215], v[196:199], v[84:87]
	v_mfma_f32_16x16x32_bf16 v[80:83], v[220:223], v[196:199], v[80:83]
	v_mfma_f32_16x16x32_bf16 v[68:71], v[212:215], v[204:207], v[68:71]
	v_mfma_f32_16x16x32_bf16 v[64:67], v[220:223], v[204:207], v[64:67]
	s_mov_b32 m0, s37
	v_lshl_add_u64 v[226:227], s[20:21], 0, v[134:135]
	s_barrier
	ds_read_b128 v[170:173], v160 offset:16384
	ds_read_b128 v[174:177], v160 offset:17408
	ds_read_b128 v[178:181], v160 offset:18432
	ds_read_b128 v[182:185], v160 offset:19456
	ds_read_b128 v[186:189], v160 offset:20480
	ds_read_b128 v[196:199], v160 offset:21504
	ds_read_b128 v[200:203], v160 offset:22528
	ds_read_b128 v[204:207], v160 offset:23552
	global_load_lds_dwordx4 v[226:227], off
	s_mov_b32 m0, s38
	v_lshl_add_u64 v[228:229], s[20:21], 0, v[130:131]
	global_load_lds_dwordx4 v[228:229], off
	s_barrier
	s_waitcnt lgkmcnt(0)
	v_mfma_f32_16x16x32_bf16 v[60:63], v[148:151], v[170:173], v[60:63]
	v_mfma_f32_16x16x32_bf16 v[56:59], v[162:165], v[170:173], v[56:59]
	v_mfma_f32_16x16x32_bf16 v[44:47], v[148:151], v[178:181], v[44:47]
	v_mfma_f32_16x16x32_bf16 v[40:43], v[162:165], v[178:181], v[40:43]
	v_mfma_f32_16x16x32_bf16 v[28:31], v[148:151], v[186:189], v[28:31]
	v_mfma_f32_16x16x32_bf16 v[24:27], v[162:165], v[186:189], v[24:27]
	v_mfma_f32_16x16x32_bf16 v[12:15], v[148:151], v[200:203], v[12:15]
	v_mfma_f32_16x16x32_bf16 v[8:11], v[162:165], v[200:203], v[8:11]
	v_mfma_f32_16x16x32_bf16 v[60:63], v[152:155], v[174:177], v[60:63]
	v_mfma_f32_16x16x32_bf16 v[56:59], v[166:169], v[174:177], v[56:59]
	v_mfma_f32_16x16x32_bf16 v[44:47], v[152:155], v[182:185], v[44:47]
	v_mfma_f32_16x16x32_bf16 v[40:43], v[166:169], v[182:185], v[40:43]
	v_mfma_f32_16x16x32_bf16 v[28:31], v[152:155], v[196:199], v[28:31]
	v_mfma_f32_16x16x32_bf16 v[24:27], v[166:169], v[196:199], v[24:27]
	v_mfma_f32_16x16x32_bf16 v[12:15], v[152:155], v[204:207], v[12:15]
	v_mfma_f32_16x16x32_bf16 v[8:11], v[166:169], v[204:207], v[8:11]
	s_barrier
	s_add_u32 s64, s50, 0x200000
	s_addc_u32 s65, s51, 0
	s_add_i32 s66, s57, s23
	s_mov_b32 m0, s66
	v_lshl_add_u64 v[148:149], s[64:65], 0, v[132:133]
	global_load_lds_dwordx4 v[148:149], off
	s_add_i32 m0, s66, 0x2000
	v_lshl_add_u64 v[148:149], s[64:65], 0, v[128:129]
	global_load_lds_dwordx4 v[148:149], off
	s_waitcnt vmcnt(6)
	s_barrier
	v_mfma_f32_16x16x32_bf16 v[52:55], v[208:211], v[170:173], v[52:55]
	v_mfma_f32_16x16x32_bf16 v[48:51], v[216:219], v[170:173], v[48:51]
	v_mfma_f32_16x16x32_bf16 v[36:39], v[208:211], v[178:181], v[36:39]
	v_mfma_f32_16x16x32_bf16 v[32:35], v[216:219], v[178:181], v[32:35]
	v_mfma_f32_16x16x32_bf16 v[20:23], v[208:211], v[186:189], v[20:23]
	v_mfma_f32_16x16x32_bf16 v[16:19], v[216:219], v[186:189], v[16:19]
	v_mfma_f32_16x16x32_bf16 v[4:7], v[208:211], v[200:203], v[4:7]
	v_mfma_f32_16x16x32_bf16 v[0:3], v[216:219], v[200:203], v[0:3]
	v_mfma_f32_16x16x32_bf16 v[52:55], v[212:215], v[174:177], v[52:55]
	v_mfma_f32_16x16x32_bf16 v[48:51], v[220:223], v[174:177], v[48:51]
	v_mfma_f32_16x16x32_bf16 v[36:39], v[212:215], v[182:185], v[36:39]
	v_mfma_f32_16x16x32_bf16 v[32:35], v[220:223], v[182:185], v[32:35]
	v_mfma_f32_16x16x32_bf16 v[20:23], v[212:215], v[196:199], v[20:23]
	v_mfma_f32_16x16x32_bf16 v[16:19], v[220:223], v[196:199], v[16:19]
	v_mfma_f32_16x16x32_bf16 v[4:7], v[212:215], v[204:207], v[4:7]
	v_mfma_f32_16x16x32_bf16 v[0:3], v[220:223], v[204:207], v[0:3]
	s_add_i32 s64, 0, 0x18000
	v_add_u32_e32 v166, s64, v156
	s_barrier
	ds_read_b128 v[148:151], v166
	ds_read_b128 v[152:155], v166 offset:1024
	ds_read_b128 v[162:165], v166 offset:2048
	ds_read_b128 v[166:169], v166 offset:3072
	s_add_u32 s20, s20, 0x200000
	s_addc_u32 s21, s21, 0
	s_mov_b32 m0, s39
	v_lshl_add_u64 v[208:209], s[20:21], 0, v[134:135]
	ds_read_b128 v[170:173], v160 offset:32768
	ds_read_b128 v[174:177], v160 offset:33792
	ds_read_b128 v[178:181], v160 offset:34816
	ds_read_b128 v[182:185], v160 offset:35840
	ds_read_b128 v[186:189], v160 offset:36864
	ds_read_b128 v[196:199], v160 offset:37888
	ds_read_b128 v[200:203], v160 offset:38912
	ds_read_b128 v[204:207], v160 offset:39936
	global_load_lds_dwordx4 v[208:209], off
	s_mov_b32 m0, s47
	v_lshl_add_u64 v[208:209], s[20:21], 0, v[130:131]
	global_load_lds_dwordx4 v[208:209], off
	s_waitcnt lgkmcnt(8)
	s_barrier
	s_waitcnt lgkmcnt(0)
	v_mfma_f32_16x16x32_bf16 v[124:127], v[148:151], v[170:173], v[124:127]
	v_mfma_f32_16x16x32_bf16 v[120:123], v[162:165], v[170:173], v[120:123]
	v_mfma_f32_16x16x32_bf16 v[108:111], v[148:151], v[178:181], v[108:111]
	v_mfma_f32_16x16x32_bf16 v[104:107], v[162:165], v[178:181], v[104:107]
	v_mfma_f32_16x16x32_bf16 v[92:95], v[148:151], v[186:189], v[92:95]
	v_mfma_f32_16x16x32_bf16 v[88:91], v[162:165], v[186:189], v[88:91]
	v_mfma_f32_16x16x32_bf16 v[76:79], v[148:151], v[200:203], v[76:79]
	v_mfma_f32_16x16x32_bf16 v[72:75], v[162:165], v[200:203], v[72:75]
	v_mfma_f32_16x16x32_bf16 v[124:127], v[152:155], v[174:177], v[124:127]
	v_mfma_f32_16x16x32_bf16 v[120:123], v[166:169], v[174:177], v[120:123]
	v_mfma_f32_16x16x32_bf16 v[108:111], v[152:155], v[182:185], v[108:111]
	v_mfma_f32_16x16x32_bf16 v[104:107], v[166:169], v[182:185], v[104:107]
	v_mfma_f32_16x16x32_bf16 v[92:95], v[152:155], v[196:199], v[92:95]
	v_mfma_f32_16x16x32_bf16 v[88:91], v[166:169], v[196:199], v[88:91]
	v_mfma_f32_16x16x32_bf16 v[76:79], v[152:155], v[204:207], v[76:79]
	v_mfma_f32_16x16x32_bf16 v[72:75], v[166:169], v[204:207], v[72:75]
	s_barrier
	s_add_i32 s65, 0, 0x1c000
	s_add_i32 s20, s64, s23
	v_add_u32_e32 v195, s65, v156
	v_lshl_add_u64 v[190:191], v[190:191], 0, s[10:11]
	s_mov_b32 m0, s20
	ds_read_b128 v[208:211], v195
	ds_read_b128 v[212:215], v195 offset:1024
	ds_read_b128 v[216:219], v195 offset:2048
	ds_read_b128 v[220:223], v195 offset:3072
	global_load_lds_dwordx4 v[190:191], off
	s_add_i32 m0, s20, 0x2000
	v_lshl_add_u64 v[190:191], v[224:225], 0, s[10:11]
	global_load_lds_dwordx4 v[190:191], off
	s_barrier
	s_waitcnt lgkmcnt(0)
	v_mfma_f32_16x16x32_bf16 v[116:119], v[208:211], v[170:173], v[116:119]
	v_mfma_f32_16x16x32_bf16 v[112:115], v[216:219], v[170:173], v[112:115]
	v_mfma_f32_16x16x32_bf16 v[100:103], v[208:211], v[178:181], v[100:103]
	v_mfma_f32_16x16x32_bf16 v[96:99], v[216:219], v[178:181], v[96:99]
	v_mfma_f32_16x16x32_bf16 v[84:87], v[208:211], v[186:189], v[84:87]
	v_mfma_f32_16x16x32_bf16 v[80:83], v[216:219], v[186:189], v[80:83]
	v_mfma_f32_16x16x32_bf16 v[68:71], v[208:211], v[200:203], v[68:71]
	v_mfma_f32_16x16x32_bf16 v[64:67], v[216:219], v[200:203], v[64:67]
	v_mfma_f32_16x16x32_bf16 v[116:119], v[212:215], v[174:177], v[116:119]
	v_mfma_f32_16x16x32_bf16 v[112:115], v[220:223], v[174:177], v[112:115]
	v_mfma_f32_16x16x32_bf16 v[100:103], v[212:215], v[182:185], v[100:103]
	v_mfma_f32_16x16x32_bf16 v[96:99], v[220:223], v[182:185], v[96:99]
	v_mfma_f32_16x16x32_bf16 v[84:87], v[212:215], v[196:199], v[84:87]
	v_mfma_f32_16x16x32_bf16 v[80:83], v[220:223], v[196:199], v[80:83]
	v_mfma_f32_16x16x32_bf16 v[68:71], v[212:215], v[204:207], v[68:71]
	v_mfma_f32_16x16x32_bf16 v[64:67], v[220:223], v[204:207], v[64:67]
	s_mov_b32 m0, s34
	v_lshl_add_u64 v[190:191], v[226:227], 0, s[10:11]
	s_barrier
	ds_read_b128 v[170:173], v160 offset:49152
	ds_read_b128 v[174:177], v160 offset:50176
	ds_read_b128 v[178:181], v160 offset:51200
	ds_read_b128 v[182:185], v160 offset:52224
	ds_read_b128 v[186:189], v160 offset:53248
	ds_read_b128 v[196:199], v160 offset:54272
	ds_read_b128 v[200:203], v160 offset:55296
	ds_read_b128 v[204:207], v160 offset:56320
	global_load_lds_dwordx4 v[190:191], off
	s_mov_b32 m0, s35
	v_lshl_add_u64 v[190:191], v[228:229], 0, s[10:11]
	global_load_lds_dwordx4 v[190:191], off
	s_barrier
	s_waitcnt lgkmcnt(0)
	v_mfma_f32_16x16x32_bf16 v[60:63], v[148:151], v[170:173], v[60:63]
	v_mfma_f32_16x16x32_bf16 v[56:59], v[162:165], v[170:173], v[56:59]
	v_mfma_f32_16x16x32_bf16 v[44:47], v[148:151], v[178:181], v[44:47]
	v_mfma_f32_16x16x32_bf16 v[40:43], v[162:165], v[178:181], v[40:43]
	v_mfma_f32_16x16x32_bf16 v[28:31], v[148:151], v[186:189], v[28:31]
	v_mfma_f32_16x16x32_bf16 v[24:27], v[162:165], v[186:189], v[24:27]
	v_mfma_f32_16x16x32_bf16 v[12:15], v[148:151], v[200:203], v[12:15]
	v_mfma_f32_16x16x32_bf16 v[8:11], v[162:165], v[200:203], v[8:11]
	v_mfma_f32_16x16x32_bf16 v[60:63], v[152:155], v[174:177], v[60:63]
	v_mfma_f32_16x16x32_bf16 v[56:59], v[166:169], v[174:177], v[56:59]
	v_mfma_f32_16x16x32_bf16 v[44:47], v[152:155], v[182:185], v[44:47]
	v_mfma_f32_16x16x32_bf16 v[40:43], v[166:169], v[182:185], v[40:43]
	v_mfma_f32_16x16x32_bf16 v[28:31], v[152:155], v[196:199], v[28:31]
	v_mfma_f32_16x16x32_bf16 v[24:27], v[166:169], v[196:199], v[24:27]
	v_mfma_f32_16x16x32_bf16 v[12:15], v[152:155], v[204:207], v[12:15]
	v_mfma_f32_16x16x32_bf16 v[8:11], v[166:169], v[204:207], v[8:11]
	s_barrier
	s_add_u32 s20, s50, 0x200080
	s_addc_u32 s21, s51, 0
	s_add_i32 s50, s65, s23
	s_mov_b32 m0, s50
	v_lshl_add_u64 v[148:149], s[20:21], 0, v[132:133]
	global_load_lds_dwordx4 v[148:149], off
	s_add_i32 m0, s50, 0x2000
	v_lshl_add_u64 v[148:149], s[20:21], 0, v[128:129]
	global_load_lds_dwordx4 v[148:149], off
	s_waitcnt vmcnt(6)
	s_barrier
	v_mfma_f32_16x16x32_bf16 v[52:55], v[208:211], v[170:173], v[52:55]
	v_mfma_f32_16x16x32_bf16 v[48:51], v[216:219], v[170:173], v[48:51]
	v_mfma_f32_16x16x32_bf16 v[36:39], v[208:211], v[178:181], v[36:39]
	v_mfma_f32_16x16x32_bf16 v[32:35], v[216:219], v[178:181], v[32:35]
	v_mfma_f32_16x16x32_bf16 v[20:23], v[208:211], v[186:189], v[20:23]
	v_mfma_f32_16x16x32_bf16 v[16:19], v[216:219], v[186:189], v[16:19]
	v_mfma_f32_16x16x32_bf16 v[4:7], v[208:211], v[200:203], v[4:7]
	v_mfma_f32_16x16x32_bf16 v[0:3], v[216:219], v[200:203], v[0:3]
	v_mfma_f32_16x16x32_bf16 v[52:55], v[212:215], v[174:177], v[52:55]
	v_mfma_f32_16x16x32_bf16 v[48:51], v[220:223], v[174:177], v[48:51]
	v_mfma_f32_16x16x32_bf16 v[36:39], v[212:215], v[182:185], v[36:39]
	v_mfma_f32_16x16x32_bf16 v[32:35], v[220:223], v[182:185], v[32:35]
	v_mfma_f32_16x16x32_bf16 v[20:23], v[212:215], v[196:199], v[20:23]
	v_mfma_f32_16x16x32_bf16 v[16:19], v[220:223], v[196:199], v[16:19]
	v_mfma_f32_16x16x32_bf16 v[4:7], v[212:215], v[204:207], v[4:7]
	v_mfma_f32_16x16x32_bf16 v[0:3], v[220:223], v[204:207], v[0:3]
	s_add_i32 s63, s63, 2
	s_add_u32 s48, s48, 0x100
	s_addc_u32 s49, s49, 0
	s_add_u32 s61, s61, 0x100
	s_addc_u32 s62, s62, 0
	s_cmpk_gt_u32 s63, 0x7d
	s_cbranch_scc0 .Lepi_nl_mlpout0
	s_cmp_lg_u32 s53, 64
	s_cbranch_scc1 .Lepi_nl_mlpout0
	s_lshl_b32 s15, s46, 8
	s_add_i32 s15, s15, s53
	v_or_b32_e32 v154, s15, v147
	s_add_i32 s17, s15, 0xffffe000
	v_lshl_or_b32 v150, s33, 8, v158
	s_lshr_b32 s17, s17, 12
	v_lshlrev_b32_e32 v148, 12, v154
	s_add_i32 s17, s17, 1
	s_cmp_gt_i32 s15, s58
	s_cselect_b32 s17, s17, 0
	s_mul_i32 s17, s17, s56
	v_lshl_add_u32 v148, v150, 1, v148
	s_add_u32 s20, s8, s17
	s_addc_u32 s21, s9, 0
	v_lshlrev_b32_e32 v149, 2, v150
	s_nop 0
	global_load_dwordx4 v[196:199], v149, s[20:21]
	global_load_dwordx4 v[200:203], v149, s[20:21] offset:16
	global_load_dwordx4 v[204:207], v149, s[20:21] offset:512
	global_load_dwordx4 v[208:211], v149, s[20:21] offset:528
	global_load_dwordx4 v[212:215], v148, s[74:75]
	global_load_dwordx4 v[216:219], v148, s[74:75] offset:256
	v_add_u32_e32 v151, 0x10000, v148
	global_load_dwordx4 v[220:223], v151, s[74:75]
	global_load_dwordx4 v[224:227], v151, s[74:75] offset:256
	v_add_u32_e32 v151, 0x20000, v148
	global_load_dwordx4 v[164:167], v151, s[74:75]
	global_load_dwordx4 v[168:171], v151, s[74:75] offset:256
	v_add_u32_e32 v151, 0x30000, v148
	global_load_dwordx4 v[172:175], v151, s[74:75]
	global_load_dwordx4 v[176:179], v151, s[74:75] offset:256
	s_waitcnt vmcnt(0)
	v_lshlrev_b32_e32 v180, 16, v212
	v_and_b32_e32 v181, 0xffff0000, v212
	v_lshlrev_b32_e32 v182, 16, v213
	v_and_b32_e32 v183, 0xffff0000, v213
	v_lshlrev_b32_e32 v184, 16, v214
	v_and_b32_e32 v185, 0xffff0000, v214
	v_lshlrev_b32_e32 v186, 16, v215
	v_and_b32_e32 v187, 0xffff0000, v215
	v_pk_fma_f32 v[124:125], v[124:125], v[196:197], v[180:181]
	v_pk_fma_f32 v[126:127], v[126:127], v[198:199], v[182:183]
	v_pk_fma_f32 v[120:121], v[120:121], v[200:201], v[184:185]
	v_pk_fma_f32 v[122:123], v[122:123], v[202:203], v[186:187]
	v_cvt_pk_bf16_f32 v123, v122, v123
	v_cvt_pk_bf16_f32 v122, v120, v121
	v_cvt_pk_bf16_f32 v121, v126, v127
	v_cvt_pk_bf16_f32 v120, v124, v125
	global_store_dwordx4 v148, v[120:123], s[74:75]
	v_lshlrev_b32_e32 v180, 16, v216
	v_and_b32_e32 v181, 0xffff0000, v216
	v_lshlrev_b32_e32 v182, 16, v217
	v_and_b32_e32 v183, 0xffff0000, v217
	v_lshlrev_b32_e32 v184, 16, v218
	v_and_b32_e32 v185, 0xffff0000, v218
	v_lshlrev_b32_e32 v186, 16, v219
	v_and_b32_e32 v187, 0xffff0000, v219
	v_pk_fma_f32 v[116:117], v[116:117], v[204:205], v[180:181]
	v_pk_fma_f32 v[118:119], v[118:119], v[206:207], v[182:183]
	v_pk_fma_f32 v[112:113], v[112:113], v[208:209], v[184:185]
	v_pk_fma_f32 v[114:115], v[114:115], v[210:211], v[186:187]
	v_cvt_pk_bf16_f32 v115, v114, v115
	v_cvt_pk_bf16_f32 v114, v112, v113
	v_cvt_pk_bf16_f32 v113, v118, v119
	v_cvt_pk_bf16_f32 v112, v116, v117
	global_store_dwordx4 v148, v[112:115], s[74:75] offset:256
	v_lshlrev_b32_e32 v180, 16, v220
	v_and_b32_e32 v181, 0xffff0000, v220
	v_lshlrev_b32_e32 v182, 16, v221
	v_and_b32_e32 v183, 0xffff0000, v221
	v_lshlrev_b32_e32 v184, 16, v222
	v_and_b32_e32 v185, 0xffff0000, v222
	v_lshlrev_b32_e32 v186, 16, v223
	v_and_b32_e32 v187, 0xffff0000, v223
	v_pk_fma_f32 v[108:109], v[108:109], v[196:197], v[180:181]
	v_pk_fma_f32 v[110:111], v[110:111], v[198:199], v[182:183]
	v_pk_fma_f32 v[104:105], v[104:105], v[200:201], v[184:185]
	v_pk_fma_f32 v[106:107], v[106:107], v[202:203], v[186:187]
	v_cvt_pk_bf16_f32 v107, v106, v107
	v_cvt_pk_bf16_f32 v106, v104, v105
	v_cvt_pk_bf16_f32 v105, v110, v111
	v_cvt_pk_bf16_f32 v104, v108, v109
	v_add_u32_e32 v151, 0x10000, v148
	global_store_dwordx4 v151, v[104:107], s[74:75]
	v_lshlrev_b32_e32 v180, 16, v224
	v_and_b32_e32 v181, 0xffff0000, v224
	v_lshlrev_b32_e32 v182, 16, v225
	v_and_b32_e32 v183, 0xffff0000, v225
	v_lshlrev_b32_e32 v184, 16, v226
	v_and_b32_e32 v185, 0xffff0000, v226
	v_lshlrev_b32_e32 v186, 16, v227
	v_and_b32_e32 v187, 0xffff0000, v227
	v_pk_fma_f32 v[100:101], v[100:101], v[204:205], v[180:181]
	v_pk_fma_f32 v[102:103], v[102:103], v[206:207], v[182:183]
	v_pk_fma_f32 v[96:97], v[96:97], v[208:209], v[184:185]
	v_pk_fma_f32 v[98:99], v[98:99], v[210:211], v[186:187]
	v_cvt_pk_bf16_f32 v99, v98, v99
	v_cvt_pk_bf16_f32 v98, v96, v97
	v_cvt_pk_bf16_f32 v97, v102, v103
	v_cvt_pk_bf16_f32 v96, v100, v101
	v_add_u32_e32 v151, 0x10000, v148
	global_store_dwordx4 v151, v[96:99], s[74:75] offset:256
	v_add_u32_e32 v151, 0x80000, v148
	global_load_dwordx4 v[212:215], v151, s[74:75]
	global_load_dwordx4 v[216:219], v151, s[74:75] offset:256
	v_add_u32_e32 v151, 0x90000, v148
	global_load_dwordx4 v[220:223], v151, s[74:75]
	global_load_dwordx4 v[224:227], v151, s[74:75] offset:256
	v_lshlrev_b32_e32 v180, 16, v164
	v_and_b32_e32 v181, 0xffff0000, v164
	v_lshlrev_b32_e32 v182, 16, v165
	v_and_b32_e32 v183, 0xffff0000, v165
	v_lshlrev_b32_e32 v184, 16, v166
	v_and_b32_e32 v185, 0xffff0000, v166
	v_lshlrev_b32_e32 v186, 16, v167
	v_and_b32_e32 v187, 0xffff0000, v167
	v_pk_fma_f32 v[92:93], v[92:93], v[196:197], v[180:181]
	v_pk_fma_f32 v[94:95], v[94:95], v[198:199], v[182:183]
	v_pk_fma_f32 v[88:89], v[88:89], v[200:201], v[184:185]
	v_pk_fma_f32 v[90:91], v[90:91], v[202:203], v[186:187]
	v_cvt_pk_bf16_f32 v91, v90, v91
	v_cvt_pk_bf16_f32 v90, v88, v89
	v_cvt_pk_bf16_f32 v89, v94, v95
	v_cvt_pk_bf16_f32 v88, v92, v93
	v_add_u32_e32 v151, 0x20000, v148
	global_store_dwordx4 v151, v[88:91], s[74:75]
	v_lshlrev_b32_e32 v180, 16, v168
	v_and_b32_e32 v181, 0xffff0000, v168
	v_lshlrev_b32_e32 v182, 16, v169
	v_and_b32_e32 v183, 0xffff0000, v169
	v_lshlrev_b32_e32 v184, 16, v170
	v_and_b32_e32 v185, 0xffff0000, v170
	v_lshlrev_b32_e32 v186, 16, v171
	v_and_b32_e32 v187, 0xffff0000, v171
	v_pk_fma_f32 v[84:85], v[84:85], v[204:205], v[180:181]
	v_pk_fma_f32 v[86:87], v[86:87], v[206:207], v[182:183]
	v_pk_fma_f32 v[80:81], v[80:81], v[208:209], v[184:185]
	v_pk_fma_f32 v[82:83], v[82:83], v[210:211], v[186:187]
	v_cvt_pk_bf16_f32 v83, v82, v83
	v_cvt_pk_bf16_f32 v82, v80, v81
	v_cvt_pk_bf16_f32 v81, v86, v87
	v_cvt_pk_bf16_f32 v80, v84, v85
	v_add_u32_e32 v151, 0x20000, v148
	global_store_dwordx4 v151, v[80:83], s[74:75] offset:256
	v_lshlrev_b32_e32 v180, 16, v172
	v_and_b32_e32 v181, 0xffff0000, v172
	v_lshlrev_b32_e32 v182, 16, v173
	v_and_b32_e32 v183, 0xffff0000, v173
	v_lshlrev_b32_e32 v184, 16, v174
	v_and_b32_e32 v185, 0xffff0000, v174
	v_lshlrev_b32_e32 v186, 16, v175
	v_and_b32_e32 v187, 0xffff0000, v175
	v_pk_fma_f32 v[76:77], v[76:77], v[196:197], v[180:181]
	v_pk_fma_f32 v[78:79], v[78:79], v[198:199], v[182:183]
	v_pk_fma_f32 v[72:73], v[72:73], v[200:201], v[184:185]
	v_pk_fma_f32 v[74:75], v[74:75], v[202:203], v[186:187]
	v_cvt_pk_bf16_f32 v75, v74, v75
	v_cvt_pk_bf16_f32 v74, v72, v73
	v_cvt_pk_bf16_f32 v73, v78, v79
	v_cvt_pk_bf16_f32 v72, v76, v77
	v_add_u32_e32 v151, 0x30000, v148
	global_store_dwordx4 v151, v[72:75], s[74:75]
	v_lshlrev_b32_e32 v180, 16, v176
	v_and_b32_e32 v181, 0xffff0000, v176
	v_lshlrev_b32_e32 v182, 16, v177
	v_and_b32_e32 v183, 0xffff0000, v177
	v_lshlrev_b32_e32 v184, 16, v178
	v_and_b32_e32 v185, 0xffff0000, v178
	v_lshlrev_b32_e32 v186, 16, v179
	v_and_b32_e32 v187, 0xffff0000, v179
	v_pk_fma_f32 v[68:69], v[68:69], v[204:205], v[180:181]
	v_pk_fma_f32 v[70:71], v[70:71], v[206:207], v[182:183]
	v_pk_fma_f32 v[64:65], v[64:65], v[208:209], v[184:185]
	v_pk_fma_f32 v[66:67], v[66:67], v[210:211], v[186:187]
	v_cvt_pk_bf16_f32 v67, v66, v67
	v_cvt_pk_bf16_f32 v66, v64, v65
	v_cvt_pk_bf16_f32 v65, v70, v71
	v_cvt_pk_bf16_f32 v64, v68, v69
	v_add_u32_e32 v151, 0x30000, v148
	global_store_dwordx4 v151, v[64:67], s[74:75] offset:256
	v_add_u32_e32 v151, 0xa0000, v148
	global_load_dwordx4 v[164:167], v151, s[74:75]
	global_load_dwordx4 v[168:171], v151, s[74:75] offset:256
	v_add_u32_e32 v151, 0xb0000, v148
	global_load_dwordx4 v[172:175], v151, s[74:75]
	global_load_dwordx4 v[176:179], v151, s[74:75] offset:256
	s_waitcnt vmcnt(0)
	v_lshlrev_b32_e32 v180, 16, v212
	v_and_b32_e32 v181, 0xffff0000, v212
	v_lshlrev_b32_e32 v182, 16, v213
	v_and_b32_e32 v183, 0xffff0000, v213
	v_lshlrev_b32_e32 v184, 16, v214
	v_and_b32_e32 v185, 0xffff0000, v214
	v_lshlrev_b32_e32 v186, 16, v215
	v_and_b32_e32 v187, 0xffff0000, v215
	v_pk_fma_f32 v[60:61], v[60:61], v[196:197], v[180:181]
	v_pk_fma_f32 v[62:63], v[62:63], v[198:199], v[182:183]
	v_pk_fma_f32 v[56:57], v[56:57], v[200:201], v[184:185]
	v_pk_fma_f32 v[58:59], v[58:59], v[202:203], v[186:187]
	v_cvt_pk_bf16_f32 v59, v58, v59
	v_cvt_pk_bf16_f32 v58, v56, v57
	v_cvt_pk_bf16_f32 v57, v62, v63
	v_cvt_pk_bf16_f32 v56, v60, v61
	v_add_u32_e32 v151, 0x80000, v148
	global_store_dwordx4 v151, v[56:59], s[74:75]
	v_lshlrev_b32_e32 v180, 16, v216
	v_and_b32_e32 v181, 0xffff0000, v216
	v_lshlrev_b32_e32 v182, 16, v217
	v_and_b32_e32 v183, 0xffff0000, v217
	v_lshlrev_b32_e32 v184, 16, v218
	v_and_b32_e32 v185, 0xffff0000, v218
	v_lshlrev_b32_e32 v186, 16, v219
	v_and_b32_e32 v187, 0xffff0000, v219
	v_pk_fma_f32 v[52:53], v[52:53], v[204:205], v[180:181]
	v_pk_fma_f32 v[54:55], v[54:55], v[206:207], v[182:183]
	v_pk_fma_f32 v[48:49], v[48:49], v[208:209], v[184:185]
	v_pk_fma_f32 v[50:51], v[50:51], v[210:211], v[186:187]
	v_cvt_pk_bf16_f32 v51, v50, v51
	v_cvt_pk_bf16_f32 v50, v48, v49
	v_cvt_pk_bf16_f32 v49, v54, v55
	v_cvt_pk_bf16_f32 v48, v52, v53
	v_add_u32_e32 v151, 0x80000, v148
	global_store_dwordx4 v151, v[48:51], s[74:75] offset:256
	v_lshlrev_b32_e32 v180, 16, v220
	v_and_b32_e32 v181, 0xffff0000, v220
	v_lshlrev_b32_e32 v182, 16, v221
	v_and_b32_e32 v183, 0xffff0000, v221
	v_lshlrev_b32_e32 v184, 16, v222
	v_and_b32_e32 v185, 0xffff0000, v222
	v_lshlrev_b32_e32 v186, 16, v223
	v_and_b32_e32 v187, 0xffff0000, v223
	v_pk_fma_f32 v[44:45], v[44:45], v[196:197], v[180:181]
	v_pk_fma_f32 v[46:47], v[46:47], v[198:199], v[182:183]
	v_pk_fma_f32 v[40:41], v[40:41], v[200:201], v[184:185]
	v_pk_fma_f32 v[42:43], v[42:43], v[202:203], v[186:187]
	v_cvt_pk_bf16_f32 v43, v42, v43
	v_cvt_pk_bf16_f32 v42, v40, v41
	v_cvt_pk_bf16_f32 v41, v46, v47
	v_cvt_pk_bf16_f32 v40, v44, v45
	v_add_u32_e32 v151, 0x90000, v148
	global_store_dwordx4 v151, v[40:43], s[74:75]
	v_lshlrev_b32_e32 v180, 16, v224
	v_and_b32_e32 v181, 0xffff0000, v224
	v_lshlrev_b32_e32 v182, 16, v225
	v_and_b32_e32 v183, 0xffff0000, v225
	v_lshlrev_b32_e32 v184, 16, v226
	v_and_b32_e32 v185, 0xffff0000, v226
	v_lshlrev_b32_e32 v186, 16, v227
	v_and_b32_e32 v187, 0xffff0000, v227
	v_pk_fma_f32 v[36:37], v[36:37], v[204:205], v[180:181]
	v_pk_fma_f32 v[38:39], v[38:39], v[206:207], v[182:183]
	v_pk_fma_f32 v[32:33], v[32:33], v[208:209], v[184:185]
	v_pk_fma_f32 v[34:35], v[34:35], v[210:211], v[186:187]
	v_cvt_pk_bf16_f32 v35, v34, v35
	v_cvt_pk_bf16_f32 v34, v32, v33
	v_cvt_pk_bf16_f32 v33, v38, v39
	v_cvt_pk_bf16_f32 v32, v36, v37
	v_add_u32_e32 v151, 0x90000, v148
	global_store_dwordx4 v151, v[32:35], s[74:75] offset:256
	v_lshlrev_b32_e32 v180, 16, v164
	v_and_b32_e32 v181, 0xffff0000, v164
	v_lshlrev_b32_e32 v182, 16, v165
	v_and_b32_e32 v183, 0xffff0000, v165
	v_lshlrev_b32_e32 v184, 16, v166
	v_and_b32_e32 v185, 0xffff0000, v166
	v_lshlrev_b32_e32 v186, 16, v167
	v_and_b32_e32 v187, 0xffff0000, v167
	v_pk_fma_f32 v[28:29], v[28:29], v[196:197], v[180:181]
	v_pk_fma_f32 v[30:31], v[30:31], v[198:199], v[182:183]
	v_pk_fma_f32 v[24:25], v[24:25], v[200:201], v[184:185]
	v_pk_fma_f32 v[26:27], v[26:27], v[202:203], v[186:187]
	v_cvt_pk_bf16_f32 v27, v26, v27
	v_cvt_pk_bf16_f32 v26, v24, v25
	v_cvt_pk_bf16_f32 v25, v30, v31
	v_cvt_pk_bf16_f32 v24, v28, v29
	v_add_u32_e32 v151, 0xa0000, v148
	global_store_dwordx4 v151, v[24:27], s[74:75]
	v_lshlrev_b32_e32 v180, 16, v168
	v_and_b32_e32 v181, 0xffff0000, v168
	v_lshlrev_b32_e32 v182, 16, v169
	v_and_b32_e32 v183, 0xffff0000, v169
	v_lshlrev_b32_e32 v184, 16, v170
	v_and_b32_e32 v185, 0xffff0000, v170
	v_lshlrev_b32_e32 v186, 16, v171
	v_and_b32_e32 v187, 0xffff0000, v171
	v_pk_fma_f32 v[20:21], v[20:21], v[204:205], v[180:181]
	v_pk_fma_f32 v[22:23], v[22:23], v[206:207], v[182:183]
	v_pk_fma_f32 v[16:17], v[16:17], v[208:209], v[184:185]
	v_pk_fma_f32 v[18:19], v[18:19], v[210:211], v[186:187]
	v_cvt_pk_bf16_f32 v19, v18, v19
	v_cvt_pk_bf16_f32 v18, v16, v17
	v_cvt_pk_bf16_f32 v17, v22, v23
	v_cvt_pk_bf16_f32 v16, v20, v21
	v_add_u32_e32 v151, 0xa0000, v148
	global_store_dwordx4 v151, v[16:19], s[74:75] offset:256
	v_lshlrev_b32_e32 v180, 16, v172
	v_and_b32_e32 v181, 0xffff0000, v172
	v_lshlrev_b32_e32 v182, 16, v173
	v_and_b32_e32 v183, 0xffff0000, v173
	v_lshlrev_b32_e32 v184, 16, v174
	v_and_b32_e32 v185, 0xffff0000, v174
	v_lshlrev_b32_e32 v186, 16, v175
	v_and_b32_e32 v187, 0xffff0000, v175
	v_pk_fma_f32 v[12:13], v[12:13], v[196:197], v[180:181]
	v_pk_fma_f32 v[14:15], v[14:15], v[198:199], v[182:183]
	v_pk_fma_f32 v[8:9], v[8:9], v[200:201], v[184:185]
	v_pk_fma_f32 v[10:11], v[10:11], v[202:203], v[186:187]
	v_cvt_pk_bf16_f32 v11, v10, v11
	v_cvt_pk_bf16_f32 v10, v8, v9
	v_cvt_pk_bf16_f32 v9, v14, v15
	v_cvt_pk_bf16_f32 v8, v12, v13
	v_add_u32_e32 v151, 0xb0000, v148
	global_store_dwordx4 v151, v[8:11], s[74:75]
	v_lshlrev_b32_e32 v180, 16, v176
	v_and_b32_e32 v181, 0xffff0000, v176
	v_lshlrev_b32_e32 v182, 16, v177
	v_and_b32_e32 v183, 0xffff0000, v177
	v_lshlrev_b32_e32 v184, 16, v178
	v_and_b32_e32 v185, 0xffff0000, v178
	v_lshlrev_b32_e32 v186, 16, v179
	v_and_b32_e32 v187, 0xffff0000, v179
	v_pk_fma_f32 v[4:5], v[4:5], v[204:205], v[180:181]
	v_pk_fma_f32 v[6:7], v[6:7], v[206:207], v[182:183]
	v_pk_fma_f32 v[0:1], v[0:1], v[208:209], v[184:185]
	v_pk_fma_f32 v[2:3], v[2:3], v[210:211], v[186:187]
	v_cvt_pk_bf16_f32 v3, v2, v3
	v_cvt_pk_bf16_f32 v2, v0, v1
	v_cvt_pk_bf16_f32 v1, v6, v7
	v_cvt_pk_bf16_f32 v0, v4, v5
	v_add_u32_e32 v151, 0xb0000, v148
	global_store_dwordx4 v151, v[0:3], s[74:75] offset:256

.LBB0_1090:
	ds_read_b128 v[148:151], v163
	ds_read_b128 v[166:169], v163 offset:1024
	ds_read_b128 v[170:173], v163 offset:2048
	ds_read_b128 v[174:177], v163 offset:3072
	s_add_u32 s18, s16, 0xfff80080
	s_addc_u32 s19, s17, -1
	s_cmp_eq_u32 s35, 28
	s_cselect_b32 s21, s1, s19
	s_cselect_b32 s20, s15, s18
	s_cselect_b32 s19, s22, s34
	s_cselect_b32 s18, s23, s33
	v_lshl_add_u64 v[142:143], s[16:17], 0, v[134:135]
	s_add_i32 m0, s38, 0xc000
	ds_read_b128 v[178:181], v164
	ds_read_b128 v[182:185], v164 offset:1024
	ds_read_b128 v[186:189], v164 offset:2048
	ds_read_b128 v[196:199], v164 offset:3072
	ds_read_b128 v[200:203], v164 offset:4096
	ds_read_b128 v[204:207], v164 offset:5120
	ds_read_b128 v[208:211], v164 offset:6144
	ds_read_b128 v[212:215], v164 offset:7168
	global_load_lds_dwordx4 v[142:143], off
	s_add_i32 m0, s38, 0xe000
	v_lshl_add_u64 v[142:143], s[16:17], 0, v[136:137]
	global_load_lds_dwordx4 v[142:143], off
	s_waitcnt lgkmcnt(8)
	s_barrier
	s_waitcnt lgkmcnt(0)
	v_mfma_f32_16x16x32_bf16 v[124:127], v[148:151], v[178:181], v[124:127]
	v_mfma_f32_16x16x32_bf16 v[120:123], v[170:173], v[178:181], v[120:123]
	v_mfma_f32_16x16x32_bf16 v[108:111], v[148:151], v[186:189], v[108:111]
	v_mfma_f32_16x16x32_bf16 v[104:107], v[170:173], v[186:189], v[104:107]
	v_mfma_f32_16x16x32_bf16 v[92:95], v[148:151], v[200:203], v[92:95]
	v_mfma_f32_16x16x32_bf16 v[88:91], v[170:173], v[200:203], v[88:91]
	v_mfma_f32_16x16x32_bf16 v[76:79], v[148:151], v[208:211], v[76:79]
	v_mfma_f32_16x16x32_bf16 v[72:75], v[170:173], v[208:211], v[72:75]
	v_mfma_f32_16x16x32_bf16 v[124:127], v[166:169], v[182:185], v[124:127]
	v_mfma_f32_16x16x32_bf16 v[120:123], v[174:177], v[182:185], v[120:123]
	v_mfma_f32_16x16x32_bf16 v[108:111], v[166:169], v[196:199], v[108:111]
	v_mfma_f32_16x16x32_bf16 v[104:107], v[174:177], v[196:199], v[104:107]
	v_mfma_f32_16x16x32_bf16 v[92:95], v[166:169], v[204:207], v[92:95]
	v_mfma_f32_16x16x32_bf16 v[88:91], v[174:177], v[204:207], v[88:91]
	v_mfma_f32_16x16x32_bf16 v[76:79], v[166:169], v[212:215], v[76:79]
	v_mfma_f32_16x16x32_bf16 v[72:75], v[174:177], v[212:215], v[72:75]
	s_barrier
	s_add_i32 s49, s65, s37
	v_lshl_add_u64 v[142:143], s[18:19], 0, v[128:129]
	s_mov_b32 m0, s49
	ds_read_b128 v[216:219], v165
	ds_read_b128 v[220:223], v165 offset:1024
	ds_read_b128 v[224:227], v165 offset:2048
	ds_read_b128 v[228:231], v165 offset:3072
	global_load_lds_dwordx4 v[142:143], off
	s_add_i32 m0, s49, 0x2000
	v_lshl_add_u64 v[152:153], s[18:19], 0, v[130:131]
	global_load_lds_dwordx4 v[152:153], off
	s_barrier
	s_waitcnt lgkmcnt(0)
	v_mfma_f32_16x16x32_bf16 v[116:119], v[216:219], v[178:181], v[116:119]
	v_mfma_f32_16x16x32_bf16 v[112:115], v[224:227], v[178:181], v[112:115]
	v_mfma_f32_16x16x32_bf16 v[100:103], v[216:219], v[186:189], v[100:103]
	v_mfma_f32_16x16x32_bf16 v[96:99], v[224:227], v[186:189], v[96:99]
	v_mfma_f32_16x16x32_bf16 v[84:87], v[216:219], v[200:203], v[84:87]
	v_mfma_f32_16x16x32_bf16 v[80:83], v[224:227], v[200:203], v[80:83]
	v_mfma_f32_16x16x32_bf16 v[68:71], v[216:219], v[208:211], v[68:71]
	v_mfma_f32_16x16x32_bf16 v[64:67], v[224:227], v[208:211], v[64:67]
	v_mfma_f32_16x16x32_bf16 v[116:119], v[220:223], v[182:185], v[116:119]
	v_mfma_f32_16x16x32_bf16 v[112:115], v[228:231], v[182:185], v[112:115]
	v_mfma_f32_16x16x32_bf16 v[100:103], v[220:223], v[196:199], v[100:103]
	v_mfma_f32_16x16x32_bf16 v[96:99], v[228:231], v[196:199], v[96:99]
	v_mfma_f32_16x16x32_bf16 v[84:87], v[220:223], v[204:207], v[84:87]
	v_mfma_f32_16x16x32_bf16 v[80:83], v[228:231], v[204:207], v[80:83]
	v_mfma_f32_16x16x32_bf16 v[68:71], v[220:223], v[212:215], v[68:71]
	v_mfma_f32_16x16x32_bf16 v[64:67], v[228:231], v[212:215], v[64:67]
	s_mov_b32 m0, s38
	v_lshl_add_u64 v[190:191], s[20:21], 0, v[128:129]
	s_barrier
	ds_read_b128 v[178:181], v164 offset:16384
	ds_read_b128 v[182:185], v164 offset:17408
	ds_read_b128 v[186:189], v164 offset:18432
	ds_read_b128 v[196:199], v164 offset:19456
	ds_read_b128 v[200:203], v164 offset:20480
	ds_read_b128 v[204:207], v164 offset:21504
	ds_read_b128 v[208:211], v164 offset:22528
	ds_read_b128 v[212:215], v164 offset:23552
	global_load_lds_dwordx4 v[190:191], off
	s_mov_b32 m0, s39
	v_lshl_add_u64 v[232:233], s[20:21], 0, v[130:131]
	global_load_lds_dwordx4 v[232:233], off
	s_barrier
	s_waitcnt lgkmcnt(0)
	v_mfma_f32_16x16x32_bf16 v[60:63], v[148:151], v[178:181], v[60:63]
	v_mfma_f32_16x16x32_bf16 v[56:59], v[170:173], v[178:181], v[56:59]
	v_mfma_f32_16x16x32_bf16 v[44:47], v[148:151], v[186:189], v[44:47]
	v_mfma_f32_16x16x32_bf16 v[40:43], v[170:173], v[186:189], v[40:43]
	v_mfma_f32_16x16x32_bf16 v[28:31], v[148:151], v[200:203], v[28:31]
	v_mfma_f32_16x16x32_bf16 v[24:27], v[170:173], v[200:203], v[24:27]
	v_mfma_f32_16x16x32_bf16 v[12:15], v[148:151], v[208:211], v[12:15]
	v_mfma_f32_16x16x32_bf16 v[8:11], v[170:173], v[208:211], v[8:11]
	v_mfma_f32_16x16x32_bf16 v[60:63], v[166:169], v[182:185], v[60:63]
	v_mfma_f32_16x16x32_bf16 v[56:59], v[174:177], v[182:185], v[56:59]
	v_mfma_f32_16x16x32_bf16 v[44:47], v[166:169], v[196:199], v[44:47]
	v_mfma_f32_16x16x32_bf16 v[40:43], v[174:177], v[196:199], v[40:43]
	v_mfma_f32_16x16x32_bf16 v[28:31], v[166:169], v[204:207], v[28:31]
	v_mfma_f32_16x16x32_bf16 v[24:27], v[174:177], v[204:207], v[24:27]
	v_mfma_f32_16x16x32_bf16 v[12:15], v[166:169], v[212:215], v[12:15]
	v_mfma_f32_16x16x32_bf16 v[8:11], v[174:177], v[212:215], v[8:11]
	s_barrier
	s_add_u32 s80, s18, 0x80000
	s_addc_u32 s81, s19, 0
	s_add_i32 s49, s67, s37
	s_mov_b32 m0, s49
	v_lshl_add_u64 v[148:149], s[80:81], 0, v[128:129]
	global_load_lds_dwordx4 v[148:149], off
	s_add_i32 m0, s49, 0x2000
	v_lshl_add_u64 v[148:149], s[80:81], 0, v[130:131]
	global_load_lds_dwordx4 v[148:149], off
	s_waitcnt vmcnt(6)
	s_barrier
	v_mfma_f32_16x16x32_bf16 v[52:55], v[216:219], v[178:181], v[52:55]
	v_mfma_f32_16x16x32_bf16 v[48:51], v[224:227], v[178:181], v[48:51]
	v_mfma_f32_16x16x32_bf16 v[36:39], v[216:219], v[186:189], v[36:39]
	v_mfma_f32_16x16x32_bf16 v[32:35], v[224:227], v[186:189], v[32:35]
	v_mfma_f32_16x16x32_bf16 v[20:23], v[216:219], v[200:203], v[20:23]
	v_mfma_f32_16x16x32_bf16 v[16:19], v[224:227], v[200:203], v[16:19]
	v_mfma_f32_16x16x32_bf16 v[4:7], v[216:219], v[208:211], v[4:7]
	v_mfma_f32_16x16x32_bf16 v[0:3], v[224:227], v[208:211], v[0:3]
	v_mfma_f32_16x16x32_bf16 v[52:55], v[220:223], v[182:185], v[52:55]
	v_mfma_f32_16x16x32_bf16 v[48:51], v[228:231], v[182:185], v[48:51]
	v_mfma_f32_16x16x32_bf16 v[36:39], v[220:223], v[196:199], v[36:39]
	v_mfma_f32_16x16x32_bf16 v[32:35], v[228:231], v[196:199], v[32:35]
	v_mfma_f32_16x16x32_bf16 v[20:23], v[220:223], v[204:207], v[20:23]
	v_mfma_f32_16x16x32_bf16 v[16:19], v[228:231], v[204:207], v[16:19]
	v_mfma_f32_16x16x32_bf16 v[4:7], v[220:223], v[212:215], v[4:7]
	v_mfma_f32_16x16x32_bf16 v[0:3], v[228:231], v[212:215], v[0:3]
	s_add_i32 s49, 0, 0x18000
	v_add_u32_e32 v132, s49, v154
	s_barrier
	ds_read_b128 v[148:151], v132
	ds_read_b128 v[166:169], v132 offset:1024
	ds_read_b128 v[170:173], v132 offset:2048
	ds_read_b128 v[174:177], v132 offset:3072
	s_add_u32 s20, s20, 0x80000
	s_addc_u32 s21, s21, 0
	s_mov_b32 m0, s56
	v_lshl_add_u64 v[216:217], s[20:21], 0, v[128:129]
	ds_read_b128 v[178:181], v164 offset:32768
	ds_read_b128 v[182:185], v164 offset:33792
	ds_read_b128 v[186:189], v164 offset:34816
	ds_read_b128 v[196:199], v164 offset:35840
	ds_read_b128 v[200:203], v164 offset:36864
	ds_read_b128 v[204:207], v164 offset:37888
	ds_read_b128 v[208:211], v164 offset:38912
	ds_read_b128 v[212:215], v164 offset:39936
	global_load_lds_dwordx4 v[216:217], off
	s_mov_b32 m0, s57
	v_lshl_add_u64 v[216:217], s[20:21], 0, v[130:131]
	global_load_lds_dwordx4 v[216:217], off
	s_waitcnt lgkmcnt(8)
	s_barrier
	s_waitcnt lgkmcnt(0)
	v_mfma_f32_16x16x32_bf16 v[124:127], v[148:151], v[178:181], v[124:127]
	v_mfma_f32_16x16x32_bf16 v[120:123], v[170:173], v[178:181], v[120:123]
	v_mfma_f32_16x16x32_bf16 v[108:111], v[148:151], v[186:189], v[108:111]
	v_mfma_f32_16x16x32_bf16 v[104:107], v[170:173], v[186:189], v[104:107]
	v_mfma_f32_16x16x32_bf16 v[92:95], v[148:151], v[200:203], v[92:95]
	v_mfma_f32_16x16x32_bf16 v[88:91], v[170:173], v[200:203], v[88:91]
	v_mfma_f32_16x16x32_bf16 v[76:79], v[148:151], v[208:211], v[76:79]
	v_mfma_f32_16x16x32_bf16 v[72:75], v[170:173], v[208:211], v[72:75]
	v_mfma_f32_16x16x32_bf16 v[124:127], v[166:169], v[182:185], v[124:127]
	v_mfma_f32_16x16x32_bf16 v[120:123], v[174:177], v[182:185], v[120:123]
	v_mfma_f32_16x16x32_bf16 v[108:111], v[166:169], v[196:199], v[108:111]
	v_mfma_f32_16x16x32_bf16 v[104:107], v[174:177], v[196:199], v[104:107]
	v_mfma_f32_16x16x32_bf16 v[92:95], v[166:169], v[204:207], v[92:95]
	v_mfma_f32_16x16x32_bf16 v[88:91], v[174:177], v[204:207], v[88:91]
	v_mfma_f32_16x16x32_bf16 v[76:79], v[166:169], v[212:215], v[76:79]
	v_mfma_f32_16x16x32_bf16 v[72:75], v[174:177], v[212:215], v[72:75]
	s_barrier
	s_add_i32 s20, 0, 0x1c000
	s_add_i32 s21, s49, s37
	v_add_u32_e32 v132, s20, v154
	v_lshl_add_u64 v[142:143], v[142:143], 0, s[46:47]
	s_mov_b32 m0, s21
	ds_read_b128 v[216:219], v132
	ds_read_b128 v[220:223], v132 offset:1024
	ds_read_b128 v[224:227], v132 offset:2048
	ds_read_b128 v[228:231], v132 offset:3072
	global_load_lds_dwordx4 v[142:143], off
	s_add_i32 m0, s21, 0x2000
	v_lshl_add_u64 v[142:143], v[152:153], 0, s[46:47]
	global_load_lds_dwordx4 v[142:143], off
	s_barrier
	s_waitcnt lgkmcnt(0)
	v_mfma_f32_16x16x32_bf16 v[116:119], v[216:219], v[178:181], v[116:119]
	v_mfma_f32_16x16x32_bf16 v[112:115], v[224:227], v[178:181], v[112:115]
	v_mfma_f32_16x16x32_bf16 v[100:103], v[216:219], v[186:189], v[100:103]
	v_mfma_f32_16x16x32_bf16 v[96:99], v[224:227], v[186:189], v[96:99]
	v_mfma_f32_16x16x32_bf16 v[84:87], v[216:219], v[200:203], v[84:87]
	v_mfma_f32_16x16x32_bf16 v[80:83], v[224:227], v[200:203], v[80:83]
	v_mfma_f32_16x16x32_bf16 v[68:71], v[216:219], v[208:211], v[68:71]
	v_mfma_f32_16x16x32_bf16 v[64:67], v[224:227], v[208:211], v[64:67]
	v_mfma_f32_16x16x32_bf16 v[116:119], v[220:223], v[182:185], v[116:119]
	v_mfma_f32_16x16x32_bf16 v[112:115], v[228:231], v[182:185], v[112:115]
	v_mfma_f32_16x16x32_bf16 v[100:103], v[220:223], v[196:199], v[100:103]
	v_mfma_f32_16x16x32_bf16 v[96:99], v[228:231], v[196:199], v[96:99]
	v_mfma_f32_16x16x32_bf16 v[84:87], v[220:223], v[204:207], v[84:87]
	v_mfma_f32_16x16x32_bf16 v[80:83], v[228:231], v[204:207], v[80:83]
	v_mfma_f32_16x16x32_bf16 v[68:71], v[220:223], v[212:215], v[68:71]
	v_mfma_f32_16x16x32_bf16 v[64:67], v[228:231], v[212:215], v[64:67]
	s_mov_b32 m0, s60
	v_lshl_add_u64 v[142:143], v[190:191], 0, s[46:47]
	s_barrier
	ds_read_b128 v[178:181], v164 offset:49152
	ds_read_b128 v[182:185], v164 offset:50176
	ds_read_b128 v[186:189], v164 offset:51200
	ds_read_b128 v[196:199], v164 offset:52224
	ds_read_b128 v[200:203], v164 offset:53248
	ds_read_b128 v[204:207], v164 offset:54272
	ds_read_b128 v[208:211], v164 offset:55296
	ds_read_b128 v[212:215], v164 offset:56320
	global_load_lds_dwordx4 v[142:143], off
	s_mov_b32 m0, s61
	v_lshl_add_u64 v[142:143], v[232:233], 0, s[46:47]
	global_load_lds_dwordx4 v[142:143], off
	s_barrier
	s_waitcnt lgkmcnt(0)
	v_mfma_f32_16x16x32_bf16 v[60:63], v[148:151], v[178:181], v[60:63]
	v_mfma_f32_16x16x32_bf16 v[56:59], v[170:173], v[178:181], v[56:59]
	v_mfma_f32_16x16x32_bf16 v[44:47], v[148:151], v[186:189], v[44:47]
	v_mfma_f32_16x16x32_bf16 v[40:43], v[170:173], v[186:189], v[40:43]
	v_mfma_f32_16x16x32_bf16 v[28:31], v[148:151], v[200:203], v[28:31]
	v_mfma_f32_16x16x32_bf16 v[24:27], v[170:173], v[200:203], v[24:27]
	v_mfma_f32_16x16x32_bf16 v[12:15], v[148:151], v[208:211], v[12:15]
	v_mfma_f32_16x16x32_bf16 v[8:11], v[170:173], v[208:211], v[8:11]
	v_mfma_f32_16x16x32_bf16 v[60:63], v[166:169], v[182:185], v[60:63]
	v_mfma_f32_16x16x32_bf16 v[56:59], v[174:177], v[182:185], v[56:59]
	v_mfma_f32_16x16x32_bf16 v[44:47], v[166:169], v[196:199], v[44:47]
	v_mfma_f32_16x16x32_bf16 v[40:43], v[174:177], v[196:199], v[40:43]
	v_mfma_f32_16x16x32_bf16 v[28:31], v[166:169], v[204:207], v[28:31]
	v_mfma_f32_16x16x32_bf16 v[24:27], v[174:177], v[204:207], v[24:27]
	v_mfma_f32_16x16x32_bf16 v[12:15], v[166:169], v[212:215], v[12:15]
	v_mfma_f32_16x16x32_bf16 v[8:11], v[174:177], v[212:215], v[8:11]
	s_barrier
	s_add_u32 s18, s18, 0x80080
	s_addc_u32 s19, s19, 0
	s_add_i32 s20, s20, s37
	s_mov_b32 m0, s20
	v_lshl_add_u64 v[142:143], s[18:19], 0, v[128:129]
	global_load_lds_dwordx4 v[142:143], off
	s_add_i32 m0, s20, 0x2000
	v_lshl_add_u64 v[142:143], s[18:19], 0, v[130:131]
	global_load_lds_dwordx4 v[142:143], off
	s_waitcnt vmcnt(6)
	s_barrier
	v_mfma_f32_16x16x32_bf16 v[52:55], v[216:219], v[178:181], v[52:55]
	v_mfma_f32_16x16x32_bf16 v[48:51], v[224:227], v[178:181], v[48:51]
	v_mfma_f32_16x16x32_bf16 v[36:39], v[216:219], v[186:189], v[36:39]
	v_mfma_f32_16x16x32_bf16 v[32:35], v[224:227], v[186:189], v[32:35]
	v_mfma_f32_16x16x32_bf16 v[20:23], v[216:219], v[200:203], v[20:23]
	v_mfma_f32_16x16x32_bf16 v[16:19], v[224:227], v[200:203], v[16:19]
	v_mfma_f32_16x16x32_bf16 v[4:7], v[216:219], v[208:211], v[4:7]
	v_mfma_f32_16x16x32_bf16 v[0:3], v[224:227], v[208:211], v[0:3]
	v_mfma_f32_16x16x32_bf16 v[52:55], v[220:223], v[182:185], v[52:55]
	v_mfma_f32_16x16x32_bf16 v[48:51], v[228:231], v[182:185], v[48:51]
	v_mfma_f32_16x16x32_bf16 v[36:39], v[220:223], v[196:199], v[36:39]
	v_mfma_f32_16x16x32_bf16 v[32:35], v[228:231], v[196:199], v[32:35]
	v_mfma_f32_16x16x32_bf16 v[20:23], v[220:223], v[204:207], v[20:23]
	v_mfma_f32_16x16x32_bf16 v[16:19], v[228:231], v[204:207], v[16:19]
	v_mfma_f32_16x16x32_bf16 v[4:7], v[220:223], v[212:215], v[4:7]
	v_mfma_f32_16x16x32_bf16 v[0:3], v[228:231], v[212:215], v[0:3]
	s_add_i32 s35, s35, 2
	s_add_u32 s16, s16, 0x100
	s_addc_u32 s17, s17, 0
	s_add_u32 s33, s33, 0x100
	s_addc_u32 s34, s34, 0
	s_cmp_gt_u32 s35, 29
	s_barrier
	s_cbranch_scc0 .LBB0_1090
	s_lshl_b32 s34, s14, 8
	s_add_i32 s34, s34, s59
	v_or_b32_e32 v150, s34, v147
	v_lshl_or_b32 v142, s0, 8, v162
	v_ashrrev_i32_e32 v151, 31, v150
	v_cmp_gt_i32_e64 s[18:19], s58, v150
	v_cmp_lt_i32_e64 s[16:17], s68, v150
	v_lshlrev_b64 v[148:149], 8, v[150:151]
	v_cmp_lt_i32_e64 s[14:15], s76, v142
	v_add_u32_e32 v132, 0xfffff700, v142
	v_add_u32_e32 v174, 0xfffff710, v142
	v_add_u32_e32 v172, 0xfffff701, v142
	v_add_u32_e32 v170, 0xfffff711, v142
	v_add_u32_e32 v169, 0xfffff702, v142
	v_add_u32_e32 v168, 0xfffff712, v142
	v_add_u32_e32 v167, 0xfffff703, v142
	v_add_u32_e32 v166, 0xfffff713, v142
	v_lshl_add_u64 v[152:153], v[150:151], 1, s[24:25]
	s_and_saveexec_b64 s[0:1], s[14:15]
	s_xor_b64 s[0:1], exec, s[0:1]
	s_cbranch_execz .LBB0_1095
	v_bfe_u32 v143, v124, 16, 1
	v_add3_u32 v143, v124, v143, s77
	v_mad_u64_u32 v[176:177], s[20:21], v132, s66, v[152:153]
	global_store_short_d16_hi v[176:177], v143, off
	v_bfe_u32 v143, v120, 16, 1
	v_add3_u32 v143, v120, v143, s77
	v_mad_u64_u32 v[176:177], s[20:21], v174, s66, v[152:153]
	global_store_short_d16_hi v[176:177], v143, off
	v_bfe_u32 v143, v125, 16, 1
	v_add3_u32 v143, v125, v143, s77
	v_mad_u64_u32 v[176:177], s[20:21], v172, s66, v[152:153]
	global_store_short_d16_hi v[176:177], v143, off
	v_bfe_u32 v143, v121, 16, 1
	v_add3_u32 v143, v121, v143, s77
	v_mad_u64_u32 v[176:177], s[20:21], v170, s66, v[152:153]
	global_store_short_d16_hi v[176:177], v143, off
	v_bfe_u32 v143, v126, 16, 1
	v_add3_u32 v143, v126, v143, s77
	v_mad_u64_u32 v[176:177], s[20:21], v169, s66, v[152:153]
	global_store_short_d16_hi v[176:177], v143, off
	v_bfe_u32 v143, v122, 16, 1
	v_add3_u32 v143, v122, v143, s77
	v_mad_u64_u32 v[176:177], s[20:21], v168, s66, v[152:153]
	global_store_short_d16_hi v[176:177], v143, off
	v_bfe_u32 v143, v127, 16, 1
	v_add3_u32 v143, v127, v143, s77
	v_mad_u64_u32 v[176:177], s[20:21], v167, s66, v[152:153]
	global_store_short_d16_hi v[176:177], v143, off
	v_bfe_u32 v143, v123, 16, 1
	v_add3_u32 v143, v123, v143, s77
	v_mad_u64_u32 v[176:177], s[20:21], v166, s66, v[152:153]
	global_store_short_d16_hi v[176:177], v143, off
	s_and_saveexec_b64 s[20:21], s[18:19]
	s_cbranch_execz .LBB0_1094
	v_lshl_add_u64 v[176:177], v[148:149], 2, s[44:45]
	v_lshl_add_u64 v[176:177], v[132:133], 2, v[176:177]
	global_store_dwordx4 v[176:177], v[124:127], off
	global_store_dwordx4 v[176:177], v[120:123], off offset:64

.LBB0_1346:
	ds_read_b128 v[148:151], v158
	ds_read_b128 v[152:155], v158 offset:1024
	ds_read_b128 v[162:165], v158 offset:2048
	ds_read_b128 v[166:169], v158 offset:3072
	s_add_u32 s20, s38, 0xfff80080
	s_addc_u32 s21, s39, -1
	s_cmp_eq_u32 s61, 28
	s_cselect_b32 s21, s17, s21
	s_cselect_b32 s20, s57, s20
	s_cselect_b32 s45, s15, s60
	s_cselect_b32 s44, s58, s59
	v_lshl_add_u64 v[190:191], s[38:39], 0, v[136:137]
	s_add_i32 m0, s37, 0xc000
	ds_read_b128 v[170:173], v159
	ds_read_b128 v[174:177], v159 offset:1024
	ds_read_b128 v[178:181], v159 offset:2048
	ds_read_b128 v[182:185], v159 offset:3072
	ds_read_b128 v[186:189], v159 offset:4096
	ds_read_b128 v[196:199], v159 offset:5120
	ds_read_b128 v[200:203], v159 offset:6144
	ds_read_b128 v[204:207], v159 offset:7168
	global_load_lds_dwordx4 v[190:191], off
	s_add_i32 m0, s37, 0xe000
	v_lshl_add_u64 v[190:191], s[38:39], 0, v[138:139]
	global_load_lds_dwordx4 v[190:191], off
	s_waitcnt lgkmcnt(8)
	s_barrier
	s_waitcnt lgkmcnt(0)
	v_mfma_f32_16x16x32_bf16 v[124:127], v[148:151], v[170:173], v[124:127]
	v_mfma_f32_16x16x32_bf16 v[120:123], v[162:165], v[170:173], v[120:123]
	v_mfma_f32_16x16x32_bf16 v[108:111], v[148:151], v[178:181], v[108:111]
	v_mfma_f32_16x16x32_bf16 v[104:107], v[162:165], v[178:181], v[104:107]
	v_mfma_f32_16x16x32_bf16 v[92:95], v[148:151], v[186:189], v[92:95]
	v_mfma_f32_16x16x32_bf16 v[88:91], v[162:165], v[186:189], v[88:91]
	v_mfma_f32_16x16x32_bf16 v[76:79], v[148:151], v[200:203], v[76:79]
	v_mfma_f32_16x16x32_bf16 v[72:75], v[162:165], v[200:203], v[72:75]
	v_mfma_f32_16x16x32_bf16 v[124:127], v[152:155], v[174:177], v[124:127]
	v_mfma_f32_16x16x32_bf16 v[120:123], v[166:169], v[174:177], v[120:123]
	v_mfma_f32_16x16x32_bf16 v[108:111], v[152:155], v[182:185], v[108:111]
	v_mfma_f32_16x16x32_bf16 v[104:107], v[166:169], v[182:185], v[104:107]
	v_mfma_f32_16x16x32_bf16 v[92:95], v[152:155], v[196:199], v[92:95]
	v_mfma_f32_16x16x32_bf16 v[88:91], v[166:169], v[196:199], v[88:91]
	v_mfma_f32_16x16x32_bf16 v[76:79], v[152:155], v[204:207], v[76:79]
	v_mfma_f32_16x16x32_bf16 v[72:75], v[166:169], v[204:207], v[72:75]
	s_barrier
	s_add_i32 s62, s53, s23
	v_lshl_add_u64 v[190:191], s[44:45], 0, v[132:133]
	s_mov_b32 m0, s62
	ds_read_b128 v[208:211], v160
	ds_read_b128 v[212:215], v160 offset:1024
	ds_read_b128 v[216:219], v160 offset:2048
	ds_read_b128 v[220:223], v160 offset:3072
	global_load_lds_dwordx4 v[190:191], off
	s_add_i32 m0, s62, 0x2000
	v_lshl_add_u64 v[224:225], s[44:45], 0, v[128:129]
	global_load_lds_dwordx4 v[224:225], off
	s_barrier
	s_waitcnt lgkmcnt(0)
	v_mfma_f32_16x16x32_bf16 v[116:119], v[208:211], v[170:173], v[116:119]
	v_mfma_f32_16x16x32_bf16 v[112:115], v[216:219], v[170:173], v[112:115]
	v_mfma_f32_16x16x32_bf16 v[100:103], v[208:211], v[178:181], v[100:103]
	v_mfma_f32_16x16x32_bf16 v[96:99], v[216:219], v[178:181], v[96:99]
	v_mfma_f32_16x16x32_bf16 v[84:87], v[208:211], v[186:189], v[84:87]
	v_mfma_f32_16x16x32_bf16 v[80:83], v[216:219], v[186:189], v[80:83]
	v_mfma_f32_16x16x32_bf16 v[68:71], v[208:211], v[200:203], v[68:71]
	v_mfma_f32_16x16x32_bf16 v[64:67], v[216:219], v[200:203], v[64:67]
	v_mfma_f32_16x16x32_bf16 v[116:119], v[212:215], v[174:177], v[116:119]
	v_mfma_f32_16x16x32_bf16 v[112:115], v[220:223], v[174:177], v[112:115]
	v_mfma_f32_16x16x32_bf16 v[100:103], v[212:215], v[182:185], v[100:103]
	v_mfma_f32_16x16x32_bf16 v[96:99], v[220:223], v[182:185], v[96:99]
	v_mfma_f32_16x16x32_bf16 v[84:87], v[212:215], v[196:199], v[84:87]
	v_mfma_f32_16x16x32_bf16 v[80:83], v[220:223], v[196:199], v[80:83]
	v_mfma_f32_16x16x32_bf16 v[68:71], v[212:215], v[204:207], v[68:71]
	v_mfma_f32_16x16x32_bf16 v[64:67], v[220:223], v[204:207], v[64:67]
	s_mov_b32 m0, s37
	v_lshl_add_u64 v[226:227], s[20:21], 0, v[134:135]
	s_barrier
	ds_read_b128 v[170:173], v159 offset:16384
	ds_read_b128 v[174:177], v159 offset:17408
	ds_read_b128 v[178:181], v159 offset:18432
	ds_read_b128 v[182:185], v159 offset:19456
	ds_read_b128 v[186:189], v159 offset:20480
	ds_read_b128 v[196:199], v159 offset:21504
	ds_read_b128 v[200:203], v159 offset:22528
	ds_read_b128 v[204:207], v159 offset:23552
	global_load_lds_dwordx4 v[226:227], off
	s_mov_b32 m0, s47
	v_lshl_add_u64 v[228:229], s[20:21], 0, v[130:131]
	global_load_lds_dwordx4 v[228:229], off
	s_barrier
	s_waitcnt lgkmcnt(0)
	v_mfma_f32_16x16x32_bf16 v[60:63], v[148:151], v[170:173], v[60:63]
	v_mfma_f32_16x16x32_bf16 v[56:59], v[162:165], v[170:173], v[56:59]
	v_mfma_f32_16x16x32_bf16 v[44:47], v[148:151], v[178:181], v[44:47]
	v_mfma_f32_16x16x32_bf16 v[40:43], v[162:165], v[178:181], v[40:43]
	v_mfma_f32_16x16x32_bf16 v[28:31], v[148:151], v[186:189], v[28:31]
	v_mfma_f32_16x16x32_bf16 v[24:27], v[162:165], v[186:189], v[24:27]
	v_mfma_f32_16x16x32_bf16 v[12:15], v[148:151], v[200:203], v[12:15]
	v_mfma_f32_16x16x32_bf16 v[8:11], v[162:165], v[200:203], v[8:11]
	v_mfma_f32_16x16x32_bf16 v[60:63], v[152:155], v[174:177], v[60:63]
	v_mfma_f32_16x16x32_bf16 v[56:59], v[166:169], v[174:177], v[56:59]
	v_mfma_f32_16x16x32_bf16 v[44:47], v[152:155], v[182:185], v[44:47]
	v_mfma_f32_16x16x32_bf16 v[40:43], v[166:169], v[182:185], v[40:43]
	v_mfma_f32_16x16x32_bf16 v[28:31], v[152:155], v[196:199], v[28:31]
	v_mfma_f32_16x16x32_bf16 v[24:27], v[166:169], v[196:199], v[24:27]
	v_mfma_f32_16x16x32_bf16 v[12:15], v[152:155], v[204:207], v[12:15]
	v_mfma_f32_16x16x32_bf16 v[8:11], v[166:169], v[204:207], v[8:11]
	s_barrier
	s_add_u32 s62, s44, 0x80000
	s_addc_u32 s63, s45, 0
	s_add_i32 s64, s55, s23
	s_mov_b32 m0, s64
	v_lshl_add_u64 v[148:149], s[62:63], 0, v[132:133]
	global_load_lds_dwordx4 v[148:149], off
	s_add_i32 m0, s64, 0x2000
	v_lshl_add_u64 v[148:149], s[62:63], 0, v[128:129]
	global_load_lds_dwordx4 v[148:149], off
	s_waitcnt vmcnt(6)
	s_barrier
	v_mfma_f32_16x16x32_bf16 v[52:55], v[208:211], v[170:173], v[52:55]
	v_mfma_f32_16x16x32_bf16 v[48:51], v[216:219], v[170:173], v[48:51]
	v_mfma_f32_16x16x32_bf16 v[36:39], v[208:211], v[178:181], v[36:39]
	v_mfma_f32_16x16x32_bf16 v[32:35], v[216:219], v[178:181], v[32:35]
	v_mfma_f32_16x16x32_bf16 v[20:23], v[208:211], v[186:189], v[20:23]
	v_mfma_f32_16x16x32_bf16 v[16:19], v[216:219], v[186:189], v[16:19]
	v_mfma_f32_16x16x32_bf16 v[4:7], v[208:211], v[200:203], v[4:7]
	v_mfma_f32_16x16x32_bf16 v[0:3], v[216:219], v[200:203], v[0:3]
	v_mfma_f32_16x16x32_bf16 v[52:55], v[212:215], v[174:177], v[52:55]
	v_mfma_f32_16x16x32_bf16 v[48:51], v[220:223], v[174:177], v[48:51]
	v_mfma_f32_16x16x32_bf16 v[36:39], v[212:215], v[182:185], v[36:39]
	v_mfma_f32_16x16x32_bf16 v[32:35], v[220:223], v[182:185], v[32:35]
	v_mfma_f32_16x16x32_bf16 v[20:23], v[212:215], v[196:199], v[20:23]
	v_mfma_f32_16x16x32_bf16 v[16:19], v[220:223], v[196:199], v[16:19]
	v_mfma_f32_16x16x32_bf16 v[4:7], v[212:215], v[204:207], v[4:7]
	v_mfma_f32_16x16x32_bf16 v[0:3], v[220:223], v[204:207], v[0:3]
	s_add_i32 s62, 0, 0x18000
	v_add_u32_e32 v161, s62, v147
	s_barrier
	ds_read_b128 v[148:151], v161
	ds_read_b128 v[152:155], v161 offset:1024
	ds_read_b128 v[162:165], v161 offset:2048
	ds_read_b128 v[166:169], v161 offset:3072
	s_add_u32 s20, s20, 0x80000
	s_addc_u32 s21, s21, 0
	s_mov_b32 m0, s48
	v_lshl_add_u64 v[208:209], s[20:21], 0, v[134:135]
	ds_read_b128 v[170:173], v159 offset:32768
	ds_read_b128 v[174:177], v159 offset:33792
	ds_read_b128 v[178:181], v159 offset:34816
	ds_read_b128 v[182:185], v159 offset:35840
	ds_read_b128 v[186:189], v159 offset:36864
	ds_read_b128 v[196:199], v159 offset:37888
	ds_read_b128 v[200:203], v159 offset:38912
	ds_read_b128 v[204:207], v159 offset:39936
	global_load_lds_dwordx4 v[208:209], off
	s_mov_b32 m0, s49
	v_lshl_add_u64 v[208:209], s[20:21], 0, v[130:131]
	global_load_lds_dwordx4 v[208:209], off
	s_waitcnt lgkmcnt(8)
	s_barrier
	s_waitcnt lgkmcnt(0)
	v_mfma_f32_16x16x32_bf16 v[124:127], v[148:151], v[170:173], v[124:127]
	v_mfma_f32_16x16x32_bf16 v[120:123], v[162:165], v[170:173], v[120:123]
	v_mfma_f32_16x16x32_bf16 v[108:111], v[148:151], v[178:181], v[108:111]
	v_mfma_f32_16x16x32_bf16 v[104:107], v[162:165], v[178:181], v[104:107]
	v_mfma_f32_16x16x32_bf16 v[92:95], v[148:151], v[186:189], v[92:95]
	v_mfma_f32_16x16x32_bf16 v[88:91], v[162:165], v[186:189], v[88:91]
	v_mfma_f32_16x16x32_bf16 v[76:79], v[148:151], v[200:203], v[76:79]
	v_mfma_f32_16x16x32_bf16 v[72:75], v[162:165], v[200:203], v[72:75]
	v_mfma_f32_16x16x32_bf16 v[124:127], v[152:155], v[174:177], v[124:127]
	v_mfma_f32_16x16x32_bf16 v[120:123], v[166:169], v[174:177], v[120:123]
	v_mfma_f32_16x16x32_bf16 v[108:111], v[152:155], v[182:185], v[108:111]
	v_mfma_f32_16x16x32_bf16 v[104:107], v[166:169], v[182:185], v[104:107]
	v_mfma_f32_16x16x32_bf16 v[92:95], v[152:155], v[196:199], v[92:95]
	v_mfma_f32_16x16x32_bf16 v[88:91], v[166:169], v[196:199], v[88:91]
	v_mfma_f32_16x16x32_bf16 v[76:79], v[152:155], v[204:207], v[76:79]
	v_mfma_f32_16x16x32_bf16 v[72:75], v[166:169], v[204:207], v[72:75]
	s_barrier
	s_add_i32 s63, 0, 0x1c000
	s_add_i32 s20, s62, s23
	v_add_u32_e32 v161, s63, v147
	v_lshl_add_u64 v[190:191], v[190:191], 0, s[10:11]
	s_mov_b32 m0, s20
	ds_read_b128 v[208:211], v161
	ds_read_b128 v[212:215], v161 offset:1024
	ds_read_b128 v[216:219], v161 offset:2048
	ds_read_b128 v[220:223], v161 offset:3072
	global_load_lds_dwordx4 v[190:191], off
	s_add_i32 m0, s20, 0x2000
	v_lshl_add_u64 v[190:191], v[224:225], 0, s[10:11]
	global_load_lds_dwordx4 v[190:191], off
	s_barrier
	s_waitcnt lgkmcnt(0)
	v_mfma_f32_16x16x32_bf16 v[116:119], v[208:211], v[170:173], v[116:119]
	v_mfma_f32_16x16x32_bf16 v[112:115], v[216:219], v[170:173], v[112:115]
	v_mfma_f32_16x16x32_bf16 v[100:103], v[208:211], v[178:181], v[100:103]
	v_mfma_f32_16x16x32_bf16 v[96:99], v[216:219], v[178:181], v[96:99]
	v_mfma_f32_16x16x32_bf16 v[84:87], v[208:211], v[186:189], v[84:87]
	v_mfma_f32_16x16x32_bf16 v[80:83], v[216:219], v[186:189], v[80:83]
	v_mfma_f32_16x16x32_bf16 v[68:71], v[208:211], v[200:203], v[68:71]
	v_mfma_f32_16x16x32_bf16 v[64:67], v[216:219], v[200:203], v[64:67]
	v_mfma_f32_16x16x32_bf16 v[116:119], v[212:215], v[174:177], v[116:119]
	v_mfma_f32_16x16x32_bf16 v[112:115], v[220:223], v[174:177], v[112:115]
	v_mfma_f32_16x16x32_bf16 v[100:103], v[212:215], v[182:185], v[100:103]
	v_mfma_f32_16x16x32_bf16 v[96:99], v[220:223], v[182:185], v[96:99]
	v_mfma_f32_16x16x32_bf16 v[84:87], v[212:215], v[196:199], v[84:87]
	v_mfma_f32_16x16x32_bf16 v[80:83], v[220:223], v[196:199], v[80:83]
	v_mfma_f32_16x16x32_bf16 v[68:71], v[212:215], v[204:207], v[68:71]
	v_mfma_f32_16x16x32_bf16 v[64:67], v[220:223], v[204:207], v[64:67]
	s_mov_b32 m0, s34
	v_lshl_add_u64 v[190:191], v[226:227], 0, s[10:11]
	s_barrier
	ds_read_b128 v[170:173], v159 offset:49152
	ds_read_b128 v[174:177], v159 offset:50176
	ds_read_b128 v[178:181], v159 offset:51200
	ds_read_b128 v[182:185], v159 offset:52224
	ds_read_b128 v[186:189], v159 offset:53248
	ds_read_b128 v[196:199], v159 offset:54272
	ds_read_b128 v[200:203], v159 offset:55296
	ds_read_b128 v[204:207], v159 offset:56320
	global_load_lds_dwordx4 v[190:191], off
	s_mov_b32 m0, s35
	v_lshl_add_u64 v[190:191], v[228:229], 0, s[10:11]
	global_load_lds_dwordx4 v[190:191], off
	s_barrier
	s_waitcnt lgkmcnt(0)
	v_mfma_f32_16x16x32_bf16 v[60:63], v[148:151], v[170:173], v[60:63]
	v_mfma_f32_16x16x32_bf16 v[56:59], v[162:165], v[170:173], v[56:59]
	v_mfma_f32_16x16x32_bf16 v[44:47], v[148:151], v[178:181], v[44:47]
	v_mfma_f32_16x16x32_bf16 v[40:43], v[162:165], v[178:181], v[40:43]
	v_mfma_f32_16x16x32_bf16 v[28:31], v[148:151], v[186:189], v[28:31]
	v_mfma_f32_16x16x32_bf16 v[24:27], v[162:165], v[186:189], v[24:27]
	v_mfma_f32_16x16x32_bf16 v[12:15], v[148:151], v[200:203], v[12:15]
	v_mfma_f32_16x16x32_bf16 v[8:11], v[162:165], v[200:203], v[8:11]
	v_mfma_f32_16x16x32_bf16 v[60:63], v[152:155], v[174:177], v[60:63]
	v_mfma_f32_16x16x32_bf16 v[56:59], v[166:169], v[174:177], v[56:59]
	v_mfma_f32_16x16x32_bf16 v[44:47], v[152:155], v[182:185], v[44:47]
	v_mfma_f32_16x16x32_bf16 v[40:43], v[166:169], v[182:185], v[40:43]
	v_mfma_f32_16x16x32_bf16 v[28:31], v[152:155], v[196:199], v[28:31]
	v_mfma_f32_16x16x32_bf16 v[24:27], v[166:169], v[196:199], v[24:27]
	v_mfma_f32_16x16x32_bf16 v[12:15], v[152:155], v[204:207], v[12:15]
	v_mfma_f32_16x16x32_bf16 v[8:11], v[166:169], v[204:207], v[8:11]
	s_barrier
	s_add_u32 s20, s44, 0x80080
	s_addc_u32 s21, s45, 0
	s_add_i32 s44, s63, s23
	s_mov_b32 m0, s44
	v_lshl_add_u64 v[148:149], s[20:21], 0, v[132:133]
	global_load_lds_dwordx4 v[148:149], off
	s_add_i32 m0, s44, 0x2000
	v_lshl_add_u64 v[148:149], s[20:21], 0, v[128:129]
	global_load_lds_dwordx4 v[148:149], off
	s_waitcnt vmcnt(6)
	s_barrier
	v_mfma_f32_16x16x32_bf16 v[52:55], v[208:211], v[170:173], v[52:55]
	v_mfma_f32_16x16x32_bf16 v[48:51], v[216:219], v[170:173], v[48:51]
	v_mfma_f32_16x16x32_bf16 v[36:39], v[208:211], v[178:181], v[36:39]
	v_mfma_f32_16x16x32_bf16 v[32:35], v[216:219], v[178:181], v[32:35]
	v_mfma_f32_16x16x32_bf16 v[20:23], v[208:211], v[186:189], v[20:23]
	v_mfma_f32_16x16x32_bf16 v[16:19], v[216:219], v[186:189], v[16:19]
	v_mfma_f32_16x16x32_bf16 v[4:7], v[208:211], v[200:203], v[4:7]
	v_mfma_f32_16x16x32_bf16 v[0:3], v[216:219], v[200:203], v[0:3]
	v_mfma_f32_16x16x32_bf16 v[52:55], v[212:215], v[174:177], v[52:55]
	v_mfma_f32_16x16x32_bf16 v[48:51], v[220:223], v[174:177], v[48:51]
	v_mfma_f32_16x16x32_bf16 v[36:39], v[212:215], v[182:185], v[36:39]
	v_mfma_f32_16x16x32_bf16 v[32:35], v[220:223], v[182:185], v[32:35]
	v_mfma_f32_16x16x32_bf16 v[20:23], v[212:215], v[196:199], v[20:23]
	v_mfma_f32_16x16x32_bf16 v[16:19], v[220:223], v[196:199], v[16:19]
	v_mfma_f32_16x16x32_bf16 v[4:7], v[212:215], v[204:207], v[4:7]
	v_mfma_f32_16x16x32_bf16 v[0:3], v[220:223], v[204:207], v[0:3]
	s_add_i32 s61, s61, 2
	s_add_u32 s38, s38, 0x100
	s_addc_u32 s39, s39, 0
	s_add_u32 s59, s59, 0x100
	s_addc_u32 s60, s60, 0
	s_cmp_gt_u32 s61, 29
	s_cbranch_scc0 .Lepi_nl_c_out
	s_cmp_lg_u32 s51, 64
	s_cbranch_scc1 .Lepi_nl_c_out
	s_lshl_b32 s15, s36, 8
	s_add_i32 s15, s15, s51
	v_or_b32_e32 v154, s15, v145
	s_add_i32 s17, s15, 0xffffe000
	v_lshl_or_b32 v150, s33, 8, v157
	s_lshr_b32 s17, s17, 12
	v_lshlrev_b32_e32 v148, 12, v154
	s_add_i32 s17, s17, 1
	s_cmp_gt_i32 s15, s56
	s_cselect_b32 s17, s17, 0
	s_mul_i32 s17, s17, s54
	v_lshl_add_u32 v148, v150, 1, v148
	s_add_u32 s20, s8, s17
	s_addc_u32 s21, s9, 0
	v_lshlrev_b32_e32 v149, 2, v150
	s_nop 0
	global_load_dwordx4 v[196:199], v149, s[20:21]
	global_load_dwordx4 v[200:203], v149, s[20:21] offset:16
	global_load_dwordx4 v[204:207], v149, s[20:21] offset:512
	global_load_dwordx4 v[208:211], v149, s[20:21] offset:528
	global_load_dwordx4 v[212:215], v148, s[74:75]
	global_load_dwordx4 v[216:219], v148, s[74:75] offset:256
	v_add_u32_e32 v151, 0x10000, v148
	global_load_dwordx4 v[220:223], v151, s[74:75]
	global_load_dwordx4 v[224:227], v151, s[74:75] offset:256
	v_add_u32_e32 v151, 0x20000, v148
	global_load_dwordx4 v[164:167], v151, s[74:75]
	global_load_dwordx4 v[168:171], v151, s[74:75] offset:256
	v_add_u32_e32 v151, 0x30000, v148
	global_load_dwordx4 v[172:175], v151, s[74:75]
	global_load_dwordx4 v[176:179], v151, s[74:75] offset:256
	s_waitcnt vmcnt(0)
	v_lshlrev_b32_e32 v180, 16, v212
	v_and_b32_e32 v181, 0xffff0000, v212
	v_lshlrev_b32_e32 v182, 16, v213
	v_and_b32_e32 v183, 0xffff0000, v213
	v_lshlrev_b32_e32 v184, 16, v214
	v_and_b32_e32 v185, 0xffff0000, v214
	v_lshlrev_b32_e32 v186, 16, v215
	v_and_b32_e32 v187, 0xffff0000, v215
	v_pk_fma_f32 v[124:125], v[124:125], v[196:197], v[180:181]
	v_pk_fma_f32 v[126:127], v[126:127], v[198:199], v[182:183]
	v_pk_fma_f32 v[120:121], v[120:121], v[200:201], v[184:185]
	v_pk_fma_f32 v[122:123], v[122:123], v[202:203], v[186:187]
	v_cvt_pk_bf16_f32 v123, v122, v123
	v_cvt_pk_bf16_f32 v122, v120, v121
	v_cvt_pk_bf16_f32 v121, v126, v127
	v_cvt_pk_bf16_f32 v120, v124, v125
	global_store_dwordx4 v148, v[120:123], s[74:75]
	v_lshlrev_b32_e32 v180, 16, v216
	v_and_b32_e32 v181, 0xffff0000, v216
	v_lshlrev_b32_e32 v182, 16, v217
	v_and_b32_e32 v183, 0xffff0000, v217
	v_lshlrev_b32_e32 v184, 16, v218
	v_and_b32_e32 v185, 0xffff0000, v218
	v_lshlrev_b32_e32 v186, 16, v219
	v_and_b32_e32 v187, 0xffff0000, v219
	v_pk_fma_f32 v[116:117], v[116:117], v[204:205], v[180:181]
	v_pk_fma_f32 v[118:119], v[118:119], v[206:207], v[182:183]
	v_pk_fma_f32 v[112:113], v[112:113], v[208:209], v[184:185]
	v_pk_fma_f32 v[114:115], v[114:115], v[210:211], v[186:187]
	v_cvt_pk_bf16_f32 v115, v114, v115
	v_cvt_pk_bf16_f32 v114, v112, v113
	v_cvt_pk_bf16_f32 v113, v118, v119
	v_cvt_pk_bf16_f32 v112, v116, v117
	global_store_dwordx4 v148, v[112:115], s[74:75] offset:256
	v_lshlrev_b32_e32 v180, 16, v220
	v_and_b32_e32 v181, 0xffff0000, v220
	v_lshlrev_b32_e32 v182, 16, v221
	v_and_b32_e32 v183, 0xffff0000, v221
	v_lshlrev_b32_e32 v184, 16, v222
	v_and_b32_e32 v185, 0xffff0000, v222
	v_lshlrev_b32_e32 v186, 16, v223
	v_and_b32_e32 v187, 0xffff0000, v223
	v_pk_fma_f32 v[108:109], v[108:109], v[196:197], v[180:181]
	v_pk_fma_f32 v[110:111], v[110:111], v[198:199], v[182:183]
	v_pk_fma_f32 v[104:105], v[104:105], v[200:201], v[184:185]
	v_pk_fma_f32 v[106:107], v[106:107], v[202:203], v[186:187]
	v_cvt_pk_bf16_f32 v107, v106, v107
	v_cvt_pk_bf16_f32 v106, v104, v105
	v_cvt_pk_bf16_f32 v105, v110, v111
	v_cvt_pk_bf16_f32 v104, v108, v109
	v_add_u32_e32 v151, 0x10000, v148
	global_store_dwordx4 v151, v[104:107], s[74:75]
	v_lshlrev_b32_e32 v180, 16, v224
	v_and_b32_e32 v181, 0xffff0000, v224
	v_lshlrev_b32_e32 v182, 16, v225
	v_and_b32_e32 v183, 0xffff0000, v225
	v_lshlrev_b32_e32 v184, 16, v226
	v_and_b32_e32 v185, 0xffff0000, v226
	v_lshlrev_b32_e32 v186, 16, v227
	v_and_b32_e32 v187, 0xffff0000, v227
	v_pk_fma_f32 v[100:101], v[100:101], v[204:205], v[180:181]
	v_pk_fma_f32 v[102:103], v[102:103], v[206:207], v[182:183]
	v_pk_fma_f32 v[96:97], v[96:97], v[208:209], v[184:185]
	v_pk_fma_f32 v[98:99], v[98:99], v[210:211], v[186:187]
	v_cvt_pk_bf16_f32 v99, v98, v99
	v_cvt_pk_bf16_f32 v98, v96, v97
	v_cvt_pk_bf16_f32 v97, v102, v103
	v_cvt_pk_bf16_f32 v96, v100, v101
	v_add_u32_e32 v151, 0x10000, v148
	global_store_dwordx4 v151, v[96:99], s[74:75] offset:256
	v_add_u32_e32 v151, 0x80000, v148
	global_load_dwordx4 v[212:215], v151, s[74:75]
	global_load_dwordx4 v[216:219], v151, s[74:75] offset:256
	v_add_u32_e32 v151, 0x90000, v148
	global_load_dwordx4 v[220:223], v151, s[74:75]
	global_load_dwordx4 v[224:227], v151, s[74:75] offset:256
	v_lshlrev_b32_e32 v180, 16, v164
	v_and_b32_e32 v181, 0xffff0000, v164
	v_lshlrev_b32_e32 v182, 16, v165
	v_and_b32_e32 v183, 0xffff0000, v165
	v_lshlrev_b32_e32 v184, 16, v166
	v_and_b32_e32 v185, 0xffff0000, v166
	v_lshlrev_b32_e32 v186, 16, v167
	v_and_b32_e32 v187, 0xffff0000, v167
	v_pk_fma_f32 v[92:93], v[92:93], v[196:197], v[180:181]
	v_pk_fma_f32 v[94:95], v[94:95], v[198:199], v[182:183]
	v_pk_fma_f32 v[88:89], v[88:89], v[200:201], v[184:185]
	v_pk_fma_f32 v[90:91], v[90:91], v[202:203], v[186:187]
	v_cvt_pk_bf16_f32 v91, v90, v91
	v_cvt_pk_bf16_f32 v90, v88, v89
	v_cvt_pk_bf16_f32 v89, v94, v95
	v_cvt_pk_bf16_f32 v88, v92, v93
	v_add_u32_e32 v151, 0x20000, v148
	global_store_dwordx4 v151, v[88:91], s[74:75]
	v_lshlrev_b32_e32 v180, 16, v168
	v_and_b32_e32 v181, 0xffff0000, v168
	v_lshlrev_b32_e32 v182, 16, v169
	v_and_b32_e32 v183, 0xffff0000, v169
	v_lshlrev_b32_e32 v184, 16, v170
	v_and_b32_e32 v185, 0xffff0000, v170
	v_lshlrev_b32_e32 v186, 16, v171
	v_and_b32_e32 v187, 0xffff0000, v171
	v_pk_fma_f32 v[84:85], v[84:85], v[204:205], v[180:181]
	v_pk_fma_f32 v[86:87], v[86:87], v[206:207], v[182:183]
	v_pk_fma_f32 v[80:81], v[80:81], v[208:209], v[184:185]
	v_pk_fma_f32 v[82:83], v[82:83], v[210:211], v[186:187]
	v_cvt_pk_bf16_f32 v83, v82, v83
	v_cvt_pk_bf16_f32 v82, v80, v81
	v_cvt_pk_bf16_f32 v81, v86, v87
	v_cvt_pk_bf16_f32 v80, v84, v85
	v_add_u32_e32 v151, 0x20000, v148
	global_store_dwordx4 v151, v[80:83], s[74:75] offset:256
	v_lshlrev_b32_e32 v180, 16, v172
	v_and_b32_e32 v181, 0xffff0000, v172
	v_lshlrev_b32_e32 v182, 16, v173
	v_and_b32_e32 v183, 0xffff0000, v173
	v_lshlrev_b32_e32 v184, 16, v174
	v_and_b32_e32 v185, 0xffff0000, v174
	v_lshlrev_b32_e32 v186, 16, v175
	v_and_b32_e32 v187, 0xffff0000, v175
	v_pk_fma_f32 v[76:77], v[76:77], v[196:197], v[180:181]
	v_pk_fma_f32 v[78:79], v[78:79], v[198:199], v[182:183]
	v_pk_fma_f32 v[72:73], v[72:73], v[200:201], v[184:185]
	v_pk_fma_f32 v[74:75], v[74:75], v[202:203], v[186:187]
	v_cvt_pk_bf16_f32 v75, v74, v75
	v_cvt_pk_bf16_f32 v74, v72, v73
	v_cvt_pk_bf16_f32 v73, v78, v79
	v_cvt_pk_bf16_f32 v72, v76, v77
	v_add_u32_e32 v151, 0x30000, v148
	global_store_dwordx4 v151, v[72:75], s[74:75]
	v_lshlrev_b32_e32 v180, 16, v176
	v_and_b32_e32 v181, 0xffff0000, v176
	v_lshlrev_b32_e32 v182, 16, v177
	v_and_b32_e32 v183, 0xffff0000, v177
	v_lshlrev_b32_e32 v184, 16, v178
	v_and_b32_e32 v185, 0xffff0000, v178
	v_lshlrev_b32_e32 v186, 16, v179
	v_and_b32_e32 v187, 0xffff0000, v179
	v_pk_fma_f32 v[68:69], v[68:69], v[204:205], v[180:181]
	v_pk_fma_f32 v[70:71], v[70:71], v[206:207], v[182:183]
	v_pk_fma_f32 v[64:65], v[64:65], v[208:209], v[184:185]
	v_pk_fma_f32 v[66:67], v[66:67], v[210:211], v[186:187]
	v_cvt_pk_bf16_f32 v67, v66, v67
	v_cvt_pk_bf16_f32 v66, v64, v65
	v_cvt_pk_bf16_f32 v65, v70, v71
	v_cvt_pk_bf16_f32 v64, v68, v69
	v_add_u32_e32 v151, 0x30000, v148
	global_store_dwordx4 v151, v[64:67], s[74:75] offset:256
	v_add_u32_e32 v151, 0xa0000, v148
	global_load_dwordx4 v[164:167], v151, s[74:75]
	global_load_dwordx4 v[168:171], v151, s[74:75] offset:256
	v_add_u32_e32 v151, 0xb0000, v148
	global_load_dwordx4 v[172:175], v151, s[74:75]
	global_load_dwordx4 v[176:179], v151, s[74:75] offset:256
	s_waitcnt vmcnt(0)
	v_lshlrev_b32_e32 v180, 16, v212
	v_and_b32_e32 v181, 0xffff0000, v212
	v_lshlrev_b32_e32 v182, 16, v213
	v_and_b32_e32 v183, 0xffff0000, v213
	v_lshlrev_b32_e32 v184, 16, v214
	v_and_b32_e32 v185, 0xffff0000, v214
	v_lshlrev_b32_e32 v186, 16, v215
	v_and_b32_e32 v187, 0xffff0000, v215
	v_pk_fma_f32 v[60:61], v[60:61], v[196:197], v[180:181]
	v_pk_fma_f32 v[62:63], v[62:63], v[198:199], v[182:183]
	v_pk_fma_f32 v[56:57], v[56:57], v[200:201], v[184:185]
	v_pk_fma_f32 v[58:59], v[58:59], v[202:203], v[186:187]
	v_cvt_pk_bf16_f32 v59, v58, v59
	v_cvt_pk_bf16_f32 v58, v56, v57
	v_cvt_pk_bf16_f32 v57, v62, v63
	v_cvt_pk_bf16_f32 v56, v60, v61
	v_add_u32_e32 v151, 0x80000, v148
	global_store_dwordx4 v151, v[56:59], s[74:75]
	v_lshlrev_b32_e32 v180, 16, v216
	v_and_b32_e32 v181, 0xffff0000, v216
	v_lshlrev_b32_e32 v182, 16, v217
	v_and_b32_e32 v183, 0xffff0000, v217
	v_lshlrev_b32_e32 v184, 16, v218
	v_and_b32_e32 v185, 0xffff0000, v218
	v_lshlrev_b32_e32 v186, 16, v219
	v_and_b32_e32 v187, 0xffff0000, v219
	v_pk_fma_f32 v[52:53], v[52:53], v[204:205], v[180:181]
	v_pk_fma_f32 v[54:55], v[54:55], v[206:207], v[182:183]
	v_pk_fma_f32 v[48:49], v[48:49], v[208:209], v[184:185]
	v_pk_fma_f32 v[50:51], v[50:51], v[210:211], v[186:187]
	v_cvt_pk_bf16_f32 v51, v50, v51
	v_cvt_pk_bf16_f32 v50, v48, v49
	v_cvt_pk_bf16_f32 v49, v54, v55
	v_cvt_pk_bf16_f32 v48, v52, v53
	v_add_u32_e32 v151, 0x80000, v148
	global_store_dwordx4 v151, v[48:51], s[74:75] offset:256
	v_lshlrev_b32_e32 v180, 16, v220
	v_and_b32_e32 v181, 0xffff0000, v220
	v_lshlrev_b32_e32 v182, 16, v221
	v_and_b32_e32 v183, 0xffff0000, v221
	v_lshlrev_b32_e32 v184, 16, v222
	v_and_b32_e32 v185, 0xffff0000, v222
	v_lshlrev_b32_e32 v186, 16, v223
	v_and_b32_e32 v187, 0xffff0000, v223
	v_pk_fma_f32 v[44:45], v[44:45], v[196:197], v[180:181]
	v_pk_fma_f32 v[46:47], v[46:47], v[198:199], v[182:183]
	v_pk_fma_f32 v[40:41], v[40:41], v[200:201], v[184:185]
	v_pk_fma_f32 v[42:43], v[42:43], v[202:203], v[186:187]
	v_cvt_pk_bf16_f32 v43, v42, v43
	v_cvt_pk_bf16_f32 v42, v40, v41
	v_cvt_pk_bf16_f32 v41, v46, v47
	v_cvt_pk_bf16_f32 v40, v44, v45
	v_add_u32_e32 v151, 0x90000, v148
	global_store_dwordx4 v151, v[40:43], s[74:75]
	v_lshlrev_b32_e32 v180, 16, v224
	v_and_b32_e32 v181, 0xffff0000, v224
	v_lshlrev_b32_e32 v182, 16, v225
	v_and_b32_e32 v183, 0xffff0000, v225
	v_lshlrev_b32_e32 v184, 16, v226
	v_and_b32_e32 v185, 0xffff0000, v226
	v_lshlrev_b32_e32 v186, 16, v227
	v_and_b32_e32 v187, 0xffff0000, v227
	v_pk_fma_f32 v[36:37], v[36:37], v[204:205], v[180:181]
	v_pk_fma_f32 v[38:39], v[38:39], v[206:207], v[182:183]
	v_pk_fma_f32 v[32:33], v[32:33], v[208:209], v[184:185]
	v_pk_fma_f32 v[34:35], v[34:35], v[210:211], v[186:187]
	v_cvt_pk_bf16_f32 v35, v34, v35
	v_cvt_pk_bf16_f32 v34, v32, v33
	v_cvt_pk_bf16_f32 v33, v38, v39
	v_cvt_pk_bf16_f32 v32, v36, v37
	v_add_u32_e32 v151, 0x90000, v148
	global_store_dwordx4 v151, v[32:35], s[74:75] offset:256
	v_lshlrev_b32_e32 v180, 16, v164
	v_and_b32_e32 v181, 0xffff0000, v164
	v_lshlrev_b32_e32 v182, 16, v165
	v_and_b32_e32 v183, 0xffff0000, v165
	v_lshlrev_b32_e32 v184, 16, v166
	v_and_b32_e32 v185, 0xffff0000, v166
	v_lshlrev_b32_e32 v186, 16, v167
	v_and_b32_e32 v187, 0xffff0000, v167
	v_pk_fma_f32 v[28:29], v[28:29], v[196:197], v[180:181]
	v_pk_fma_f32 v[30:31], v[30:31], v[198:199], v[182:183]
	v_pk_fma_f32 v[24:25], v[24:25], v[200:201], v[184:185]
	v_pk_fma_f32 v[26:27], v[26:27], v[202:203], v[186:187]
	v_cvt_pk_bf16_f32 v27, v26, v27
	v_cvt_pk_bf16_f32 v26, v24, v25
	v_cvt_pk_bf16_f32 v25, v30, v31
	v_cvt_pk_bf16_f32 v24, v28, v29
	v_add_u32_e32 v151, 0xa0000, v148
	global_store_dwordx4 v151, v[24:27], s[74:75]
	v_lshlrev_b32_e32 v180, 16, v168
	v_and_b32_e32 v181, 0xffff0000, v168
	v_lshlrev_b32_e32 v182, 16, v169
	v_and_b32_e32 v183, 0xffff0000, v169
	v_lshlrev_b32_e32 v184, 16, v170
	v_and_b32_e32 v185, 0xffff0000, v170
	v_lshlrev_b32_e32 v186, 16, v171
	v_and_b32_e32 v187, 0xffff0000, v171
	v_pk_fma_f32 v[20:21], v[20:21], v[204:205], v[180:181]
	v_pk_fma_f32 v[22:23], v[22:23], v[206:207], v[182:183]
	v_pk_fma_f32 v[16:17], v[16:17], v[208:209], v[184:185]
	v_pk_fma_f32 v[18:19], v[18:19], v[210:211], v[186:187]
	v_cvt_pk_bf16_f32 v19, v18, v19
	v_cvt_pk_bf16_f32 v18, v16, v17
	v_cvt_pk_bf16_f32 v17, v22, v23
	v_cvt_pk_bf16_f32 v16, v20, v21
	v_add_u32_e32 v151, 0xa0000, v148
	global_store_dwordx4 v151, v[16:19], s[74:75] offset:256
	v_lshlrev_b32_e32 v180, 16, v172
	v_and_b32_e32 v181, 0xffff0000, v172
	v_lshlrev_b32_e32 v182, 16, v173
	v_and_b32_e32 v183, 0xffff0000, v173
	v_lshlrev_b32_e32 v184, 16, v174
	v_and_b32_e32 v185, 0xffff0000, v174
	v_lshlrev_b32_e32 v186, 16, v175
	v_and_b32_e32 v187, 0xffff0000, v175
	v_pk_fma_f32 v[12:13], v[12:13], v[196:197], v[180:181]
	v_pk_fma_f32 v[14:15], v[14:15], v[198:199], v[182:183]
	v_pk_fma_f32 v[8:9], v[8:9], v[200:201], v[184:185]
	v_pk_fma_f32 v[10:11], v[10:11], v[202:203], v[186:187]
	v_cvt_pk_bf16_f32 v11, v10, v11
	v_cvt_pk_bf16_f32 v10, v8, v9
	v_cvt_pk_bf16_f32 v9, v14, v15
	v_cvt_pk_bf16_f32 v8, v12, v13
	v_add_u32_e32 v151, 0xb0000, v148
	global_store_dwordx4 v151, v[8:11], s[74:75]
	v_lshlrev_b32_e32 v180, 16, v176
	v_and_b32_e32 v181, 0xffff0000, v176
	v_lshlrev_b32_e32 v182, 16, v177
	v_and_b32_e32 v183, 0xffff0000, v177
	v_lshlrev_b32_e32 v184, 16, v178
	v_and_b32_e32 v185, 0xffff0000, v178
	v_lshlrev_b32_e32 v186, 16, v179
	v_and_b32_e32 v187, 0xffff0000, v179
	v_pk_fma_f32 v[4:5], v[4:5], v[204:205], v[180:181]
	v_pk_fma_f32 v[6:7], v[6:7], v[206:207], v[182:183]
	v_pk_fma_f32 v[0:1], v[0:1], v[208:209], v[184:185]
	v_pk_fma_f32 v[2:3], v[2:3], v[210:211], v[186:187]
	v_cvt_pk_bf16_f32 v3, v2, v3
	v_cvt_pk_bf16_f32 v2, v0, v1
	v_cvt_pk_bf16_f32 v1, v6, v7
	v_cvt_pk_bf16_f32 v0, v4, v5
	v_add_u32_e32 v151, 0xb0000, v148
	global_store_dwordx4 v151, v[0:3], s[74:75] offset:256

.LBB0_1402:
	ds_read_b128 v[154:157], v151
	ds_read_b128 v[158:161], v151 offset:1024
	ds_read_b128 v[162:165], v151 offset:2048
	ds_read_b128 v[166:169], v151 offset:3072
	s_add_u32 s20, s26, 0xfff80080
	s_addc_u32 s21, s27, -1
	s_cmp_eq_u32 s52, 28
	s_cselect_b32 s21, s15, s21
	s_cselect_b32 s20, s48, s20
	s_cselect_b32 s37, s11, s51
	s_cselect_b32 s36, s49, s50
	v_lshl_add_u64 v[148:149], s[26:27], 0, v[136:137]
	s_add_i32 m0, s25, 0xc000
	ds_read_b128 v[170:173], v152
	ds_read_b128 v[174:177], v152 offset:1024
	ds_read_b128 v[178:181], v152 offset:2048
	ds_read_b128 v[182:185], v152 offset:3072
	ds_read_b128 v[186:189], v152 offset:4096
	ds_read_b128 v[196:199], v152 offset:5120
	ds_read_b128 v[200:203], v152 offset:6144
	ds_read_b128 v[204:207], v152 offset:7168
	global_load_lds_dwordx4 v[148:149], off
	s_add_i32 m0, s25, 0xe000
	v_lshl_add_u64 v[148:149], s[26:27], 0, v[138:139]
	global_load_lds_dwordx4 v[148:149], off
	s_waitcnt lgkmcnt(8)
	s_barrier
	s_waitcnt lgkmcnt(0)
	v_mfma_f32_16x16x32_bf16 v[124:127], v[154:157], v[170:173], v[124:127]
	v_mfma_f32_16x16x32_bf16 v[120:123], v[162:165], v[170:173], v[120:123]
	v_mfma_f32_16x16x32_bf16 v[108:111], v[154:157], v[178:181], v[108:111]
	v_mfma_f32_16x16x32_bf16 v[104:107], v[162:165], v[178:181], v[104:107]
	v_mfma_f32_16x16x32_bf16 v[92:95], v[154:157], v[186:189], v[92:95]
	v_mfma_f32_16x16x32_bf16 v[88:91], v[162:165], v[186:189], v[88:91]
	v_mfma_f32_16x16x32_bf16 v[76:79], v[154:157], v[200:203], v[76:79]
	v_mfma_f32_16x16x32_bf16 v[72:75], v[162:165], v[200:203], v[72:75]
	v_mfma_f32_16x16x32_bf16 v[124:127], v[158:161], v[174:177], v[124:127]
	v_mfma_f32_16x16x32_bf16 v[120:123], v[166:169], v[174:177], v[120:123]
	v_mfma_f32_16x16x32_bf16 v[108:111], v[158:161], v[182:185], v[108:111]
	v_mfma_f32_16x16x32_bf16 v[104:107], v[166:169], v[182:185], v[104:107]
	v_mfma_f32_16x16x32_bf16 v[92:95], v[158:161], v[196:199], v[92:95]
	v_mfma_f32_16x16x32_bf16 v[88:91], v[166:169], v[196:199], v[88:91]
	v_mfma_f32_16x16x32_bf16 v[76:79], v[158:161], v[204:207], v[76:79]
	v_mfma_f32_16x16x32_bf16 v[72:75], v[166:169], v[204:207], v[72:75]
	s_barrier
	s_add_i32 s53, s46, s23
	v_lshl_add_u64 v[148:149], s[36:37], 0, v[132:133]
	s_mov_b32 m0, s53
	ds_read_b128 v[208:211], v153
	ds_read_b128 v[212:215], v153 offset:1024
	ds_read_b128 v[216:219], v153 offset:2048
	ds_read_b128 v[220:223], v153 offset:3072
	global_load_lds_dwordx4 v[148:149], off
	s_add_i32 m0, s53, 0x2000
	v_lshl_add_u64 v[190:191], s[36:37], 0, v[128:129]
	global_load_lds_dwordx4 v[190:191], off
	s_barrier
	s_waitcnt lgkmcnt(0)
	v_mfma_f32_16x16x32_bf16 v[116:119], v[208:211], v[170:173], v[116:119]
	v_mfma_f32_16x16x32_bf16 v[112:115], v[216:219], v[170:173], v[112:115]
	v_mfma_f32_16x16x32_bf16 v[100:103], v[208:211], v[178:181], v[100:103]
	v_mfma_f32_16x16x32_bf16 v[96:99], v[216:219], v[178:181], v[96:99]
	v_mfma_f32_16x16x32_bf16 v[84:87], v[208:211], v[186:189], v[84:87]
	v_mfma_f32_16x16x32_bf16 v[80:83], v[216:219], v[186:189], v[80:83]
	v_mfma_f32_16x16x32_bf16 v[68:71], v[208:211], v[200:203], v[68:71]
	v_mfma_f32_16x16x32_bf16 v[64:67], v[216:219], v[200:203], v[64:67]
	v_mfma_f32_16x16x32_bf16 v[116:119], v[212:215], v[174:177], v[116:119]
	v_mfma_f32_16x16x32_bf16 v[112:115], v[220:223], v[174:177], v[112:115]
	v_mfma_f32_16x16x32_bf16 v[100:103], v[212:215], v[182:185], v[100:103]
	v_mfma_f32_16x16x32_bf16 v[96:99], v[220:223], v[182:185], v[96:99]
	v_mfma_f32_16x16x32_bf16 v[84:87], v[212:215], v[196:199], v[84:87]
	v_mfma_f32_16x16x32_bf16 v[80:83], v[220:223], v[196:199], v[80:83]
	v_mfma_f32_16x16x32_bf16 v[68:71], v[212:215], v[204:207], v[68:71]
	v_mfma_f32_16x16x32_bf16 v[64:67], v[220:223], v[204:207], v[64:67]
	s_mov_b32 m0, s25
	v_lshl_add_u64 v[224:225], s[20:21], 0, v[134:135]
	s_barrier
	ds_read_b128 v[170:173], v152 offset:16384
	ds_read_b128 v[174:177], v152 offset:17408
	ds_read_b128 v[178:181], v152 offset:18432
	ds_read_b128 v[182:185], v152 offset:19456
	ds_read_b128 v[186:189], v152 offset:20480
	ds_read_b128 v[196:199], v152 offset:21504
	ds_read_b128 v[200:203], v152 offset:22528
	ds_read_b128 v[204:207], v152 offset:23552
	global_load_lds_dwordx4 v[224:225], off
	s_mov_b32 m0, s35
	v_lshl_add_u64 v[226:227], s[20:21], 0, v[130:131]
	global_load_lds_dwordx4 v[226:227], off
	s_barrier
	s_waitcnt lgkmcnt(0)
	v_mfma_f32_16x16x32_bf16 v[60:63], v[154:157], v[170:173], v[60:63]
	v_mfma_f32_16x16x32_bf16 v[56:59], v[162:165], v[170:173], v[56:59]
	v_mfma_f32_16x16x32_bf16 v[44:47], v[154:157], v[178:181], v[44:47]
	v_mfma_f32_16x16x32_bf16 v[40:43], v[162:165], v[178:181], v[40:43]
	v_mfma_f32_16x16x32_bf16 v[28:31], v[154:157], v[186:189], v[28:31]
	v_mfma_f32_16x16x32_bf16 v[24:27], v[162:165], v[186:189], v[24:27]
	v_mfma_f32_16x16x32_bf16 v[12:15], v[154:157], v[200:203], v[12:15]
	v_mfma_f32_16x16x32_bf16 v[8:11], v[162:165], v[200:203], v[8:11]
	v_mfma_f32_16x16x32_bf16 v[60:63], v[158:161], v[174:177], v[60:63]
	v_mfma_f32_16x16x32_bf16 v[56:59], v[166:169], v[174:177], v[56:59]
	v_mfma_f32_16x16x32_bf16 v[44:47], v[158:161], v[182:185], v[44:47]
	v_mfma_f32_16x16x32_bf16 v[40:43], v[166:169], v[182:185], v[40:43]
	v_mfma_f32_16x16x32_bf16 v[28:31], v[158:161], v[196:199], v[28:31]
	v_mfma_f32_16x16x32_bf16 v[24:27], v[166:169], v[196:199], v[24:27]
	v_mfma_f32_16x16x32_bf16 v[12:15], v[158:161], v[204:207], v[12:15]
	v_mfma_f32_16x16x32_bf16 v[8:11], v[166:169], v[204:207], v[8:11]
	s_barrier
	s_add_u32 s54, s36, 0x80000
	s_addc_u32 s55, s37, 0
	s_add_i32 s53, s47, s23
	s_mov_b32 m0, s53
	v_lshl_add_u64 v[154:155], s[54:55], 0, v[132:133]
	global_load_lds_dwordx4 v[154:155], off
	s_add_i32 m0, s53, 0x2000
	v_lshl_add_u64 v[154:155], s[54:55], 0, v[128:129]
	global_load_lds_dwordx4 v[154:155], off
	s_waitcnt vmcnt(6)
	s_barrier
	v_mfma_f32_16x16x32_bf16 v[52:55], v[208:211], v[170:173], v[52:55]
	v_mfma_f32_16x16x32_bf16 v[48:51], v[216:219], v[170:173], v[48:51]
	v_mfma_f32_16x16x32_bf16 v[36:39], v[208:211], v[178:181], v[36:39]
	v_mfma_f32_16x16x32_bf16 v[32:35], v[216:219], v[178:181], v[32:35]
	v_mfma_f32_16x16x32_bf16 v[20:23], v[208:211], v[186:189], v[20:23]
	v_mfma_f32_16x16x32_bf16 v[16:19], v[216:219], v[186:189], v[16:19]
	v_mfma_f32_16x16x32_bf16 v[4:7], v[208:211], v[200:203], v[4:7]
	v_mfma_f32_16x16x32_bf16 v[0:3], v[216:219], v[200:203], v[0:3]
	v_mfma_f32_16x16x32_bf16 v[52:55], v[212:215], v[174:177], v[52:55]
	v_mfma_f32_16x16x32_bf16 v[48:51], v[220:223], v[174:177], v[48:51]
	v_mfma_f32_16x16x32_bf16 v[36:39], v[212:215], v[182:185], v[36:39]
	v_mfma_f32_16x16x32_bf16 v[32:35], v[220:223], v[182:185], v[32:35]
	v_mfma_f32_16x16x32_bf16 v[20:23], v[212:215], v[196:199], v[20:23]
	v_mfma_f32_16x16x32_bf16 v[16:19], v[220:223], v[196:199], v[16:19]
	v_mfma_f32_16x16x32_bf16 v[4:7], v[212:215], v[204:207], v[4:7]
	v_mfma_f32_16x16x32_bf16 v[0:3], v[220:223], v[204:207], v[0:3]
	s_add_i32 s53, 0, 0x18000
	v_add_u32_e32 v166, s53, v147
	s_barrier
	ds_read_b128 v[154:157], v166
	ds_read_b128 v[158:161], v166 offset:1024
	ds_read_b128 v[162:165], v166 offset:2048
	ds_read_b128 v[166:169], v166 offset:3072
	s_add_u32 s20, s20, 0x80000
	s_addc_u32 s21, s21, 0
	s_mov_b32 m0, s38
	v_lshl_add_u64 v[208:209], s[20:21], 0, v[134:135]
	ds_read_b128 v[170:173], v152 offset:32768
	ds_read_b128 v[174:177], v152 offset:33792
	ds_read_b128 v[178:181], v152 offset:34816
	ds_read_b128 v[182:185], v152 offset:35840
	ds_read_b128 v[186:189], v152 offset:36864
	ds_read_b128 v[196:199], v152 offset:37888
	ds_read_b128 v[200:203], v152 offset:38912
	ds_read_b128 v[204:207], v152 offset:39936
	global_load_lds_dwordx4 v[208:209], off
	s_mov_b32 m0, s39
	v_lshl_add_u64 v[208:209], s[20:21], 0, v[130:131]
	global_load_lds_dwordx4 v[208:209], off
	s_waitcnt lgkmcnt(8)
	s_barrier
	s_waitcnt lgkmcnt(0)
	v_mfma_f32_16x16x32_bf16 v[124:127], v[154:157], v[170:173], v[124:127]
	v_mfma_f32_16x16x32_bf16 v[120:123], v[162:165], v[170:173], v[120:123]
	v_mfma_f32_16x16x32_bf16 v[108:111], v[154:157], v[178:181], v[108:111]
	v_mfma_f32_16x16x32_bf16 v[104:107], v[162:165], v[178:181], v[104:107]
	v_mfma_f32_16x16x32_bf16 v[92:95], v[154:157], v[186:189], v[92:95]
	v_mfma_f32_16x16x32_bf16 v[88:91], v[162:165], v[186:189], v[88:91]
	v_mfma_f32_16x16x32_bf16 v[76:79], v[154:157], v[200:203], v[76:79]
	v_mfma_f32_16x16x32_bf16 v[72:75], v[162:165], v[200:203], v[72:75]
	v_mfma_f32_16x16x32_bf16 v[124:127], v[158:161], v[174:177], v[124:127]
	v_mfma_f32_16x16x32_bf16 v[120:123], v[166:169], v[174:177], v[120:123]
	v_mfma_f32_16x16x32_bf16 v[108:111], v[158:161], v[182:185], v[108:111]
	v_mfma_f32_16x16x32_bf16 v[104:107], v[166:169], v[182:185], v[104:107]
	v_mfma_f32_16x16x32_bf16 v[92:95], v[158:161], v[196:199], v[92:95]
	v_mfma_f32_16x16x32_bf16 v[88:91], v[166:169], v[196:199], v[88:91]
	v_mfma_f32_16x16x32_bf16 v[76:79], v[158:161], v[204:207], v[76:79]
	v_mfma_f32_16x16x32_bf16 v[72:75], v[166:169], v[204:207], v[72:75]
	s_barrier
	s_add_i32 s54, 0, 0x1c000
	s_add_i32 s20, s53, s23
	v_add_u32_e32 v193, s54, v147
	v_lshl_add_u64 v[148:149], v[148:149], 0, s[8:9]
	s_mov_b32 m0, s20
	ds_read_b128 v[208:211], v193
	ds_read_b128 v[212:215], v193 offset:1024
	ds_read_b128 v[216:219], v193 offset:2048
	ds_read_b128 v[220:223], v193 offset:3072
	global_load_lds_dwordx4 v[148:149], off
	s_add_i32 m0, s20, 0x2000
	v_lshl_add_u64 v[148:149], v[190:191], 0, s[8:9]
	global_load_lds_dwordx4 v[148:149], off
	s_barrier
	s_waitcnt lgkmcnt(0)
	v_mfma_f32_16x16x32_bf16 v[116:119], v[208:211], v[170:173], v[116:119]
	v_mfma_f32_16x16x32_bf16 v[112:115], v[216:219], v[170:173], v[112:115]
	v_mfma_f32_16x16x32_bf16 v[100:103], v[208:211], v[178:181], v[100:103]
	v_mfma_f32_16x16x32_bf16 v[96:99], v[216:219], v[178:181], v[96:99]
	v_mfma_f32_16x16x32_bf16 v[84:87], v[208:211], v[186:189], v[84:87]
	v_mfma_f32_16x16x32_bf16 v[80:83], v[216:219], v[186:189], v[80:83]
	v_mfma_f32_16x16x32_bf16 v[68:71], v[208:211], v[200:203], v[68:71]
	v_mfma_f32_16x16x32_bf16 v[64:67], v[216:219], v[200:203], v[64:67]
	v_mfma_f32_16x16x32_bf16 v[116:119], v[212:215], v[174:177], v[116:119]
	v_mfma_f32_16x16x32_bf16 v[112:115], v[220:223], v[174:177], v[112:115]
	v_mfma_f32_16x16x32_bf16 v[100:103], v[212:215], v[182:185], v[100:103]
	v_mfma_f32_16x16x32_bf16 v[96:99], v[220:223], v[182:185], v[96:99]
	v_mfma_f32_16x16x32_bf16 v[84:87], v[212:215], v[196:199], v[84:87]
	v_mfma_f32_16x16x32_bf16 v[80:83], v[220:223], v[196:199], v[80:83]
	v_mfma_f32_16x16x32_bf16 v[68:71], v[212:215], v[204:207], v[68:71]
	v_mfma_f32_16x16x32_bf16 v[64:67], v[220:223], v[204:207], v[64:67]
	s_mov_b32 m0, s41
	v_lshl_add_u64 v[148:149], v[224:225], 0, s[8:9]
	s_barrier
	ds_read_b128 v[170:173], v152 offset:49152
	ds_read_b128 v[174:177], v152 offset:50176
	ds_read_b128 v[178:181], v152 offset:51200
	ds_read_b128 v[182:185], v152 offset:52224
	ds_read_b128 v[186:189], v152 offset:53248
	ds_read_b128 v[196:199], v152 offset:54272
	ds_read_b128 v[200:203], v152 offset:55296
	ds_read_b128 v[204:207], v152 offset:56320
	global_load_lds_dwordx4 v[148:149], off
	s_mov_b32 m0, s44
	v_lshl_add_u64 v[148:149], v[226:227], 0, s[8:9]
	global_load_lds_dwordx4 v[148:149], off
	s_barrier
	s_waitcnt lgkmcnt(0)
	v_mfma_f32_16x16x32_bf16 v[60:63], v[154:157], v[170:173], v[60:63]
	v_mfma_f32_16x16x32_bf16 v[56:59], v[162:165], v[170:173], v[56:59]
	v_mfma_f32_16x16x32_bf16 v[44:47], v[154:157], v[178:181], v[44:47]
	v_mfma_f32_16x16x32_bf16 v[40:43], v[162:165], v[178:181], v[40:43]
	v_mfma_f32_16x16x32_bf16 v[28:31], v[154:157], v[186:189], v[28:31]
	v_mfma_f32_16x16x32_bf16 v[24:27], v[162:165], v[186:189], v[24:27]
	v_mfma_f32_16x16x32_bf16 v[12:15], v[154:157], v[200:203], v[12:15]
	v_mfma_f32_16x16x32_bf16 v[8:11], v[162:165], v[200:203], v[8:11]
	v_mfma_f32_16x16x32_bf16 v[60:63], v[158:161], v[174:177], v[60:63]
	v_mfma_f32_16x16x32_bf16 v[56:59], v[166:169], v[174:177], v[56:59]
	v_mfma_f32_16x16x32_bf16 v[44:47], v[158:161], v[182:185], v[44:47]
	v_mfma_f32_16x16x32_bf16 v[40:43], v[166:169], v[182:185], v[40:43]
	v_mfma_f32_16x16x32_bf16 v[28:31], v[158:161], v[196:199], v[28:31]
	v_mfma_f32_16x16x32_bf16 v[24:27], v[166:169], v[196:199], v[24:27]
	v_mfma_f32_16x16x32_bf16 v[12:15], v[158:161], v[204:207], v[12:15]
	v_mfma_f32_16x16x32_bf16 v[8:11], v[166:169], v[204:207], v[8:11]
	s_barrier
	s_add_u32 s20, s36, 0x80080
	s_addc_u32 s21, s37, 0
	s_add_i32 s36, s54, s23
	s_mov_b32 m0, s36
	v_lshl_add_u64 v[148:149], s[20:21], 0, v[132:133]
	global_load_lds_dwordx4 v[148:149], off
	s_add_i32 m0, s36, 0x2000
	v_lshl_add_u64 v[148:149], s[20:21], 0, v[128:129]
	global_load_lds_dwordx4 v[148:149], off
	s_waitcnt vmcnt(6)
	s_barrier
	v_mfma_f32_16x16x32_bf16 v[52:55], v[208:211], v[170:173], v[52:55]
	v_mfma_f32_16x16x32_bf16 v[48:51], v[216:219], v[170:173], v[48:51]
	v_mfma_f32_16x16x32_bf16 v[36:39], v[208:211], v[178:181], v[36:39]
	v_mfma_f32_16x16x32_bf16 v[32:35], v[216:219], v[178:181], v[32:35]
	v_mfma_f32_16x16x32_bf16 v[20:23], v[208:211], v[186:189], v[20:23]
	v_mfma_f32_16x16x32_bf16 v[16:19], v[216:219], v[186:189], v[16:19]
	v_mfma_f32_16x16x32_bf16 v[4:7], v[208:211], v[200:203], v[4:7]
	v_mfma_f32_16x16x32_bf16 v[0:3], v[216:219], v[200:203], v[0:3]
	v_mfma_f32_16x16x32_bf16 v[52:55], v[212:215], v[174:177], v[52:55]
	v_mfma_f32_16x16x32_bf16 v[48:51], v[220:223], v[174:177], v[48:51]
	v_mfma_f32_16x16x32_bf16 v[36:39], v[212:215], v[182:185], v[36:39]
	v_mfma_f32_16x16x32_bf16 v[32:35], v[220:223], v[182:185], v[32:35]
	v_mfma_f32_16x16x32_bf16 v[20:23], v[212:215], v[196:199], v[20:23]
	v_mfma_f32_16x16x32_bf16 v[16:19], v[220:223], v[196:199], v[16:19]
	v_mfma_f32_16x16x32_bf16 v[4:7], v[212:215], v[204:207], v[4:7]
	v_mfma_f32_16x16x32_bf16 v[0:3], v[220:223], v[204:207], v[0:3]
	s_add_i32 s52, s52, 2
	s_add_u32 s26, s26, 0x100
	s_addc_u32 s27, s27, 0
	s_add_u32 s50, s50, 0x100
	s_addc_u32 s51, s51, 0
	s_cmp_gt_u32 s52, 29
	s_cbranch_scc0 .Ldup_nl_mlpin1
	s_cmpk_gt_u32 s12, 0xff
	s_cbranch_scc0 .Ldup_nl_mlpin1
	v_lshl_add_u32 v148, s24, 8, v145
	v_max_f32_e32 v124, v124, v124
	v_max_f32_e32 v120, v120, v120
	v_ashrrev_i32_e32 v149, 31, v148
	v_max_f32_e32 v124, 0, v124
	v_max_f32_e32 v120, 0, v120
	v_lshlrev_b64 v[156:157], 14, v[148:149]
	v_mul_f32_e32 v149, v124, v124
	v_mul_f32_e32 v124, v120, v120
	v_max_f32_e32 v120, v125, v125
	v_max_f32_e32 v121, v121, v121
	v_max_f32_e32 v120, 0, v120
	v_max_f32_e32 v121, 0, v121
	v_mul_f32_e32 v158, v120, v120
	v_mul_f32_e32 v159, v121, v121
	v_max_f32_e32 v120, v126, v126
	v_max_f32_e32 v121, v122, v122
	v_max_f32_e32 v120, 0, v120
	v_max_f32_e32 v121, 0, v121
	v_lshl_or_b32 v154, s33, 8, v150
	v_mul_f32_e32 v160, v120, v120
	v_mul_f32_e32 v125, v121, v121
	v_max_f32_e32 v120, v127, v127
	v_max_f32_e32 v121, v123, v123
	v_max_f32_e32 v116, v116, v116
	v_max_f32_e32 v112, v112, v112
	v_max_f32_e32 v117, v117, v117
	v_max_f32_e32 v113, v113, v113
	v_max_f32_e32 v118, v118, v118
	v_max_f32_e32 v114, v114, v114
	v_max_f32_e32 v119, v119, v119
	v_max_f32_e32 v115, v115, v115
	v_ashrrev_i32_e32 v155, 31, v154
	v_max_f32_e32 v120, 0, v120
	v_max_f32_e32 v121, 0, v121
	v_max_f32_e32 v116, 0, v116
	v_max_f32_e32 v112, 0, v112
	v_max_f32_e32 v117, 0, v117
	v_max_f32_e32 v113, 0, v113
	v_max_f32_e32 v118, 0, v118
	v_max_f32_e32 v114, 0, v114
	v_max_f32_e32 v119, 0, v119
	v_max_f32_e32 v115, 0, v115
	v_mul_f32_e32 v161, v120, v120
	v_mul_f32_e32 v162, v121, v121
	v_lshl_add_u64 v[122:123], s[28:29], 0, v[156:157]
	v_lshlrev_b64 v[120:121], 1, v[154:155]
	v_mul_f32_e32 v116, v116, v116
	v_mul_f32_e32 v112, v112, v112
	v_mul_f32_e32 v117, v117, v117
	v_mul_f32_e32 v113, v113, v113
	v_mul_f32_e32 v118, v118, v118
	v_mul_f32_e32 v114, v114, v114
	v_mul_f32_e32 v119, v119, v119
	v_mul_f32_e32 v115, v115, v115
	v_max_f32_e32 v104, v104, v104
	v_lshl_add_u64 v[126:127], v[122:123], 0, v[120:121]
	v_cvt_pk_bf16_f32 v115, v114, v115
	v_cvt_pk_bf16_f32 v114, v112, v113
	v_cvt_pk_bf16_f32 v113, v118, v119
	v_cvt_pk_bf16_f32 v112, v116, v117
	v_max_f32_e32 v104, 0, v104
	global_store_dwordx4 v[126:127], v[112:115], off offset:256
	v_max_f32_e32 v105, v105, v105
	v_max_f32_e32 v105, 0, v105
	v_mul_f32_e32 v115, v104, v104
	v_max_f32_e32 v104, v109, v109
	v_max_f32_e32 v104, 0, v104
	v_mul_f32_e32 v116, v104, v104
	v_mul_f32_e32 v117, v105, v105
	v_max_f32_e32 v104, v110, v110
	v_max_f32_e32 v105, v106, v106
	v_or_b32_e32 v112, 16, v148
	v_max_f32_e32 v104, 0, v104
	v_max_f32_e32 v105, 0, v105
	v_ashrrev_i32_e32 v113, 31, v112
	v_mul_f32_e32 v110, v104, v104
	v_mul_f32_e32 v106, v105, v105
	v_max_f32_e32 v104, v111, v111
	v_max_f32_e32 v105, v107, v107
	v_max_f32_e32 v100, v100, v100
	v_max_f32_e32 v96, v96, v96
	v_max_f32_e32 v101, v101, v101
	v_max_f32_e32 v97, v97, v97
	v_max_f32_e32 v102, v102, v102
	v_max_f32_e32 v98, v98, v98
	v_max_f32_e32 v103, v103, v103
	v_max_f32_e32 v99, v99, v99
	v_lshlrev_b64 v[112:113], 14, v[112:113]
	v_max_f32_e32 v108, v108, v108
	v_max_f32_e32 v104, 0, v104
	v_max_f32_e32 v105, 0, v105
	v_max_f32_e32 v100, 0, v100
	v_max_f32_e32 v96, 0, v96
	v_max_f32_e32 v101, 0, v101
	v_max_f32_e32 v97, 0, v97
	v_max_f32_e32 v102, 0, v102
	v_max_f32_e32 v98, 0, v98
	v_max_f32_e32 v103, 0, v103
	v_max_f32_e32 v99, 0, v99
	v_max_f32_e32 v108, 0, v108
	v_mul_f32_e32 v111, v104, v104
	v_mul_f32_e32 v107, v105, v105
	v_lshl_add_u64 v[104:105], s[28:29], 0, v[112:113]
	v_mul_f32_e32 v100, v100, v100
	v_mul_f32_e32 v96, v96, v96
	v_mul_f32_e32 v101, v101, v101
	v_mul_f32_e32 v97, v97, v97
	v_mul_f32_e32 v102, v102, v102
	v_mul_f32_e32 v98, v98, v98
	v_mul_f32_e32 v103, v103, v103
	v_mul_f32_e32 v99, v99, v99
	v_max_f32_e32 v88, v88, v88
	v_mul_f32_e32 v114, v108, v108
	v_lshl_add_u64 v[108:109], v[104:105], 0, v[120:121]
	v_cvt_pk_bf16_f32 v99, v98, v99
	v_cvt_pk_bf16_f32 v98, v96, v97
	v_cvt_pk_bf16_f32 v97, v102, v103
	v_cvt_pk_bf16_f32 v96, v100, v101
	v_max_f32_e32 v88, 0, v88
	global_store_dwordx4 v[108:109], v[96:99], off offset:256
	v_max_f32_e32 v89, v89, v89
	v_max_f32_e32 v89, 0, v89
	v_mul_f32_e32 v99, v88, v88
	v_max_f32_e32 v88, v93, v93
	v_max_f32_e32 v88, 0, v88
	v_mul_f32_e32 v100, v88, v88
	v_mul_f32_e32 v101, v89, v89
	v_max_f32_e32 v88, v94, v94
	v_max_f32_e32 v89, v90, v90
	v_or_b32_e32 v96, 32, v148
	v_max_f32_e32 v88, 0, v88
	v_max_f32_e32 v89, 0, v89
	v_ashrrev_i32_e32 v97, 31, v96
	v_mul_f32_e32 v94, v88, v88
	v_mul_f32_e32 v90, v89, v89
	v_max_f32_e32 v88, v95, v95
	v_max_f32_e32 v89, v91, v91
	v_max_f32_e32 v84, v84, v84
	v_max_f32_e32 v80, v80, v80
	v_max_f32_e32 v85, v85, v85
	v_max_f32_e32 v81, v81, v81
	v_max_f32_e32 v86, v86, v86
	v_max_f32_e32 v82, v82, v82
	v_max_f32_e32 v87, v87, v87
	v_max_f32_e32 v83, v83, v83
	v_lshlrev_b64 v[96:97], 14, v[96:97]
	v_max_f32_e32 v92, v92, v92
	v_max_f32_e32 v88, 0, v88
	v_max_f32_e32 v89, 0, v89
	v_max_f32_e32 v84, 0, v84
	v_max_f32_e32 v80, 0, v80
	v_max_f32_e32 v85, 0, v85
	v_max_f32_e32 v81, 0, v81
	v_max_f32_e32 v86, 0, v86
	v_max_f32_e32 v82, 0, v82
	v_max_f32_e32 v87, 0, v87
	v_max_f32_e32 v83, 0, v83
	v_max_f32_e32 v92, 0, v92
	v_mul_f32_e32 v95, v88, v88
	v_mul_f32_e32 v91, v89, v89
	v_lshl_add_u64 v[88:89], s[28:29], 0, v[96:97]
	v_mul_f32_e32 v84, v84, v84
	v_mul_f32_e32 v80, v80, v80
	v_mul_f32_e32 v85, v85, v85
	v_mul_f32_e32 v81, v81, v81
	v_mul_f32_e32 v86, v86, v86
	v_mul_f32_e32 v82, v82, v82
	v_mul_f32_e32 v87, v87, v87
	v_mul_f32_e32 v83, v83, v83
	v_max_f32_e32 v72, v72, v72
	v_mul_f32_e32 v98, v92, v92
	v_lshl_add_u64 v[92:93], v[88:89], 0, v[120:121]
	v_cvt_pk_bf16_f32 v83, v82, v83
	v_cvt_pk_bf16_f32 v82, v80, v81
	v_cvt_pk_bf16_f32 v81, v86, v87
	v_cvt_pk_bf16_f32 v80, v84, v85
	v_max_f32_e32 v72, 0, v72
	global_store_dwordx4 v[92:93], v[80:83], off offset:256
	v_max_f32_e32 v73, v73, v73
	v_max_f32_e32 v73, 0, v73
	v_mul_f32_e32 v83, v72, v72
	v_max_f32_e32 v72, v77, v77
	v_max_f32_e32 v72, 0, v72
	v_mul_f32_e32 v84, v72, v72
	v_mul_f32_e32 v85, v73, v73
	v_max_f32_e32 v72, v78, v78
	v_max_f32_e32 v73, v74, v74
	v_or_b32_e32 v80, 48, v148
	v_max_f32_e32 v72, 0, v72
	v_max_f32_e32 v73, 0, v73
	v_ashrrev_i32_e32 v81, 31, v80
	v_mul_f32_e32 v78, v72, v72
	v_mul_f32_e32 v74, v73, v73
	v_max_f32_e32 v72, v79, v79
	v_max_f32_e32 v73, v75, v75
	v_max_f32_e32 v68, v68, v68
	v_max_f32_e32 v64, v64, v64
	v_max_f32_e32 v69, v69, v69
	v_max_f32_e32 v65, v65, v65
	v_max_f32_e32 v70, v70, v70
	v_max_f32_e32 v66, v66, v66
	v_max_f32_e32 v71, v71, v71
	v_max_f32_e32 v67, v67, v67
	v_lshlrev_b64 v[80:81], 14, v[80:81]
	v_max_f32_e32 v76, v76, v76
	v_max_f32_e32 v72, 0, v72
	v_max_f32_e32 v73, 0, v73
	v_max_f32_e32 v68, 0, v68
	v_max_f32_e32 v64, 0, v64
	v_max_f32_e32 v69, 0, v69
	v_max_f32_e32 v65, 0, v65
	v_max_f32_e32 v70, 0, v70
	v_max_f32_e32 v66, 0, v66
	v_max_f32_e32 v71, 0, v71
	v_max_f32_e32 v67, 0, v67
	v_max_f32_e32 v76, 0, v76
	v_mul_f32_e32 v79, v72, v72
	v_mul_f32_e32 v75, v73, v73
	v_lshl_add_u64 v[72:73], s[28:29], 0, v[80:81]
	v_mul_f32_e32 v68, v68, v68
	v_mul_f32_e32 v64, v64, v64
	v_mul_f32_e32 v69, v69, v69
	v_mul_f32_e32 v65, v65, v65
	v_mul_f32_e32 v70, v70, v70
	v_mul_f32_e32 v66, v66, v66
	v_mul_f32_e32 v71, v71, v71
	v_mul_f32_e32 v67, v67, v67
	v_max_f32_e32 v56, v56, v56
	v_mul_f32_e32 v82, v76, v76
	v_lshl_add_u64 v[76:77], v[72:73], 0, v[120:121]
	v_cvt_pk_bf16_f32 v67, v66, v67
	v_cvt_pk_bf16_f32 v66, v64, v65
	v_cvt_pk_bf16_f32 v65, v70, v71
	v_cvt_pk_bf16_f32 v64, v68, v69
	v_max_f32_e32 v56, 0, v56
	global_store_dwordx4 v[76:77], v[64:67], off offset:256
	v_max_f32_e32 v57, v57, v57
	v_max_f32_e32 v57, 0, v57
	v_mul_f32_e32 v67, v56, v56
	v_max_f32_e32 v56, v61, v61
	v_max_f32_e32 v56, 0, v56
	v_mul_f32_e32 v68, v56, v56
	v_mul_f32_e32 v69, v57, v57
	v_max_f32_e32 v56, v62, v62
	v_max_f32_e32 v57, v58, v58
	v_add_u32_e32 v64, 0x80, v148
	v_max_f32_e32 v56, 0, v56
	v_max_f32_e32 v57, 0, v57
	v_ashrrev_i32_e32 v65, 31, v64
	v_mul_f32_e32 v62, v56, v56
	v_mul_f32_e32 v58, v57, v57
	v_max_f32_e32 v56, v63, v63
	v_max_f32_e32 v57, v59, v59
	v_max_f32_e32 v52, v52, v52
	v_max_f32_e32 v48, v48, v48
	v_max_f32_e32 v53, v53, v53
	v_max_f32_e32 v49, v49, v49
	v_max_f32_e32 v54, v54, v54
	v_max_f32_e32 v50, v50, v50
	v_max_f32_e32 v55, v55, v55
	v_max_f32_e32 v51, v51, v51
	v_lshlrev_b64 v[64:65], 14, v[64:65]
	v_max_f32_e32 v60, v60, v60
	v_max_f32_e32 v56, 0, v56
	v_max_f32_e32 v57, 0, v57
	v_max_f32_e32 v52, 0, v52
	v_max_f32_e32 v48, 0, v48
	v_max_f32_e32 v53, 0, v53
	v_max_f32_e32 v49, 0, v49
	v_max_f32_e32 v54, 0, v54
	v_max_f32_e32 v50, 0, v50
	v_max_f32_e32 v55, 0, v55
	v_max_f32_e32 v51, 0, v51
	v_max_f32_e32 v60, 0, v60
	v_mul_f32_e32 v63, v56, v56
	v_mul_f32_e32 v59, v57, v57
	v_lshl_add_u64 v[56:57], s[28:29], 0, v[64:65]
	v_mul_f32_e32 v52, v52, v52
	v_mul_f32_e32 v48, v48, v48
	v_mul_f32_e32 v53, v53, v53
	v_mul_f32_e32 v49, v49, v49
	v_mul_f32_e32 v54, v54, v54
	v_mul_f32_e32 v50, v50, v50
	v_mul_f32_e32 v55, v55, v55
	v_mul_f32_e32 v51, v51, v51
	v_max_f32_e32 v40, v40, v40
	v_mul_f32_e32 v66, v60, v60
	v_lshl_add_u64 v[60:61], v[56:57], 0, v[120:121]
	v_cvt_pk_bf16_f32 v51, v50, v51
	v_cvt_pk_bf16_f32 v50, v48, v49
	v_cvt_pk_bf16_f32 v49, v54, v55
	v_cvt_pk_bf16_f32 v48, v52, v53
	v_max_f32_e32 v40, 0, v40
	global_store_dwordx4 v[60:61], v[48:51], off offset:256
	v_max_f32_e32 v41, v41, v41
	v_max_f32_e32 v41, 0, v41
	v_mul_f32_e32 v51, v40, v40
	v_max_f32_e32 v40, v45, v45
	v_max_f32_e32 v40, 0, v40
	v_mul_f32_e32 v52, v40, v40
	v_mul_f32_e32 v53, v41, v41
	v_max_f32_e32 v40, v46, v46
	v_max_f32_e32 v41, v42, v42
	v_add_u32_e32 v48, 0x90, v148
	v_max_f32_e32 v40, 0, v40
	v_max_f32_e32 v41, 0, v41
	v_ashrrev_i32_e32 v49, 31, v48
	v_mul_f32_e32 v46, v40, v40
	v_mul_f32_e32 v42, v41, v41
	v_max_f32_e32 v40, v47, v47
	v_max_f32_e32 v41, v43, v43
	v_max_f32_e32 v36, v36, v36
	v_max_f32_e32 v32, v32, v32
	v_max_f32_e32 v37, v37, v37
	v_max_f32_e32 v33, v33, v33
	v_max_f32_e32 v38, v38, v38
	v_max_f32_e32 v34, v34, v34
	v_max_f32_e32 v39, v39, v39
	v_max_f32_e32 v35, v35, v35
	v_lshlrev_b64 v[48:49], 14, v[48:49]
	v_max_f32_e32 v44, v44, v44
	v_max_f32_e32 v40, 0, v40
	v_max_f32_e32 v41, 0, v41
	v_max_f32_e32 v36, 0, v36
	v_max_f32_e32 v32, 0, v32
	v_max_f32_e32 v37, 0, v37
	v_max_f32_e32 v33, 0, v33
	v_max_f32_e32 v38, 0, v38
	v_max_f32_e32 v34, 0, v34
	v_max_f32_e32 v39, 0, v39
	v_max_f32_e32 v35, 0, v35
	v_max_f32_e32 v44, 0, v44
	v_mul_f32_e32 v47, v40, v40
	v_mul_f32_e32 v43, v41, v41
	v_lshl_add_u64 v[40:41], s[28:29], 0, v[48:49]
	v_mul_f32_e32 v36, v36, v36
	v_mul_f32_e32 v32, v32, v32
	v_mul_f32_e32 v37, v37, v37
	v_mul_f32_e32 v33, v33, v33
	v_mul_f32_e32 v38, v38, v38
	v_mul_f32_e32 v34, v34, v34
	v_mul_f32_e32 v39, v39, v39
	v_mul_f32_e32 v35, v35, v35
	v_max_f32_e32 v24, v24, v24
	v_mul_f32_e32 v50, v44, v44
	v_lshl_add_u64 v[44:45], v[40:41], 0, v[120:121]
	v_cvt_pk_bf16_f32 v35, v34, v35
	v_cvt_pk_bf16_f32 v34, v32, v33
	v_cvt_pk_bf16_f32 v33, v38, v39
	v_cvt_pk_bf16_f32 v32, v36, v37
	v_max_f32_e32 v24, 0, v24
	global_store_dwordx4 v[44:45], v[32:35], off offset:256
	v_max_f32_e32 v25, v25, v25
	v_max_f32_e32 v25, 0, v25
	v_mul_f32_e32 v35, v24, v24
	v_max_f32_e32 v24, v29, v29
	v_max_f32_e32 v24, 0, v24
	v_mul_f32_e32 v36, v24, v24
	v_mul_f32_e32 v37, v25, v25
	v_max_f32_e32 v24, v30, v30
	v_max_f32_e32 v25, v26, v26
	v_add_u32_e32 v32, 0xa0, v148
	v_max_f32_e32 v24, 0, v24
	v_max_f32_e32 v25, 0, v25
	v_ashrrev_i32_e32 v33, 31, v32
	v_mul_f32_e32 v30, v24, v24
	v_mul_f32_e32 v26, v25, v25
	v_max_f32_e32 v24, v31, v31
	v_max_f32_e32 v25, v27, v27
	v_max_f32_e32 v20, v20, v20
	v_max_f32_e32 v16, v16, v16
	v_max_f32_e32 v21, v21, v21
	v_max_f32_e32 v17, v17, v17
	v_max_f32_e32 v22, v22, v22
	v_max_f32_e32 v18, v18, v18
	v_max_f32_e32 v23, v23, v23
	v_max_f32_e32 v19, v19, v19
	v_lshlrev_b64 v[32:33], 14, v[32:33]
	v_max_f32_e32 v28, v28, v28
	v_max_f32_e32 v24, 0, v24
	v_max_f32_e32 v25, 0, v25
	v_max_f32_e32 v20, 0, v20
	v_max_f32_e32 v16, 0, v16
	v_max_f32_e32 v21, 0, v21
	v_max_f32_e32 v17, 0, v17
	v_max_f32_e32 v22, 0, v22
	v_max_f32_e32 v18, 0, v18
	v_max_f32_e32 v23, 0, v23
	v_max_f32_e32 v19, 0, v19
	v_max_f32_e32 v28, 0, v28
	v_mul_f32_e32 v31, v24, v24
	v_mul_f32_e32 v27, v25, v25
	v_lshl_add_u64 v[24:25], s[28:29], 0, v[32:33]
	v_mul_f32_e32 v20, v20, v20
	v_mul_f32_e32 v16, v16, v16
	v_mul_f32_e32 v21, v21, v21
	v_mul_f32_e32 v17, v17, v17
	v_mul_f32_e32 v22, v22, v22
	v_mul_f32_e32 v18, v18, v18
	v_mul_f32_e32 v23, v23, v23
	v_mul_f32_e32 v19, v19, v19
	v_max_f32_e32 v8, v8, v8
	v_mul_f32_e32 v34, v28, v28
	v_lshl_add_u64 v[28:29], v[24:25], 0, v[120:121]
	v_cvt_pk_bf16_f32 v19, v18, v19
	v_cvt_pk_bf16_f32 v18, v16, v17
	v_cvt_pk_bf16_f32 v17, v22, v23
	v_cvt_pk_bf16_f32 v16, v20, v21
	v_max_f32_e32 v8, 0, v8
	global_store_dwordx4 v[28:29], v[16:19], off offset:256
	v_max_f32_e32 v9, v9, v9
	v_max_f32_e32 v9, 0, v9
	v_mul_f32_e32 v19, v8, v8
	v_max_f32_e32 v8, v13, v13
	v_max_f32_e32 v8, 0, v8
	v_mul_f32_e32 v20, v8, v8
	v_mul_f32_e32 v21, v9, v9
	v_max_f32_e32 v8, v14, v14
	v_max_f32_e32 v9, v10, v10
	v_add_u32_e32 v16, 0xb0, v148
	v_max_f32_e32 v8, 0, v8
	v_max_f32_e32 v9, 0, v9
	v_ashrrev_i32_e32 v17, 31, v16
	v_max_f32_e32 v12, v12, v12
	v_mul_f32_e32 v14, v8, v8
	v_mul_f32_e32 v10, v9, v9
	v_max_f32_e32 v8, v15, v15
	v_max_f32_e32 v9, v11, v11
	v_max_f32_e32 v4, v4, v4
	v_max_f32_e32 v0, v0, v0
	v_max_f32_e32 v5, v5, v5
	v_max_f32_e32 v1, v1, v1
	v_max_f32_e32 v6, v6, v6
	v_max_f32_e32 v2, v2, v2
	v_max_f32_e32 v7, v7, v7
	v_max_f32_e32 v3, v3, v3
	v_lshlrev_b64 v[16:17], 14, v[16:17]
	v_max_f32_e32 v12, 0, v12
	v_max_f32_e32 v8, 0, v8
	v_max_f32_e32 v9, 0, v9
	v_max_f32_e32 v4, 0, v4
	v_max_f32_e32 v0, 0, v0
	v_max_f32_e32 v5, 0, v5
	v_max_f32_e32 v1, 0, v1
	v_max_f32_e32 v6, 0, v6
	v_max_f32_e32 v2, 0, v2
	v_max_f32_e32 v7, 0, v7
	v_max_f32_e32 v3, 0, v3
	v_mul_f32_e32 v18, v12, v12
	v_mul_f32_e32 v15, v8, v8
	v_mul_f32_e32 v11, v9, v9
	v_lshl_add_u64 v[8:9], s[28:29], 0, v[16:17]
	v_mul_f32_e32 v4, v4, v4
	v_mul_f32_e32 v0, v0, v0
	v_mul_f32_e32 v5, v5, v5
	v_mul_f32_e32 v1, v1, v1
	v_mul_f32_e32 v6, v6, v6
	v_mul_f32_e32 v2, v2, v2
	v_mul_f32_e32 v7, v7, v7
	v_mul_f32_e32 v3, v3, v3
	v_cvt_pk_bf16_f32 v125, v125, v162
	v_cvt_pk_bf16_f32 v124, v124, v159
	v_cvt_pk_bf16_f32 v123, v160, v161
	v_cvt_pk_bf16_f32 v122, v149, v158
	v_cvt_pk_bf16_f32 v107, v106, v107
	v_cvt_pk_bf16_f32 v106, v115, v117
	v_cvt_pk_bf16_f32 v105, v110, v111
	v_cvt_pk_bf16_f32 v104, v114, v116
	v_cvt_pk_bf16_f32 v91, v90, v91
	v_cvt_pk_bf16_f32 v90, v99, v101
	v_cvt_pk_bf16_f32 v89, v94, v95
	v_cvt_pk_bf16_f32 v88, v98, v100
	v_cvt_pk_bf16_f32 v75, v74, v75
	v_cvt_pk_bf16_f32 v74, v83, v85
	v_cvt_pk_bf16_f32 v73, v78, v79
	v_cvt_pk_bf16_f32 v72, v82, v84
	v_cvt_pk_bf16_f32 v59, v58, v59
	v_cvt_pk_bf16_f32 v58, v67, v69
	v_cvt_pk_bf16_f32 v57, v62, v63
	v_cvt_pk_bf16_f32 v56, v66, v68
	v_cvt_pk_bf16_f32 v43, v42, v43
	v_cvt_pk_bf16_f32 v42, v51, v53
	v_cvt_pk_bf16_f32 v41, v46, v47
	v_cvt_pk_bf16_f32 v40, v50, v52
	v_cvt_pk_bf16_f32 v27, v26, v27
	v_cvt_pk_bf16_f32 v26, v35, v37
	v_cvt_pk_bf16_f32 v25, v30, v31
	v_cvt_pk_bf16_f32 v24, v34, v36
	v_lshl_add_u64 v[12:13], v[8:9], 0, v[120:121]
	v_cvt_pk_bf16_f32 v11, v10, v11
	v_cvt_pk_bf16_f32 v10, v19, v21
	v_cvt_pk_bf16_f32 v9, v14, v15
	v_cvt_pk_bf16_f32 v8, v18, v20
	v_cvt_pk_bf16_f32 v3, v2, v3
	v_cvt_pk_bf16_f32 v2, v0, v1
	v_cvt_pk_bf16_f32 v1, v6, v7
	v_cvt_pk_bf16_f32 v0, v4, v5
	global_store_dwordx4 v[126:127], v[122:125], off
	global_store_dwordx4 v[108:109], v[104:107], off
	global_store_dwordx4 v[92:93], v[88:91], off
	global_store_dwordx4 v[76:77], v[72:75], off
	global_store_dwordx4 v[60:61], v[56:59], off
	global_store_dwordx4 v[44:45], v[40:43], off
	global_store_dwordx4 v[28:29], v[24:27], off
	global_store_dwordx4 v[12:13], v[8:11], off
	global_store_dwordx4 v[12:13], v[0:3], off offset:256

.LBB0_1433:
	ds_read_b128 v[148:151], v158
	ds_read_b128 v[152:155], v158 offset:1024
	ds_read_b128 v[162:165], v158 offset:2048
	ds_read_b128 v[166:169], v158 offset:3072
	s_add_u32 s20, s26, 0xffe00080
	s_addc_u32 s21, s27, -1
	s_cmpk_eq_i32 s53, 0x7c
	s_cselect_b32 s21, s15, s21
	s_cselect_b32 s20, s49, s20
	s_cselect_b32 s31, s11, s52
	s_cselect_b32 s30, s50, s51
	v_lshl_add_u64 v[204:205], s[26:27], 0, v[136:137]
	s_add_i32 m0, s25, 0xc000
	ds_read_b128 v[170:173], v159
	ds_read_b128 v[174:177], v159 offset:1024
	ds_read_b128 v[178:181], v159 offset:2048
	ds_read_b128 v[182:185], v159 offset:3072
	ds_read_b128 v[186:189], v159 offset:4096
	ds_read_b128 v[190:193], v159 offset:5120
	ds_read_b128 v[196:199], v159 offset:6144
	ds_read_b128 v[200:203], v159 offset:7168
	global_load_lds_dwordx4 v[204:205], off
	s_add_i32 m0, s25, 0xe000
	v_lshl_add_u64 v[204:205], s[26:27], 0, v[138:139]
	global_load_lds_dwordx4 v[204:205], off
	s_waitcnt lgkmcnt(8)
	s_barrier
	s_waitcnt lgkmcnt(0)
	v_mfma_f32_16x16x32_bf16 v[124:127], v[148:151], v[170:173], v[124:127]
	v_mfma_f32_16x16x32_bf16 v[120:123], v[162:165], v[170:173], v[120:123]
	v_mfma_f32_16x16x32_bf16 v[108:111], v[148:151], v[178:181], v[108:111]
	v_mfma_f32_16x16x32_bf16 v[104:107], v[162:165], v[178:181], v[104:107]
	v_mfma_f32_16x16x32_bf16 v[92:95], v[148:151], v[186:189], v[92:95]
	v_mfma_f32_16x16x32_bf16 v[88:91], v[162:165], v[186:189], v[88:91]
	v_mfma_f32_16x16x32_bf16 v[76:79], v[148:151], v[196:199], v[76:79]
	v_mfma_f32_16x16x32_bf16 v[72:75], v[162:165], v[196:199], v[72:75]
	v_mfma_f32_16x16x32_bf16 v[124:127], v[152:155], v[174:177], v[124:127]
	v_mfma_f32_16x16x32_bf16 v[120:123], v[166:169], v[174:177], v[120:123]
	v_mfma_f32_16x16x32_bf16 v[108:111], v[152:155], v[182:185], v[108:111]
	v_mfma_f32_16x16x32_bf16 v[104:107], v[166:169], v[182:185], v[104:107]
	v_mfma_f32_16x16x32_bf16 v[92:95], v[152:155], v[190:193], v[92:95]
	v_mfma_f32_16x16x32_bf16 v[88:91], v[166:169], v[190:193], v[88:91]
	v_mfma_f32_16x16x32_bf16 v[76:79], v[152:155], v[200:203], v[76:79]
	v_mfma_f32_16x16x32_bf16 v[72:75], v[166:169], v[200:203], v[72:75]
	s_barrier
	s_add_i32 s54, s45, s23
	v_lshl_add_u64 v[220:221], s[30:31], 0, v[132:133]
	s_mov_b32 m0, s54
	ds_read_b128 v[204:207], v160
	ds_read_b128 v[208:211], v160 offset:1024
	ds_read_b128 v[212:215], v160 offset:2048
	ds_read_b128 v[216:219], v160 offset:3072
	global_load_lds_dwordx4 v[220:221], off
	s_add_i32 m0, s54, 0x2000
	v_lshl_add_u64 v[222:223], s[30:31], 0, v[128:129]
	global_load_lds_dwordx4 v[222:223], off
	s_barrier
	s_waitcnt lgkmcnt(0)
	v_mfma_f32_16x16x32_bf16 v[116:119], v[204:207], v[170:173], v[116:119]
	v_mfma_f32_16x16x32_bf16 v[112:115], v[212:215], v[170:173], v[112:115]
	v_mfma_f32_16x16x32_bf16 v[100:103], v[204:207], v[178:181], v[100:103]
	v_mfma_f32_16x16x32_bf16 v[96:99], v[212:215], v[178:181], v[96:99]
	v_mfma_f32_16x16x32_bf16 v[84:87], v[204:207], v[186:189], v[84:87]
	v_mfma_f32_16x16x32_bf16 v[80:83], v[212:215], v[186:189], v[80:83]
	v_mfma_f32_16x16x32_bf16 v[68:71], v[204:207], v[196:199], v[68:71]
	v_mfma_f32_16x16x32_bf16 v[64:67], v[212:215], v[196:199], v[64:67]
	v_mfma_f32_16x16x32_bf16 v[116:119], v[208:211], v[174:177], v[116:119]
	v_mfma_f32_16x16x32_bf16 v[112:115], v[216:219], v[174:177], v[112:115]
	v_mfma_f32_16x16x32_bf16 v[100:103], v[208:211], v[182:185], v[100:103]
	v_mfma_f32_16x16x32_bf16 v[96:99], v[216:219], v[182:185], v[96:99]
	v_mfma_f32_16x16x32_bf16 v[84:87], v[208:211], v[190:193], v[84:87]
	v_mfma_f32_16x16x32_bf16 v[80:83], v[216:219], v[190:193], v[80:83]
	v_mfma_f32_16x16x32_bf16 v[68:71], v[208:211], v[200:203], v[68:71]
	v_mfma_f32_16x16x32_bf16 v[64:67], v[216:219], v[200:203], v[64:67]
	s_mov_b32 m0, s25
	v_lshl_add_u64 v[224:225], s[20:21], 0, v[134:135]
	s_barrier
	ds_read_b128 v[170:173], v159 offset:16384
	ds_read_b128 v[174:177], v159 offset:17408
	ds_read_b128 v[178:181], v159 offset:18432
	ds_read_b128 v[182:185], v159 offset:19456
	ds_read_b128 v[186:189], v159 offset:20480
	ds_read_b128 v[190:193], v159 offset:21504
	ds_read_b128 v[196:199], v159 offset:22528
	ds_read_b128 v[200:203], v159 offset:23552
	global_load_lds_dwordx4 v[224:225], off
	s_mov_b32 m0, s37
	v_lshl_add_u64 v[226:227], s[20:21], 0, v[130:131]
	global_load_lds_dwordx4 v[226:227], off
	s_barrier
	s_waitcnt lgkmcnt(0)
	v_mfma_f32_16x16x32_bf16 v[60:63], v[148:151], v[170:173], v[60:63]
	v_mfma_f32_16x16x32_bf16 v[56:59], v[162:165], v[170:173], v[56:59]
	v_mfma_f32_16x16x32_bf16 v[44:47], v[148:151], v[178:181], v[44:47]
	v_mfma_f32_16x16x32_bf16 v[40:43], v[162:165], v[178:181], v[40:43]
	v_mfma_f32_16x16x32_bf16 v[28:31], v[148:151], v[186:189], v[28:31]
	v_mfma_f32_16x16x32_bf16 v[24:27], v[162:165], v[186:189], v[24:27]
	v_mfma_f32_16x16x32_bf16 v[12:15], v[148:151], v[196:199], v[12:15]
	v_mfma_f32_16x16x32_bf16 v[8:11], v[162:165], v[196:199], v[8:11]
	v_mfma_f32_16x16x32_bf16 v[60:63], v[152:155], v[174:177], v[60:63]
	v_mfma_f32_16x16x32_bf16 v[56:59], v[166:169], v[174:177], v[56:59]
	v_mfma_f32_16x16x32_bf16 v[44:47], v[152:155], v[182:185], v[44:47]
	v_mfma_f32_16x16x32_bf16 v[40:43], v[166:169], v[182:185], v[40:43]
	v_mfma_f32_16x16x32_bf16 v[28:31], v[152:155], v[190:193], v[28:31]
	v_mfma_f32_16x16x32_bf16 v[24:27], v[166:169], v[190:193], v[24:27]
	v_mfma_f32_16x16x32_bf16 v[12:15], v[152:155], v[200:203], v[12:15]
	v_mfma_f32_16x16x32_bf16 v[8:11], v[166:169], v[200:203], v[8:11]
	s_barrier
	s_add_u32 s54, s30, 0x200000
	s_addc_u32 s55, s31, 0
	s_add_i32 s56, s47, s23
	s_mov_b32 m0, s56
	v_lshl_add_u64 v[148:149], s[54:55], 0, v[132:133]
	global_load_lds_dwordx4 v[148:149], off
	s_add_i32 m0, s56, 0x2000
	v_lshl_add_u64 v[148:149], s[54:55], 0, v[128:129]
	global_load_lds_dwordx4 v[148:149], off
	s_waitcnt vmcnt(6)
	s_barrier
	v_mfma_f32_16x16x32_bf16 v[52:55], v[204:207], v[170:173], v[52:55]
	v_mfma_f32_16x16x32_bf16 v[48:51], v[212:215], v[170:173], v[48:51]
	v_mfma_f32_16x16x32_bf16 v[36:39], v[204:207], v[178:181], v[36:39]
	v_mfma_f32_16x16x32_bf16 v[32:35], v[212:215], v[178:181], v[32:35]
	v_mfma_f32_16x16x32_bf16 v[20:23], v[204:207], v[186:189], v[20:23]
	v_mfma_f32_16x16x32_bf16 v[16:19], v[212:215], v[186:189], v[16:19]
	v_mfma_f32_16x16x32_bf16 v[4:7], v[204:207], v[196:199], v[4:7]
	v_mfma_f32_16x16x32_bf16 v[0:3], v[212:215], v[196:199], v[0:3]
	v_mfma_f32_16x16x32_bf16 v[52:55], v[208:211], v[174:177], v[52:55]
	v_mfma_f32_16x16x32_bf16 v[48:51], v[216:219], v[174:177], v[48:51]
	v_mfma_f32_16x16x32_bf16 v[36:39], v[208:211], v[182:185], v[36:39]
	v_mfma_f32_16x16x32_bf16 v[32:35], v[216:219], v[182:185], v[32:35]
	v_mfma_f32_16x16x32_bf16 v[20:23], v[208:211], v[190:193], v[20:23]
	v_mfma_f32_16x16x32_bf16 v[16:19], v[216:219], v[190:193], v[16:19]
	v_mfma_f32_16x16x32_bf16 v[4:7], v[208:211], v[200:203], v[4:7]
	v_mfma_f32_16x16x32_bf16 v[0:3], v[216:219], v[200:203], v[0:3]
	s_add_i32 s54, 0, 0x18000
	v_add_u32_e32 v161, s54, v147
	s_barrier
	ds_read_b128 v[148:151], v161
	ds_read_b128 v[152:155], v161 offset:1024
	ds_read_b128 v[162:165], v161 offset:2048
	ds_read_b128 v[166:169], v161 offset:3072
	s_add_u32 s20, s20, 0x200000
	s_addc_u32 s21, s21, 0
	s_mov_b32 m0, s38
	v_lshl_add_u64 v[204:205], s[20:21], 0, v[134:135]
	ds_read_b128 v[170:173], v159 offset:32768
	ds_read_b128 v[174:177], v159 offset:33792
	ds_read_b128 v[178:181], v159 offset:34816
	ds_read_b128 v[182:185], v159 offset:35840
	ds_read_b128 v[186:189], v159 offset:36864
	ds_read_b128 v[190:193], v159 offset:37888
	ds_read_b128 v[196:199], v159 offset:38912
	ds_read_b128 v[200:203], v159 offset:39936
	global_load_lds_dwordx4 v[204:205], off
	s_mov_b32 m0, s39
	v_lshl_add_u64 v[204:205], s[20:21], 0, v[130:131]
	global_load_lds_dwordx4 v[204:205], off
	s_waitcnt lgkmcnt(8)
	s_barrier
	s_waitcnt lgkmcnt(0)
	v_mfma_f32_16x16x32_bf16 v[124:127], v[148:151], v[170:173], v[124:127]
	v_mfma_f32_16x16x32_bf16 v[120:123], v[162:165], v[170:173], v[120:123]
	v_mfma_f32_16x16x32_bf16 v[108:111], v[148:151], v[178:181], v[108:111]
	v_mfma_f32_16x16x32_bf16 v[104:107], v[162:165], v[178:181], v[104:107]
	v_mfma_f32_16x16x32_bf16 v[92:95], v[148:151], v[186:189], v[92:95]
	v_mfma_f32_16x16x32_bf16 v[88:91], v[162:165], v[186:189], v[88:91]
	v_mfma_f32_16x16x32_bf16 v[76:79], v[148:151], v[196:199], v[76:79]
	v_mfma_f32_16x16x32_bf16 v[72:75], v[162:165], v[196:199], v[72:75]
	v_mfma_f32_16x16x32_bf16 v[124:127], v[152:155], v[174:177], v[124:127]
	v_mfma_f32_16x16x32_bf16 v[120:123], v[166:169], v[174:177], v[120:123]
	v_mfma_f32_16x16x32_bf16 v[108:111], v[152:155], v[182:185], v[108:111]
	v_mfma_f32_16x16x32_bf16 v[104:107], v[166:169], v[182:185], v[104:107]
	v_mfma_f32_16x16x32_bf16 v[92:95], v[152:155], v[190:193], v[92:95]
	v_mfma_f32_16x16x32_bf16 v[88:91], v[166:169], v[190:193], v[88:91]
	v_mfma_f32_16x16x32_bf16 v[76:79], v[152:155], v[200:203], v[76:79]
	v_mfma_f32_16x16x32_bf16 v[72:75], v[166:169], v[200:203], v[72:75]
	s_barrier
	s_add_i32 s55, 0, 0x1c000
	s_add_i32 s20, s54, s23
	v_add_u32_e32 v161, s55, v147
	v_lshl_add_u64 v[220:221], v[220:221], 0, s[8:9]
	s_mov_b32 m0, s20
	ds_read_b128 v[204:207], v161
	ds_read_b128 v[208:211], v161 offset:1024
	ds_read_b128 v[212:215], v161 offset:2048
	ds_read_b128 v[216:219], v161 offset:3072
	global_load_lds_dwordx4 v[220:221], off
	s_add_i32 m0, s20, 0x2000
	v_lshl_add_u64 v[220:221], v[222:223], 0, s[8:9]
	global_load_lds_dwordx4 v[220:221], off
	s_barrier
	s_waitcnt lgkmcnt(0)
	v_mfma_f32_16x16x32_bf16 v[116:119], v[204:207], v[170:173], v[116:119]
	v_mfma_f32_16x16x32_bf16 v[112:115], v[212:215], v[170:173], v[112:115]
	v_mfma_f32_16x16x32_bf16 v[100:103], v[204:207], v[178:181], v[100:103]
	v_mfma_f32_16x16x32_bf16 v[96:99], v[212:215], v[178:181], v[96:99]
	v_mfma_f32_16x16x32_bf16 v[84:87], v[204:207], v[186:189], v[84:87]
	v_mfma_f32_16x16x32_bf16 v[80:83], v[212:215], v[186:189], v[80:83]
	v_mfma_f32_16x16x32_bf16 v[68:71], v[204:207], v[196:199], v[68:71]
	v_mfma_f32_16x16x32_bf16 v[64:67], v[212:215], v[196:199], v[64:67]
	v_mfma_f32_16x16x32_bf16 v[116:119], v[208:211], v[174:177], v[116:119]
	v_mfma_f32_16x16x32_bf16 v[112:115], v[216:219], v[174:177], v[112:115]
	v_mfma_f32_16x16x32_bf16 v[100:103], v[208:211], v[182:185], v[100:103]
	v_mfma_f32_16x16x32_bf16 v[96:99], v[216:219], v[182:185], v[96:99]
	v_mfma_f32_16x16x32_bf16 v[84:87], v[208:211], v[190:193], v[84:87]
	v_mfma_f32_16x16x32_bf16 v[80:83], v[216:219], v[190:193], v[80:83]
	v_mfma_f32_16x16x32_bf16 v[68:71], v[208:211], v[200:203], v[68:71]
	v_mfma_f32_16x16x32_bf16 v[64:67], v[216:219], v[200:203], v[64:67]
	s_mov_b32 m0, s35
	v_lshl_add_u64 v[220:221], v[224:225], 0, s[8:9]
	s_barrier
	ds_read_b128 v[170:173], v159 offset:49152
	ds_read_b128 v[174:177], v159 offset:50176
	ds_read_b128 v[178:181], v159 offset:51200
	ds_read_b128 v[182:185], v159 offset:52224
	ds_read_b128 v[186:189], v159 offset:53248
	ds_read_b128 v[190:193], v159 offset:54272
	ds_read_b128 v[196:199], v159 offset:55296
	ds_read_b128 v[200:203], v159 offset:56320
	global_load_lds_dwordx4 v[220:221], off
	s_mov_b32 m0, s41
	v_lshl_add_u64 v[220:221], v[226:227], 0, s[8:9]
	global_load_lds_dwordx4 v[220:221], off
	s_barrier
	s_waitcnt lgkmcnt(0)
	v_mfma_f32_16x16x32_bf16 v[60:63], v[148:151], v[170:173], v[60:63]
	v_mfma_f32_16x16x32_bf16 v[56:59], v[162:165], v[170:173], v[56:59]
	v_mfma_f32_16x16x32_bf16 v[44:47], v[148:151], v[178:181], v[44:47]
	v_mfma_f32_16x16x32_bf16 v[40:43], v[162:165], v[178:181], v[40:43]
	v_mfma_f32_16x16x32_bf16 v[28:31], v[148:151], v[186:189], v[28:31]
	v_mfma_f32_16x16x32_bf16 v[24:27], v[162:165], v[186:189], v[24:27]
	v_mfma_f32_16x16x32_bf16 v[12:15], v[148:151], v[196:199], v[12:15]
	v_mfma_f32_16x16x32_bf16 v[8:11], v[162:165], v[196:199], v[8:11]
	v_mfma_f32_16x16x32_bf16 v[60:63], v[152:155], v[174:177], v[60:63]
	v_mfma_f32_16x16x32_bf16 v[56:59], v[166:169], v[174:177], v[56:59]
	v_mfma_f32_16x16x32_bf16 v[44:47], v[152:155], v[182:185], v[44:47]
	v_mfma_f32_16x16x32_bf16 v[40:43], v[166:169], v[182:185], v[40:43]
	v_mfma_f32_16x16x32_bf16 v[28:31], v[152:155], v[190:193], v[28:31]
	v_mfma_f32_16x16x32_bf16 v[24:27], v[166:169], v[190:193], v[24:27]
	v_mfma_f32_16x16x32_bf16 v[12:15], v[152:155], v[200:203], v[12:15]
	v_mfma_f32_16x16x32_bf16 v[8:11], v[166:169], v[200:203], v[8:11]
	s_barrier
	s_add_u32 s20, s30, 0x200080
	s_addc_u32 s21, s31, 0
	s_add_i32 s30, s55, s23
	s_mov_b32 m0, s30
	v_lshl_add_u64 v[148:149], s[20:21], 0, v[132:133]
	global_load_lds_dwordx4 v[148:149], off
	s_add_i32 m0, s30, 0x2000
	v_lshl_add_u64 v[148:149], s[20:21], 0, v[128:129]
	global_load_lds_dwordx4 v[148:149], off
	s_waitcnt vmcnt(6)
	s_barrier
	v_mfma_f32_16x16x32_bf16 v[52:55], v[204:207], v[170:173], v[52:55]
	v_mfma_f32_16x16x32_bf16 v[48:51], v[212:215], v[170:173], v[48:51]
	v_mfma_f32_16x16x32_bf16 v[36:39], v[204:207], v[178:181], v[36:39]
	v_mfma_f32_16x16x32_bf16 v[32:35], v[212:215], v[178:181], v[32:35]
	v_mfma_f32_16x16x32_bf16 v[20:23], v[204:207], v[186:189], v[20:23]
	v_mfma_f32_16x16x32_bf16 v[16:19], v[212:215], v[186:189], v[16:19]
	v_mfma_f32_16x16x32_bf16 v[4:7], v[204:207], v[196:199], v[4:7]
	v_mfma_f32_16x16x32_bf16 v[0:3], v[212:215], v[196:199], v[0:3]
	v_mfma_f32_16x16x32_bf16 v[52:55], v[208:211], v[174:177], v[52:55]
	v_mfma_f32_16x16x32_bf16 v[48:51], v[216:219], v[174:177], v[48:51]
	v_mfma_f32_16x16x32_bf16 v[36:39], v[208:211], v[182:185], v[36:39]
	v_mfma_f32_16x16x32_bf16 v[32:35], v[216:219], v[182:185], v[32:35]
	v_mfma_f32_16x16x32_bf16 v[20:23], v[208:211], v[190:193], v[20:23]
	v_mfma_f32_16x16x32_bf16 v[16:19], v[216:219], v[190:193], v[16:19]
	v_mfma_f32_16x16x32_bf16 v[4:7], v[208:211], v[200:203], v[4:7]
	v_mfma_f32_16x16x32_bf16 v[0:3], v[216:219], v[200:203], v[0:3]
	s_add_i32 s53, s53, 2
	s_add_u32 s26, s26, 0x100
	s_addc_u32 s27, s27, 0
	s_add_u32 s51, s51, 0x100
	s_addc_u32 s52, s52, 0
	s_cmpk_gt_u32 s53, 0x7d
	s_cbranch_scc0 .Lepi_nl_mlpout1
	s_cmp_lg_u32 s34, 64
	s_cbranch_scc1 .Lepi_nl_mlpout1
	s_lshl_b32 s11, s24, 8
	s_add_i32 s11, s11, s34
	v_or_b32_e32 v154, s11, v145
	s_add_i32 s15, s11, 0xffffe000
	v_lshl_or_b32 v150, s33, 8, v157
	s_lshr_b32 s15, s15, 12
	v_lshlrev_b32_e32 v148, 12, v154
	s_add_i32 s15, s15, 1
	s_cmp_gt_i32 s11, s48
	s_cselect_b32 s15, s15, 0
	s_mul_i32 s15, s15, s46
	v_lshl_add_u32 v148, v150, 1, v148
	s_add_u32 s20, s6, s15
	s_addc_u32 s21, s7, 0
	v_lshlrev_b32_e32 v149, 2, v150
	s_nop 0
	global_load_dwordx4 v[196:199], v149, s[20:21]
	global_load_dwordx4 v[200:203], v149, s[20:21] offset:16
	global_load_dwordx4 v[204:207], v149, s[20:21] offset:512
	global_load_dwordx4 v[208:211], v149, s[20:21] offset:528
	global_load_dwordx4 v[212:215], v148, s[74:75]
	global_load_dwordx4 v[216:219], v148, s[74:75] offset:256
	v_add_u32_e32 v151, 0x10000, v148
	global_load_dwordx4 v[220:223], v151, s[74:75]
	global_load_dwordx4 v[224:227], v151, s[74:75] offset:256
	v_add_u32_e32 v151, 0x20000, v148
	global_load_dwordx4 v[164:167], v151, s[74:75]
	global_load_dwordx4 v[168:171], v151, s[74:75] offset:256
	v_add_u32_e32 v151, 0x30000, v148
	global_load_dwordx4 v[172:175], v151, s[74:75]
	global_load_dwordx4 v[176:179], v151, s[74:75] offset:256
	s_waitcnt vmcnt(0)
	v_lshlrev_b32_e32 v180, 16, v212
	v_and_b32_e32 v181, 0xffff0000, v212
	v_lshlrev_b32_e32 v182, 16, v213
	v_and_b32_e32 v183, 0xffff0000, v213
	v_lshlrev_b32_e32 v184, 16, v214
	v_and_b32_e32 v185, 0xffff0000, v214
	v_lshlrev_b32_e32 v186, 16, v215
	v_and_b32_e32 v187, 0xffff0000, v215
	v_pk_fma_f32 v[124:125], v[124:125], v[196:197], v[180:181]
	v_pk_fma_f32 v[126:127], v[126:127], v[198:199], v[182:183]
	v_pk_fma_f32 v[120:121], v[120:121], v[200:201], v[184:185]
	v_pk_fma_f32 v[122:123], v[122:123], v[202:203], v[186:187]
	v_cvt_pk_bf16_f32 v123, v122, v123
	v_cvt_pk_bf16_f32 v122, v120, v121
	v_cvt_pk_bf16_f32 v121, v126, v127
	v_cvt_pk_bf16_f32 v120, v124, v125
	global_store_dwordx4 v148, v[120:123], s[42:43]
	v_lshlrev_b32_e32 v180, 16, v216
	v_and_b32_e32 v181, 0xffff0000, v216
	v_lshlrev_b32_e32 v182, 16, v217
	v_and_b32_e32 v183, 0xffff0000, v217
	v_lshlrev_b32_e32 v184, 16, v218
	v_and_b32_e32 v185, 0xffff0000, v218
	v_lshlrev_b32_e32 v186, 16, v219
	v_and_b32_e32 v187, 0xffff0000, v219
	v_pk_fma_f32 v[116:117], v[116:117], v[204:205], v[180:181]
	v_pk_fma_f32 v[118:119], v[118:119], v[206:207], v[182:183]
	v_pk_fma_f32 v[112:113], v[112:113], v[208:209], v[184:185]
	v_pk_fma_f32 v[114:115], v[114:115], v[210:211], v[186:187]
	v_cvt_pk_bf16_f32 v115, v114, v115
	v_cvt_pk_bf16_f32 v114, v112, v113
	v_cvt_pk_bf16_f32 v113, v118, v119
	v_cvt_pk_bf16_f32 v112, v116, v117
	global_store_dwordx4 v148, v[112:115], s[42:43] offset:256
	v_lshlrev_b32_e32 v180, 16, v220
	v_and_b32_e32 v181, 0xffff0000, v220
	v_lshlrev_b32_e32 v182, 16, v221
	v_and_b32_e32 v183, 0xffff0000, v221
	v_lshlrev_b32_e32 v184, 16, v222
	v_and_b32_e32 v185, 0xffff0000, v222
	v_lshlrev_b32_e32 v186, 16, v223
	v_and_b32_e32 v187, 0xffff0000, v223
	v_pk_fma_f32 v[108:109], v[108:109], v[196:197], v[180:181]
	v_pk_fma_f32 v[110:111], v[110:111], v[198:199], v[182:183]
	v_pk_fma_f32 v[104:105], v[104:105], v[200:201], v[184:185]
	v_pk_fma_f32 v[106:107], v[106:107], v[202:203], v[186:187]
	v_cvt_pk_bf16_f32 v107, v106, v107
	v_cvt_pk_bf16_f32 v106, v104, v105
	v_cvt_pk_bf16_f32 v105, v110, v111
	v_cvt_pk_bf16_f32 v104, v108, v109
	v_add_u32_e32 v151, 0x10000, v148
	global_store_dwordx4 v151, v[104:107], s[42:43]
	v_lshlrev_b32_e32 v180, 16, v224
	v_and_b32_e32 v181, 0xffff0000, v224
	v_lshlrev_b32_e32 v182, 16, v225
	v_and_b32_e32 v183, 0xffff0000, v225
	v_lshlrev_b32_e32 v184, 16, v226
	v_and_b32_e32 v185, 0xffff0000, v226
	v_lshlrev_b32_e32 v186, 16, v227
	v_and_b32_e32 v187, 0xffff0000, v227
	v_pk_fma_f32 v[100:101], v[100:101], v[204:205], v[180:181]
	v_pk_fma_f32 v[102:103], v[102:103], v[206:207], v[182:183]
	v_pk_fma_f32 v[96:97], v[96:97], v[208:209], v[184:185]
	v_pk_fma_f32 v[98:99], v[98:99], v[210:211], v[186:187]
	v_cvt_pk_bf16_f32 v99, v98, v99
	v_cvt_pk_bf16_f32 v98, v96, v97
	v_cvt_pk_bf16_f32 v97, v102, v103
	v_cvt_pk_bf16_f32 v96, v100, v101
	v_add_u32_e32 v151, 0x10000, v148
	global_store_dwordx4 v151, v[96:99], s[42:43] offset:256
	v_add_u32_e32 v151, 0x80000, v148
	global_load_dwordx4 v[212:215], v151, s[74:75]
	global_load_dwordx4 v[216:219], v151, s[74:75] offset:256
	v_add_u32_e32 v151, 0x90000, v148
	global_load_dwordx4 v[220:223], v151, s[74:75]
	global_load_dwordx4 v[224:227], v151, s[74:75] offset:256
	v_lshlrev_b32_e32 v180, 16, v164
	v_and_b32_e32 v181, 0xffff0000, v164
	v_lshlrev_b32_e32 v182, 16, v165
	v_and_b32_e32 v183, 0xffff0000, v165
	v_lshlrev_b32_e32 v184, 16, v166
	v_and_b32_e32 v185, 0xffff0000, v166
	v_lshlrev_b32_e32 v186, 16, v167
	v_and_b32_e32 v187, 0xffff0000, v167
	v_pk_fma_f32 v[92:93], v[92:93], v[196:197], v[180:181]
	v_pk_fma_f32 v[94:95], v[94:95], v[198:199], v[182:183]
	v_pk_fma_f32 v[88:89], v[88:89], v[200:201], v[184:185]
	v_pk_fma_f32 v[90:91], v[90:91], v[202:203], v[186:187]
	v_cvt_pk_bf16_f32 v91, v90, v91
	v_cvt_pk_bf16_f32 v90, v88, v89
	v_cvt_pk_bf16_f32 v89, v94, v95
	v_cvt_pk_bf16_f32 v88, v92, v93
	v_add_u32_e32 v151, 0x20000, v148
	global_store_dwordx4 v151, v[88:91], s[42:43]
	v_lshlrev_b32_e32 v180, 16, v168
	v_and_b32_e32 v181, 0xffff0000, v168
	v_lshlrev_b32_e32 v182, 16, v169
	v_and_b32_e32 v183, 0xffff0000, v169
	v_lshlrev_b32_e32 v184, 16, v170
	v_and_b32_e32 v185, 0xffff0000, v170
	v_lshlrev_b32_e32 v186, 16, v171
	v_and_b32_e32 v187, 0xffff0000, v171
	v_pk_fma_f32 v[84:85], v[84:85], v[204:205], v[180:181]
	v_pk_fma_f32 v[86:87], v[86:87], v[206:207], v[182:183]
	v_pk_fma_f32 v[80:81], v[80:81], v[208:209], v[184:185]
	v_pk_fma_f32 v[82:83], v[82:83], v[210:211], v[186:187]
	v_cvt_pk_bf16_f32 v83, v82, v83
	v_cvt_pk_bf16_f32 v82, v80, v81
	v_cvt_pk_bf16_f32 v81, v86, v87
	v_cvt_pk_bf16_f32 v80, v84, v85
	v_add_u32_e32 v151, 0x20000, v148
	global_store_dwordx4 v151, v[80:83], s[42:43] offset:256
	v_lshlrev_b32_e32 v180, 16, v172
	v_and_b32_e32 v181, 0xffff0000, v172
	v_lshlrev_b32_e32 v182, 16, v173
	v_and_b32_e32 v183, 0xffff0000, v173
	v_lshlrev_b32_e32 v184, 16, v174
	v_and_b32_e32 v185, 0xffff0000, v174
	v_lshlrev_b32_e32 v186, 16, v175
	v_and_b32_e32 v187, 0xffff0000, v175
	v_pk_fma_f32 v[76:77], v[76:77], v[196:197], v[180:181]
	v_pk_fma_f32 v[78:79], v[78:79], v[198:199], v[182:183]
	v_pk_fma_f32 v[72:73], v[72:73], v[200:201], v[184:185]
	v_pk_fma_f32 v[74:75], v[74:75], v[202:203], v[186:187]
	v_cvt_pk_bf16_f32 v75, v74, v75
	v_cvt_pk_bf16_f32 v74, v72, v73
	v_cvt_pk_bf16_f32 v73, v78, v79
	v_cvt_pk_bf16_f32 v72, v76, v77
	v_add_u32_e32 v151, 0x30000, v148
	global_store_dwordx4 v151, v[72:75], s[42:43]
	v_lshlrev_b32_e32 v180, 16, v176
	v_and_b32_e32 v181, 0xffff0000, v176
	v_lshlrev_b32_e32 v182, 16, v177
	v_and_b32_e32 v183, 0xffff0000, v177
	v_lshlrev_b32_e32 v184, 16, v178
	v_and_b32_e32 v185, 0xffff0000, v178
	v_lshlrev_b32_e32 v186, 16, v179
	v_and_b32_e32 v187, 0xffff0000, v179
	v_pk_fma_f32 v[68:69], v[68:69], v[204:205], v[180:181]
	v_pk_fma_f32 v[70:71], v[70:71], v[206:207], v[182:183]
	v_pk_fma_f32 v[64:65], v[64:65], v[208:209], v[184:185]
	v_pk_fma_f32 v[66:67], v[66:67], v[210:211], v[186:187]
	v_cvt_pk_bf16_f32 v67, v66, v67
	v_cvt_pk_bf16_f32 v66, v64, v65
	v_cvt_pk_bf16_f32 v65, v70, v71
	v_cvt_pk_bf16_f32 v64, v68, v69
	v_add_u32_e32 v151, 0x30000, v148
	global_store_dwordx4 v151, v[64:67], s[42:43] offset:256
	v_add_u32_e32 v151, 0xa0000, v148
	global_load_dwordx4 v[164:167], v151, s[74:75]
	global_load_dwordx4 v[168:171], v151, s[74:75] offset:256
	v_add_u32_e32 v151, 0xb0000, v148
	global_load_dwordx4 v[172:175], v151, s[74:75]
	global_load_dwordx4 v[176:179], v151, s[74:75] offset:256
	s_waitcnt vmcnt(0)
	v_lshlrev_b32_e32 v180, 16, v212
	v_and_b32_e32 v181, 0xffff0000, v212
	v_lshlrev_b32_e32 v182, 16, v213
	v_and_b32_e32 v183, 0xffff0000, v213
	v_lshlrev_b32_e32 v184, 16, v214
	v_and_b32_e32 v185, 0xffff0000, v214
	v_lshlrev_b32_e32 v186, 16, v215
	v_and_b32_e32 v187, 0xffff0000, v215
	v_pk_fma_f32 v[60:61], v[60:61], v[196:197], v[180:181]
	v_pk_fma_f32 v[62:63], v[62:63], v[198:199], v[182:183]
	v_pk_fma_f32 v[56:57], v[56:57], v[200:201], v[184:185]
	v_pk_fma_f32 v[58:59], v[58:59], v[202:203], v[186:187]
	v_cvt_pk_bf16_f32 v59, v58, v59
	v_cvt_pk_bf16_f32 v58, v56, v57
	v_cvt_pk_bf16_f32 v57, v62, v63
	v_cvt_pk_bf16_f32 v56, v60, v61
	v_add_u32_e32 v151, 0x80000, v148
	global_store_dwordx4 v151, v[56:59], s[42:43]
	v_lshlrev_b32_e32 v180, 16, v216
	v_and_b32_e32 v181, 0xffff0000, v216
	v_lshlrev_b32_e32 v182, 16, v217
	v_and_b32_e32 v183, 0xffff0000, v217
	v_lshlrev_b32_e32 v184, 16, v218
	v_and_b32_e32 v185, 0xffff0000, v218
	v_lshlrev_b32_e32 v186, 16, v219
	v_and_b32_e32 v187, 0xffff0000, v219
	v_pk_fma_f32 v[52:53], v[52:53], v[204:205], v[180:181]
	v_pk_fma_f32 v[54:55], v[54:55], v[206:207], v[182:183]
	v_pk_fma_f32 v[48:49], v[48:49], v[208:209], v[184:185]
	v_pk_fma_f32 v[50:51], v[50:51], v[210:211], v[186:187]
	v_cvt_pk_bf16_f32 v51, v50, v51
	v_cvt_pk_bf16_f32 v50, v48, v49
	v_cvt_pk_bf16_f32 v49, v54, v55
	v_cvt_pk_bf16_f32 v48, v52, v53
	v_add_u32_e32 v151, 0x80000, v148
	global_store_dwordx4 v151, v[48:51], s[42:43] offset:256
	v_lshlrev_b32_e32 v180, 16, v220
	v_and_b32_e32 v181, 0xffff0000, v220
	v_lshlrev_b32_e32 v182, 16, v221
	v_and_b32_e32 v183, 0xffff0000, v221
	v_lshlrev_b32_e32 v184, 16, v222
	v_and_b32_e32 v185, 0xffff0000, v222
	v_lshlrev_b32_e32 v186, 16, v223
	v_and_b32_e32 v187, 0xffff0000, v223
	v_pk_fma_f32 v[44:45], v[44:45], v[196:197], v[180:181]
	v_pk_fma_f32 v[46:47], v[46:47], v[198:199], v[182:183]
	v_pk_fma_f32 v[40:41], v[40:41], v[200:201], v[184:185]
	v_pk_fma_f32 v[42:43], v[42:43], v[202:203], v[186:187]
	v_cvt_pk_bf16_f32 v43, v42, v43
	v_cvt_pk_bf16_f32 v42, v40, v41
	v_cvt_pk_bf16_f32 v41, v46, v47
	v_cvt_pk_bf16_f32 v40, v44, v45
	v_add_u32_e32 v151, 0x90000, v148
	global_store_dwordx4 v151, v[40:43], s[42:43]
	v_lshlrev_b32_e32 v180, 16, v224
	v_and_b32_e32 v181, 0xffff0000, v224
	v_lshlrev_b32_e32 v182, 16, v225
	v_and_b32_e32 v183, 0xffff0000, v225
	v_lshlrev_b32_e32 v184, 16, v226
	v_and_b32_e32 v185, 0xffff0000, v226
	v_lshlrev_b32_e32 v186, 16, v227
	v_and_b32_e32 v187, 0xffff0000, v227
	v_pk_fma_f32 v[36:37], v[36:37], v[204:205], v[180:181]
	v_pk_fma_f32 v[38:39], v[38:39], v[206:207], v[182:183]
	v_pk_fma_f32 v[32:33], v[32:33], v[208:209], v[184:185]
	v_pk_fma_f32 v[34:35], v[34:35], v[210:211], v[186:187]
	v_cvt_pk_bf16_f32 v35, v34, v35
	v_cvt_pk_bf16_f32 v34, v32, v33
	v_cvt_pk_bf16_f32 v33, v38, v39
	v_cvt_pk_bf16_f32 v32, v36, v37
	v_add_u32_e32 v151, 0x90000, v148
	global_store_dwordx4 v151, v[32:35], s[42:43] offset:256
	v_lshlrev_b32_e32 v180, 16, v164
	v_and_b32_e32 v181, 0xffff0000, v164
	v_lshlrev_b32_e32 v182, 16, v165
	v_and_b32_e32 v183, 0xffff0000, v165
	v_lshlrev_b32_e32 v184, 16, v166
	v_and_b32_e32 v185, 0xffff0000, v166
	v_lshlrev_b32_e32 v186, 16, v167
	v_and_b32_e32 v187, 0xffff0000, v167
	v_pk_fma_f32 v[28:29], v[28:29], v[196:197], v[180:181]
	v_pk_fma_f32 v[30:31], v[30:31], v[198:199], v[182:183]
	v_pk_fma_f32 v[24:25], v[24:25], v[200:201], v[184:185]
	v_pk_fma_f32 v[26:27], v[26:27], v[202:203], v[186:187]
	v_cvt_pk_bf16_f32 v27, v26, v27
	v_cvt_pk_bf16_f32 v26, v24, v25
	v_cvt_pk_bf16_f32 v25, v30, v31
	v_cvt_pk_bf16_f32 v24, v28, v29
	v_add_u32_e32 v151, 0xa0000, v148
	global_store_dwordx4 v151, v[24:27], s[42:43]
	v_lshlrev_b32_e32 v180, 16, v168
	v_and_b32_e32 v181, 0xffff0000, v168
	v_lshlrev_b32_e32 v182, 16, v169
	v_and_b32_e32 v183, 0xffff0000, v169
	v_lshlrev_b32_e32 v184, 16, v170
	v_and_b32_e32 v185, 0xffff0000, v170
	v_lshlrev_b32_e32 v186, 16, v171
	v_and_b32_e32 v187, 0xffff0000, v171
	v_pk_fma_f32 v[20:21], v[20:21], v[204:205], v[180:181]
	v_pk_fma_f32 v[22:23], v[22:23], v[206:207], v[182:183]
	v_pk_fma_f32 v[16:17], v[16:17], v[208:209], v[184:185]
	v_pk_fma_f32 v[18:19], v[18:19], v[210:211], v[186:187]
	v_cvt_pk_bf16_f32 v19, v18, v19
	v_cvt_pk_bf16_f32 v18, v16, v17
	v_cvt_pk_bf16_f32 v17, v22, v23
	v_cvt_pk_bf16_f32 v16, v20, v21
	v_add_u32_e32 v151, 0xa0000, v148
	global_store_dwordx4 v151, v[16:19], s[42:43] offset:256
	v_lshlrev_b32_e32 v180, 16, v172
	v_and_b32_e32 v181, 0xffff0000, v172
	v_lshlrev_b32_e32 v182, 16, v173
	v_and_b32_e32 v183, 0xffff0000, v173
	v_lshlrev_b32_e32 v184, 16, v174
	v_and_b32_e32 v185, 0xffff0000, v174
	v_lshlrev_b32_e32 v186, 16, v175
	v_and_b32_e32 v187, 0xffff0000, v175
	v_pk_fma_f32 v[12:13], v[12:13], v[196:197], v[180:181]
	v_pk_fma_f32 v[14:15], v[14:15], v[198:199], v[182:183]
	v_pk_fma_f32 v[8:9], v[8:9], v[200:201], v[184:185]
	v_pk_fma_f32 v[10:11], v[10:11], v[202:203], v[186:187]
	v_cvt_pk_bf16_f32 v11, v10, v11
	v_cvt_pk_bf16_f32 v10, v8, v9
	v_cvt_pk_bf16_f32 v9, v14, v15
	v_cvt_pk_bf16_f32 v8, v12, v13
	v_add_u32_e32 v151, 0xb0000, v148
	global_store_dwordx4 v151, v[8:11], s[42:43]
	v_lshlrev_b32_e32 v180, 16, v176
	v_and_b32_e32 v181, 0xffff0000, v176
	v_lshlrev_b32_e32 v182, 16, v177
	v_and_b32_e32 v183, 0xffff0000, v177
	v_lshlrev_b32_e32 v184, 16, v178
	v_and_b32_e32 v185, 0xffff0000, v178
	v_lshlrev_b32_e32 v186, 16, v179
	v_and_b32_e32 v187, 0xffff0000, v179
	v_pk_fma_f32 v[4:5], v[4:5], v[204:205], v[180:181]
	v_pk_fma_f32 v[6:7], v[6:7], v[206:207], v[182:183]
	v_pk_fma_f32 v[0:1], v[0:1], v[208:209], v[184:185]
	v_pk_fma_f32 v[2:3], v[2:3], v[210:211], v[186:187]
	v_cvt_pk_bf16_f32 v3, v2, v3
	v_cvt_pk_bf16_f32 v2, v0, v1
	v_cvt_pk_bf16_f32 v1, v6, v7
	v_cvt_pk_bf16_f32 v0, v4, v5
	v_add_u32_e32 v151, 0xb0000, v148
	global_store_dwordx4 v151, v[0:3], s[42:43] offset:256
